# hyena: forward q=4 pass + spectrum multiply + inverse q=4 pass fused into the middle step (16 contiguous elements per thread, one LDS round trip instead of three)
# speedup vs baseline: 1.1743x; 1.0119x over previous
; HD float2 cmul(float2 a, float2 b){ return make_float2(a.x*b.x - a.y*b.y, a.x*b.y + a.y*b.x); }
; HD float2 cmulc(float2 a, float2 b){ return make_float2(a.x*b.x + a.y*b.y, a.y*b.x - a.x*b.y); }
; template<bool INV, bool NOTW>
; HD void bf4c(float2* Z, int i0, int i1, int i2, int i3, float2 w1, float2 w2, float2 w3){
;   float2 a0=Z[i0], a1=Z[i1], a2=Z[i2], a3=Z[i3];
;   if (INV && !NOTW){ a1=cmulc(a1,w1); a2=cmulc(a2,w2); a3=cmulc(a3,w3); }
;   float2 s02=make_float2(a0.x+a2.x,a0.y+a2.y), d02=make_float2(a0.x-a2.x,a0.y-a2.y);
;   float2 s13=make_float2(a1.x+a3.x,a1.y+a3.y), d13=make_float2(a1.x-a3.x,a1.y-a3.y);
;   float2 y0=make_float2(s02.x+s13.x,s02.y+s13.y), y2=make_float2(s02.x-s13.x,s02.y-s13.y);
;   float2 ym=make_float2(d02.x+d13.y,d02.y-d13.x);
;   float2 yp=make_float2(d02.x-d13.y,d02.y+d13.x);
;   float2 y1, y3;
;   if (INV){ y1=yp; y3=ym; } else if (NOTW){ y1=ym; y3=yp; } else { y1=cmul(ym,w1); y2=cmul(y2,w2); y3=cmul(yp,w3); }
;   Z[i0]=y0; Z[i1]=y1; Z[i2]=y2; Z[i3]=y3;
; }
; template<bool INV, int LQ, bool BARRIER=true>
; HD void fft_pass(float2* Z, const float2* twA, const float2* twB, int tid){
;     ...
;     _Pragma("unroll") for (int e=0;e<2;++e){ int j=tid+512*e; int k=j*tws;
;       float2 w1=cmul(twA[k>>6],twB[k&63]), w2=cmul(w1,w1), w3=cmul(w2,w1);
;       _Pragma("unroll") for (int ip=0;ip<4;++ip){ int base=ip*4096+j; bf4c<INV,false>(Z,base,base+q,base+2*q,base+3*q,w1,w2,w3); } }
.Lmy_pf_skipb:
	v_mov_b32_e32 v222, 0x3f6c835e
	v_mov_b32_e32 v223, 0x3ec3ef15
	v_mov_b32_e32 v224, 0x3f3504f3
	v_mov_b32_e32 v225, 0x3f3504f3
	v_and_b32_e32 v8, 255, v154
	v_lshrrev_b32_e32 v9, 4, v8
	v_lshlrev_b32_e32 v9, 3, v9
	v_add_u32_e32 v9, 0x20800, v9
	v_and_b32_e32 v10, 15, v8
	v_lshlrev_b32_e32 v10, 5, v10
	v_add_u32_e32 v10, 0x20a00, v10
	ds_read_b64 v[0:1], v9
	ds_read_b64 v[2:3], v10
	s_waitcnt lgkmcnt(0)
	v_pk_mul_f32 v[250:251], v[0:1], v[2:3] op_sel:[1,1] op_sel_hi:[1,0]
	v_pk_fma_f32 v[80:81], v[0:1], v[2:3], v[250:251] op_sel:[0,0,0] op_sel_hi:[0,1,1] neg_lo:[0,0,1]
	v_pk_mul_f32 v[250:251], v[80:81], v[80:81] op_sel:[1,1] op_sel_hi:[1,0]
	v_pk_fma_f32 v[82:83], v[80:81], v[80:81], v[250:251] op_sel:[0,0,0] op_sel_hi:[0,1,1] neg_lo:[0,0,1]
	v_pk_mul_f32 v[250:251], v[82:83], v[80:81] op_sel:[1,1] op_sel_hi:[1,0]
	v_pk_fma_f32 v[84:85], v[82:83], v[80:81], v[250:251] op_sel:[0,0,0] op_sel_hi:[0,1,1] neg_lo:[0,0,1]
	v_lshrrev_b32_e32 v9, 2, v8
	v_lshlrev_b32_e32 v9, 3, v9
	v_add_u32_e32 v9, 0x20800, v9
	v_and_b32_e32 v10, 3, v8
	v_lshlrev_b32_e32 v10, 7, v10
	v_add_u32_e32 v10, 0x20a00, v10
	ds_read_b64 v[0:1], v9
	ds_read_b64 v[2:3], v10
	s_waitcnt lgkmcnt(0)
	v_pk_mul_f32 v[250:251], v[0:1], v[2:3] op_sel:[1,1] op_sel_hi:[1,0]
	v_pk_fma_f32 v[236:237], v[0:1], v[2:3], v[250:251] op_sel:[0,0,0] op_sel_hi:[0,1,1] neg_lo:[0,0,1]
	v_pk_mul_f32 v[250:251], v[236:237], v[236:237] op_sel:[1,1] op_sel_hi:[1,0]
	v_pk_fma_f32 v[238:239], v[236:237], v[236:237], v[250:251] op_sel:[0,0,0] op_sel_hi:[0,1,1] neg_lo:[0,0,1]
	v_pk_mul_f32 v[250:251], v[238:239], v[236:237] op_sel:[1,1] op_sel_hi:[1,0]
	v_pk_fma_f32 v[240:241], v[238:239], v[236:237], v[250:251] op_sel:[0,0,0] op_sel_hi:[0,1,1] neg_lo:[0,0,1]
	v_lshrrev_b32_e32 v226, 8, v154
	v_lshlrev_b32_e32 v226, 12, v226
	v_and_b32_e32 v227, 255, v154
	v_add_u32_e32 v226, v226, v227
	v_lshlrev_b32_e32 v226, 3, v226
	v_add_u32_e32 v227, 0x10000, v226
	ds_read_b64 v[0:1], v226 offset:0
	ds_read_b64 v[8:9], v226 offset:8192
	ds_read_b64 v[16:17], v226 offset:16384
	ds_read_b64 v[24:25], v226 offset:24576
	ds_read_b64 v[2:3], v226 offset:2048
	ds_read_b64 v[10:11], v226 offset:10240
	ds_read_b64 v[18:19], v226 offset:18432
	ds_read_b64 v[26:27], v226 offset:26624
	ds_read_b64 v[4:5], v226 offset:4096
	ds_read_b64 v[12:13], v226 offset:12288
	ds_read_b64 v[20:21], v226 offset:20480
	ds_read_b64 v[28:29], v226 offset:28672
	ds_read_b64 v[6:7], v226 offset:6144
	ds_read_b64 v[14:15], v226 offset:14336
	ds_read_b64 v[22:23], v226 offset:22528
	ds_read_b64 v[30:31], v226 offset:30720
	s_waitcnt lgkmcnt(12)
	v_pk_add_f32 v[242:243], v[0:1], v[16:17]
	v_pk_add_f32 v[244:245], v[0:1], v[16:17] neg_lo:[0,1] neg_hi:[0,1]
	v_pk_add_f32 v[246:247], v[8:9], v[24:25]
	v_pk_add_f32 v[248:249], v[8:9], v[24:25] neg_lo:[0,1] neg_hi:[0,1]
	v_pk_add_f32 v[0:1], v[242:243], v[246:247]
	v_pk_add_f32 v[8:9], v[244:245], v[248:249] op_sel:[0,1] op_sel_hi:[1,0] neg_hi:[0,1]
	v_pk_mul_f32 v[250:251], v[8:9], v[80:81] op_sel:[1,1] op_sel_hi:[1,0]
	v_pk_fma_f32 v[8:9], v[8:9], v[80:81], v[250:251] op_sel:[0,0,0] op_sel_hi:[0,1,1] neg_lo:[0,0,1]
	v_pk_add_f32 v[16:17], v[242:243], v[246:247] neg_lo:[0,1] neg_hi:[0,1]
	v_pk_mul_f32 v[250:251], v[16:17], v[82:83] op_sel:[1,1] op_sel_hi:[1,0]
	v_pk_fma_f32 v[16:17], v[16:17], v[82:83], v[250:251] op_sel:[0,0,0] op_sel_hi:[0,1,1] neg_lo:[0,0,1]
	v_pk_add_f32 v[24:25], v[244:245], v[248:249] op_sel:[0,1] op_sel_hi:[1,0] neg_lo:[0,1]
	v_pk_mul_f32 v[250:251], v[24:25], v[84:85] op_sel:[1,1] op_sel_hi:[1,0]
	v_pk_fma_f32 v[24:25], v[24:25], v[84:85], v[250:251] op_sel:[0,0,0] op_sel_hi:[0,1,1] neg_lo:[0,0,1]
	s_waitcnt lgkmcnt(8)
	v_pk_add_f32 v[242:243], v[2:3], v[18:19]
	v_pk_add_f32 v[244:245], v[2:3], v[18:19] neg_lo:[0,1] neg_hi:[0,1]
	v_pk_add_f32 v[246:247], v[10:11], v[26:27]
	v_pk_add_f32 v[248:249], v[10:11], v[26:27] neg_lo:[0,1] neg_hi:[0,1]
	v_pk_add_f32 v[2:3], v[242:243], v[246:247]
	v_pk_add_f32 v[10:11], v[244:245], v[248:249] op_sel:[0,1] op_sel_hi:[1,0] neg_hi:[0,1]
	v_pk_mul_f32 v[250:251], v[10:11], v[80:81] op_sel:[1,1] op_sel_hi:[1,0]
	v_pk_fma_f32 v[10:11], v[10:11], v[80:81], v[250:251] op_sel:[0,0,0] op_sel_hi:[0,1,1] neg_lo:[0,0,1]
	v_pk_mul_f32 v[250:251], v[10:11], v[222:223] op_sel:[1,1] op_sel_hi:[1,0] neg_lo:[0,1] neg_hi:[0,0]
	v_pk_fma_f32 v[10:11], v[10:11], v[222:223], v[250:251] op_sel:[0,0,0] op_sel_hi:[0,1,1] neg_lo:[0,0,1] neg_hi:[0,1,0]
	v_pk_add_f32 v[18:19], v[242:243], v[246:247] neg_lo:[0,1] neg_hi:[0,1]
	v_pk_mul_f32 v[250:251], v[18:19], v[82:83] op_sel:[1,1] op_sel_hi:[1,0]
	v_pk_fma_f32 v[18:19], v[18:19], v[82:83], v[250:251] op_sel:[0,0,0] op_sel_hi:[0,1,1] neg_lo:[0,0,1]
	v_pk_mul_f32 v[250:251], v[18:19], v[224:225] op_sel:[1,1] op_sel_hi:[1,0] neg_lo:[0,1] neg_hi:[0,0]
	v_pk_fma_f32 v[18:19], v[18:19], v[224:225], v[250:251] op_sel:[0,0,0] op_sel_hi:[0,1,1] neg_lo:[0,0,1] neg_hi:[0,1,0]
	v_pk_add_f32 v[26:27], v[244:245], v[248:249] op_sel:[0,1] op_sel_hi:[1,0] neg_lo:[0,1]
	v_pk_mul_f32 v[250:251], v[26:27], v[84:85] op_sel:[1,1] op_sel_hi:[1,0]
	v_pk_fma_f32 v[26:27], v[26:27], v[84:85], v[250:251] op_sel:[0,0,0] op_sel_hi:[0,1,1] neg_lo:[0,0,1]
	v_pk_mul_f32 v[250:251], v[26:27], v[222:223] op_sel:[1,0] op_sel_hi:[1,1] neg_lo:[0,1] neg_hi:[0,0]
	v_pk_fma_f32 v[26:27], v[26:27], v[222:223], v[250:251] op_sel:[0,1,0] op_sel_hi:[0,0,1] neg_lo:[0,0,1] neg_hi:[0,1,0]
	s_waitcnt lgkmcnt(4)
; HD float2 cmul(float2 a, float2 b){ return make_float2(a.x*b.x - a.y*b.y, a.x*b.y + a.y*b.x); }
; HD float2 cmulc(float2 a, float2 b){ return make_float2(a.x*b.x + a.y*b.y, a.y*b.x - a.x*b.y); }
; template<bool INV, bool NOTW>
; HD void bf4c(float2* Z, int i0, int i1, int i2, int i3, float2 w1, float2 w2, float2 w3){
;   float2 a0=Z[i0], a1=Z[i1], a2=Z[i2], a3=Z[i3];
;   if (INV && !NOTW){ a1=cmulc(a1,w1); a2=cmulc(a2,w2); a3=cmulc(a3,w3); }
;   float2 s02=make_float2(a0.x+a2.x,a0.y+a2.y), d02=make_float2(a0.x-a2.x,a0.y-a2.y);
;   float2 s13=make_float2(a1.x+a3.x,a1.y+a3.y), d13=make_float2(a1.x-a3.x,a1.y-a3.y);
;   float2 y0=make_float2(s02.x+s13.x,s02.y+s13.y), y2=make_float2(s02.x-s13.x,s02.y-s13.y);
;   float2 ym=make_float2(d02.x+d13.y,d02.y-d13.x);
;   float2 yp=make_float2(d02.x-d13.y,d02.y+d13.x);
;   float2 y1, y3;
;   if (INV){ y1=yp; y3=ym; } else if (NOTW){ y1=ym; y3=yp; } else { y1=cmul(ym,w1); y2=cmul(y2,w2); y3=cmul(yp,w3); }
;   Z[i0]=y0; Z[i1]=y1; Z[i2]=y2; Z[i3]=y3;
; }
; template<bool INV, int LQ, bool BARRIER=true>
; HD void fft_pass(float2* Z, const float2* twA, const float2* twB, int tid){
;     ...
;     _Pragma("unroll") for (int e=0;e<2;++e){ int j=tid+512*e; int k=j*tws;
;       float2 w1=cmul(twA[k>>6],twB[k&63]), w2=cmul(w1,w1), w3=cmul(w2,w1);
;       _Pragma("unroll") for (int ip=0;ip<4;++ip){ int base=ip*4096+j; bf4c<INV,false>(Z,base,base+q,base+2*q,base+3*q,w1,w2,w3); } }
	v_pk_add_f32 v[242:243], v[4:5], v[20:21]
	v_pk_add_f32 v[244:245], v[4:5], v[20:21] neg_lo:[0,1] neg_hi:[0,1]
	v_pk_add_f32 v[246:247], v[12:13], v[28:29]
	v_pk_add_f32 v[248:249], v[12:13], v[28:29] neg_lo:[0,1] neg_hi:[0,1]
	v_pk_add_f32 v[4:5], v[242:243], v[246:247]
	v_pk_add_f32 v[12:13], v[244:245], v[248:249] op_sel:[0,1] op_sel_hi:[1,0] neg_hi:[0,1]
	v_pk_mul_f32 v[250:251], v[12:13], v[80:81] op_sel:[1,1] op_sel_hi:[1,0]
	v_pk_fma_f32 v[12:13], v[12:13], v[80:81], v[250:251] op_sel:[0,0,0] op_sel_hi:[0,1,1] neg_lo:[0,0,1]
	v_pk_mul_f32 v[250:251], v[12:13], v[224:225] op_sel:[1,1] op_sel_hi:[1,0] neg_lo:[0,1] neg_hi:[0,0]
	v_pk_fma_f32 v[12:13], v[12:13], v[224:225], v[250:251] op_sel:[0,0,0] op_sel_hi:[0,1,1] neg_lo:[0,0,1] neg_hi:[0,1,0]
	v_pk_add_f32 v[20:21], v[242:243], v[246:247] neg_lo:[0,1] neg_hi:[0,1]
	v_pk_mul_f32 v[250:251], v[20:21], v[82:83] op_sel:[1,1] op_sel_hi:[1,0]
	v_pk_fma_f32 v[20:21], v[20:21], v[82:83], v[250:251] op_sel:[0,0,0] op_sel_hi:[0,1,1] neg_lo:[0,0,1]
	v_pk_add_f32 v[20:21], v[20:21], 0 op_sel:[1,0] op_sel_hi:[0,0] neg_hi:[1,0]
	v_pk_add_f32 v[28:29], v[244:245], v[248:249] op_sel:[0,1] op_sel_hi:[1,0] neg_lo:[0,1]
	v_pk_mul_f32 v[250:251], v[28:29], v[84:85] op_sel:[1,1] op_sel_hi:[1,0]
	v_pk_fma_f32 v[28:29], v[28:29], v[84:85], v[250:251] op_sel:[0,0,0] op_sel_hi:[0,1,1] neg_lo:[0,0,1]
	v_pk_mul_f32 v[250:251], v[28:29], v[224:225] op_sel:[1,1] op_sel_hi:[1,0] neg_lo:[0,1] neg_hi:[0,1]
	v_pk_fma_f32 v[28:29], v[28:29], v[224:225], v[250:251] op_sel:[0,0,0] op_sel_hi:[0,1,1] neg_lo:[0,1,1] neg_hi:[0,1,0]
	s_waitcnt lgkmcnt(0)
	v_pk_add_f32 v[242:243], v[6:7], v[22:23]
	v_pk_add_f32 v[244:245], v[6:7], v[22:23] neg_lo:[0,1] neg_hi:[0,1]
	v_pk_add_f32 v[246:247], v[14:15], v[30:31]
	v_pk_add_f32 v[248:249], v[14:15], v[30:31] neg_lo:[0,1] neg_hi:[0,1]
	v_pk_add_f32 v[6:7], v[242:243], v[246:247]
	v_pk_add_f32 v[14:15], v[244:245], v[248:249] op_sel:[0,1] op_sel_hi:[1,0] neg_hi:[0,1]
	v_pk_mul_f32 v[250:251], v[14:15], v[80:81] op_sel:[1,1] op_sel_hi:[1,0]
	v_pk_fma_f32 v[14:15], v[14:15], v[80:81], v[250:251] op_sel:[0,0,0] op_sel_hi:[0,1,1] neg_lo:[0,0,1]
	v_pk_mul_f32 v[250:251], v[14:15], v[222:223] op_sel:[1,0] op_sel_hi:[1,1] neg_lo:[0,1] neg_hi:[0,0]
	v_pk_fma_f32 v[14:15], v[14:15], v[222:223], v[250:251] op_sel:[0,1,0] op_sel_hi:[0,0,1] neg_lo:[0,0,1] neg_hi:[0,1,0]
	v_pk_add_f32 v[22:23], v[242:243], v[246:247] neg_lo:[0,1] neg_hi:[0,1]
	v_pk_mul_f32 v[250:251], v[22:23], v[82:83] op_sel:[1,1] op_sel_hi:[1,0]
	v_pk_fma_f32 v[22:23], v[22:23], v[82:83], v[250:251] op_sel:[0,0,0] op_sel_hi:[0,1,1] neg_lo:[0,0,1]
	v_pk_mul_f32 v[250:251], v[22:23], v[224:225] op_sel:[1,1] op_sel_hi:[1,0] neg_lo:[0,1] neg_hi:[0,1]
	v_pk_fma_f32 v[22:23], v[22:23], v[224:225], v[250:251] op_sel:[0,0,0] op_sel_hi:[0,1,1] neg_lo:[0,1,1] neg_hi:[0,1,0]
	v_pk_add_f32 v[30:31], v[244:245], v[248:249] op_sel:[0,1] op_sel_hi:[1,0] neg_lo:[0,1]
	v_pk_mul_f32 v[250:251], v[30:31], v[84:85] op_sel:[1,1] op_sel_hi:[1,0]
	v_pk_fma_f32 v[30:31], v[30:31], v[84:85], v[250:251] op_sel:[0,0,0] op_sel_hi:[0,1,1] neg_lo:[0,0,1]
	v_pk_mul_f32 v[250:251], v[30:31], v[222:223] op_sel:[1,1] op_sel_hi:[1,0] neg_lo:[0,0] neg_hi:[0,1]
	v_pk_fma_f32 v[30:31], v[30:31], v[222:223], v[250:251] op_sel:[0,0,0] op_sel_hi:[0,1,1] neg_lo:[0,1,1] neg_hi:[0,0,0]
	v_pk_add_f32 v[242:243], v[0:1], v[4:5]
	v_pk_add_f32 v[244:245], v[0:1], v[4:5] neg_lo:[0,1] neg_hi:[0,1]
	v_pk_add_f32 v[246:247], v[2:3], v[6:7]
	v_pk_add_f32 v[248:249], v[2:3], v[6:7] neg_lo:[0,1] neg_hi:[0,1]
	v_pk_add_f32 v[0:1], v[242:243], v[246:247]
	ds_write_b64 v226, v[0:1] offset:0
	v_pk_add_f32 v[2:3], v[244:245], v[248:249] op_sel:[0,1] op_sel_hi:[1,0] neg_hi:[0,1]
	v_pk_mul_f32 v[250:251], v[2:3], v[236:237] op_sel:[1,1] op_sel_hi:[1,0]
	v_pk_fma_f32 v[2:3], v[2:3], v[236:237], v[250:251] op_sel:[0,0,0] op_sel_hi:[0,1,1] neg_lo:[0,0,1]
	ds_write_b64 v226, v[2:3] offset:2048
	v_pk_add_f32 v[4:5], v[242:243], v[246:247] neg_lo:[0,1] neg_hi:[0,1]
	v_pk_mul_f32 v[250:251], v[4:5], v[238:239] op_sel:[1,1] op_sel_hi:[1,0]
	v_pk_fma_f32 v[4:5], v[4:5], v[238:239], v[250:251] op_sel:[0,0,0] op_sel_hi:[0,1,1] neg_lo:[0,0,1]
	ds_write_b64 v226, v[4:5] offset:4096
	v_pk_add_f32 v[6:7], v[244:245], v[248:249] op_sel:[0,1] op_sel_hi:[1,0] neg_lo:[0,1]
	v_pk_mul_f32 v[250:251], v[6:7], v[240:241] op_sel:[1,1] op_sel_hi:[1,0]
	v_pk_fma_f32 v[6:7], v[6:7], v[240:241], v[250:251] op_sel:[0,0,0] op_sel_hi:[0,1,1] neg_lo:[0,0,1]
	ds_write_b64 v226, v[6:7] offset:6144
	v_pk_add_f32 v[242:243], v[8:9], v[12:13]
	v_pk_add_f32 v[244:245], v[8:9], v[12:13] neg_lo:[0,1] neg_hi:[0,1]
	v_pk_add_f32 v[246:247], v[10:11], v[14:15]
	v_pk_add_f32 v[248:249], v[10:11], v[14:15] neg_lo:[0,1] neg_hi:[0,1]
	v_pk_add_f32 v[8:9], v[242:243], v[246:247]
	ds_write_b64 v226, v[8:9] offset:8192
	v_pk_add_f32 v[10:11], v[244:245], v[248:249] op_sel:[0,1] op_sel_hi:[1,0] neg_hi:[0,1]
	v_pk_mul_f32 v[250:251], v[10:11], v[236:237] op_sel:[1,1] op_sel_hi:[1,0]
	v_pk_fma_f32 v[10:11], v[10:11], v[236:237], v[250:251] op_sel:[0,0,0] op_sel_hi:[0,1,1] neg_lo:[0,0,1]
	ds_write_b64 v226, v[10:11] offset:10240
	v_pk_add_f32 v[12:13], v[242:243], v[246:247] neg_lo:[0,1] neg_hi:[0,1]
	v_pk_mul_f32 v[250:251], v[12:13], v[238:239] op_sel:[1,1] op_sel_hi:[1,0]
	v_pk_fma_f32 v[12:13], v[12:13], v[238:239], v[250:251] op_sel:[0,0,0] op_sel_hi:[0,1,1] neg_lo:[0,0,1]
	ds_write_b64 v226, v[12:13] offset:12288
	v_pk_add_f32 v[14:15], v[244:245], v[248:249] op_sel:[0,1] op_sel_hi:[1,0] neg_lo:[0,1]
	v_pk_mul_f32 v[250:251], v[14:15], v[240:241] op_sel:[1,1] op_sel_hi:[1,0]
; HD float2 cmul(float2 a, float2 b){ return make_float2(a.x*b.x - a.y*b.y, a.x*b.y + a.y*b.x); }
; HD float2 cmulc(float2 a, float2 b){ return make_float2(a.x*b.x + a.y*b.y, a.y*b.x - a.x*b.y); }
; template<bool INV, bool NOTW>
; HD void bf4c(float2* Z, int i0, int i1, int i2, int i3, float2 w1, float2 w2, float2 w3){
;   float2 a0=Z[i0], a1=Z[i1], a2=Z[i2], a3=Z[i3];
;   if (INV && !NOTW){ a1=cmulc(a1,w1); a2=cmulc(a2,w2); a3=cmulc(a3,w3); }
;   float2 s02=make_float2(a0.x+a2.x,a0.y+a2.y), d02=make_float2(a0.x-a2.x,a0.y-a2.y);
;   float2 s13=make_float2(a1.x+a3.x,a1.y+a3.y), d13=make_float2(a1.x-a3.x,a1.y-a3.y);
;   float2 y0=make_float2(s02.x+s13.x,s02.y+s13.y), y2=make_float2(s02.x-s13.x,s02.y-s13.y);
;   float2 ym=make_float2(d02.x+d13.y,d02.y-d13.x);
;   float2 yp=make_float2(d02.x-d13.y,d02.y+d13.x);
;   float2 y1, y3;
;   if (INV){ y1=yp; y3=ym; } else if (NOTW){ y1=ym; y3=yp; } else { y1=cmul(ym,w1); y2=cmul(y2,w2); y3=cmul(yp,w3); }
;   Z[i0]=y0; Z[i1]=y1; Z[i2]=y2; Z[i3]=y3;
; }
; template<bool INV, int LQ, bool BARRIER=true>
; HD void fft_pass(float2* Z, const float2* twA, const float2* twB, int tid){
;     ...
;     _Pragma("unroll") for (int e=0;e<2;++e){ int j=tid+512*e; int k=j*tws;
;       float2 w1=cmul(twA[k>>6],twB[k&63]), w2=cmul(w1,w1), w3=cmul(w2,w1);
;       _Pragma("unroll") for (int ip=0;ip<4;++ip){ int base=ip*4096+j; bf4c<INV,false>(Z,base,base+q,base+2*q,base+3*q,w1,w2,w3); } }
	v_pk_fma_f32 v[14:15], v[14:15], v[240:241], v[250:251] op_sel:[0,0,0] op_sel_hi:[0,1,1] neg_lo:[0,0,1]
	ds_write_b64 v226, v[14:15] offset:14336
	v_pk_add_f32 v[242:243], v[16:17], v[20:21]
	v_pk_add_f32 v[244:245], v[16:17], v[20:21] neg_lo:[0,1] neg_hi:[0,1]
	v_pk_add_f32 v[246:247], v[18:19], v[22:23]
	v_pk_add_f32 v[248:249], v[18:19], v[22:23] neg_lo:[0,1] neg_hi:[0,1]
	v_pk_add_f32 v[16:17], v[242:243], v[246:247]
	ds_write_b64 v226, v[16:17] offset:16384
	v_pk_add_f32 v[18:19], v[244:245], v[248:249] op_sel:[0,1] op_sel_hi:[1,0] neg_hi:[0,1]
	v_pk_mul_f32 v[250:251], v[18:19], v[236:237] op_sel:[1,1] op_sel_hi:[1,0]
	v_pk_fma_f32 v[18:19], v[18:19], v[236:237], v[250:251] op_sel:[0,0,0] op_sel_hi:[0,1,1] neg_lo:[0,0,1]
	ds_write_b64 v226, v[18:19] offset:18432
	v_pk_add_f32 v[20:21], v[242:243], v[246:247] neg_lo:[0,1] neg_hi:[0,1]
	v_pk_mul_f32 v[250:251], v[20:21], v[238:239] op_sel:[1,1] op_sel_hi:[1,0]
	v_pk_fma_f32 v[20:21], v[20:21], v[238:239], v[250:251] op_sel:[0,0,0] op_sel_hi:[0,1,1] neg_lo:[0,0,1]
	ds_write_b64 v226, v[20:21] offset:20480
	v_pk_add_f32 v[22:23], v[244:245], v[248:249] op_sel:[0,1] op_sel_hi:[1,0] neg_lo:[0,1]
	v_pk_mul_f32 v[250:251], v[22:23], v[240:241] op_sel:[1,1] op_sel_hi:[1,0]
	v_pk_fma_f32 v[22:23], v[22:23], v[240:241], v[250:251] op_sel:[0,0,0] op_sel_hi:[0,1,1] neg_lo:[0,0,1]
	ds_write_b64 v226, v[22:23] offset:22528
	v_pk_add_f32 v[242:243], v[24:25], v[28:29]
	v_pk_add_f32 v[244:245], v[24:25], v[28:29] neg_lo:[0,1] neg_hi:[0,1]
	v_pk_add_f32 v[246:247], v[26:27], v[30:31]
	v_pk_add_f32 v[248:249], v[26:27], v[30:31] neg_lo:[0,1] neg_hi:[0,1]
	v_pk_add_f32 v[24:25], v[242:243], v[246:247]
	ds_write_b64 v226, v[24:25] offset:24576
	v_pk_add_f32 v[26:27], v[244:245], v[248:249] op_sel:[0,1] op_sel_hi:[1,0] neg_hi:[0,1]
	v_pk_mul_f32 v[250:251], v[26:27], v[236:237] op_sel:[1,1] op_sel_hi:[1,0]
	v_pk_fma_f32 v[26:27], v[26:27], v[236:237], v[250:251] op_sel:[0,0,0] op_sel_hi:[0,1,1] neg_lo:[0,0,1]
	ds_write_b64 v226, v[26:27] offset:26624
	v_pk_add_f32 v[28:29], v[242:243], v[246:247] neg_lo:[0,1] neg_hi:[0,1]
	v_pk_mul_f32 v[250:251], v[28:29], v[238:239] op_sel:[1,1] op_sel_hi:[1,0]
	v_pk_fma_f32 v[28:29], v[28:29], v[238:239], v[250:251] op_sel:[0,0,0] op_sel_hi:[0,1,1] neg_lo:[0,0,1]
	ds_write_b64 v226, v[28:29] offset:28672
	v_pk_add_f32 v[30:31], v[244:245], v[248:249] op_sel:[0,1] op_sel_hi:[1,0] neg_lo:[0,1]
	v_pk_mul_f32 v[250:251], v[30:31], v[240:241] op_sel:[1,1] op_sel_hi:[1,0]
	v_pk_fma_f32 v[30:31], v[30:31], v[240:241], v[250:251] op_sel:[0,0,0] op_sel_hi:[0,1,1] neg_lo:[0,0,1]
	ds_write_b64 v226, v[30:31] offset:30720
	ds_read_b64 v[0:1], v227 offset:0
	ds_read_b64 v[8:9], v227 offset:8192
	ds_read_b64 v[16:17], v227 offset:16384
	ds_read_b64 v[24:25], v227 offset:24576
	ds_read_b64 v[2:3], v227 offset:2048
	ds_read_b64 v[10:11], v227 offset:10240
	ds_read_b64 v[18:19], v227 offset:18432
	ds_read_b64 v[26:27], v227 offset:26624
	ds_read_b64 v[4:5], v227 offset:4096
	ds_read_b64 v[12:13], v227 offset:12288
	ds_read_b64 v[20:21], v227 offset:20480
	ds_read_b64 v[28:29], v227 offset:28672
	ds_read_b64 v[6:7], v227 offset:6144
	ds_read_b64 v[14:15], v227 offset:14336
	ds_read_b64 v[22:23], v227 offset:22528
	ds_read_b64 v[30:31], v227 offset:30720
	s_waitcnt lgkmcnt(12)
	v_pk_add_f32 v[242:243], v[0:1], v[16:17]
	v_pk_add_f32 v[244:245], v[0:1], v[16:17] neg_lo:[0,1] neg_hi:[0,1]
	v_pk_add_f32 v[246:247], v[8:9], v[24:25]
	v_pk_add_f32 v[248:249], v[8:9], v[24:25] neg_lo:[0,1] neg_hi:[0,1]
	v_pk_add_f32 v[0:1], v[242:243], v[246:247]
	v_pk_add_f32 v[8:9], v[244:245], v[248:249] op_sel:[0,1] op_sel_hi:[1,0] neg_hi:[0,1]
	v_pk_mul_f32 v[250:251], v[8:9], v[80:81] op_sel:[1,1] op_sel_hi:[1,0]
	v_pk_fma_f32 v[8:9], v[8:9], v[80:81], v[250:251] op_sel:[0,0,0] op_sel_hi:[0,1,1] neg_lo:[0,0,1]
	v_pk_add_f32 v[16:17], v[242:243], v[246:247] neg_lo:[0,1] neg_hi:[0,1]
	v_pk_mul_f32 v[250:251], v[16:17], v[82:83] op_sel:[1,1] op_sel_hi:[1,0]
	v_pk_fma_f32 v[16:17], v[16:17], v[82:83], v[250:251] op_sel:[0,0,0] op_sel_hi:[0,1,1] neg_lo:[0,0,1]
	v_pk_add_f32 v[24:25], v[244:245], v[248:249] op_sel:[0,1] op_sel_hi:[1,0] neg_lo:[0,1]
	v_pk_mul_f32 v[250:251], v[24:25], v[84:85] op_sel:[1,1] op_sel_hi:[1,0]
	v_pk_fma_f32 v[24:25], v[24:25], v[84:85], v[250:251] op_sel:[0,0,0] op_sel_hi:[0,1,1] neg_lo:[0,0,1]
	s_waitcnt lgkmcnt(8)
	v_pk_add_f32 v[242:243], v[2:3], v[18:19]
	v_pk_add_f32 v[244:245], v[2:3], v[18:19] neg_lo:[0,1] neg_hi:[0,1]
	v_pk_add_f32 v[246:247], v[10:11], v[26:27]
	v_pk_add_f32 v[248:249], v[10:11], v[26:27] neg_lo:[0,1] neg_hi:[0,1]
	v_pk_add_f32 v[2:3], v[242:243], v[246:247]
	v_pk_add_f32 v[10:11], v[244:245], v[248:249] op_sel:[0,1] op_sel_hi:[1,0] neg_hi:[0,1]
	v_pk_mul_f32 v[250:251], v[10:11], v[80:81] op_sel:[1,1] op_sel_hi:[1,0]
	v_pk_fma_f32 v[10:11], v[10:11], v[80:81], v[250:251] op_sel:[0,0,0] op_sel_hi:[0,1,1] neg_lo:[0,0,1]
	v_pk_mul_f32 v[250:251], v[10:11], v[222:223] op_sel:[1,1] op_sel_hi:[1,0] neg_lo:[0,1] neg_hi:[0,0]
	v_pk_fma_f32 v[10:11], v[10:11], v[222:223], v[250:251] op_sel:[0,0,0] op_sel_hi:[0,1,1] neg_lo:[0,0,1] neg_hi:[0,1,0]
	v_pk_add_f32 v[18:19], v[242:243], v[246:247] neg_lo:[0,1] neg_hi:[0,1]
	v_pk_mul_f32 v[250:251], v[18:19], v[82:83] op_sel:[1,1] op_sel_hi:[1,0]
	v_pk_fma_f32 v[18:19], v[18:19], v[82:83], v[250:251] op_sel:[0,0,0] op_sel_hi:[0,1,1] neg_lo:[0,0,1]
	v_pk_mul_f32 v[250:251], v[18:19], v[224:225] op_sel:[1,1] op_sel_hi:[1,0] neg_lo:[0,1] neg_hi:[0,0]
	v_pk_fma_f32 v[18:19], v[18:19], v[224:225], v[250:251] op_sel:[0,0,0] op_sel_hi:[0,1,1] neg_lo:[0,0,1] neg_hi:[0,1,0]
	v_pk_add_f32 v[26:27], v[244:245], v[248:249] op_sel:[0,1] op_sel_hi:[1,0] neg_lo:[0,1]
	v_pk_mul_f32 v[250:251], v[26:27], v[84:85] op_sel:[1,1] op_sel_hi:[1,0]
	v_pk_fma_f32 v[26:27], v[26:27], v[84:85], v[250:251] op_sel:[0,0,0] op_sel_hi:[0,1,1] neg_lo:[0,0,1]
	v_pk_mul_f32 v[250:251], v[26:27], v[222:223] op_sel:[1,0] op_sel_hi:[1,1] neg_lo:[0,1] neg_hi:[0,0]
	v_pk_fma_f32 v[26:27], v[26:27], v[222:223], v[250:251] op_sel:[0,1,0] op_sel_hi:[0,0,1] neg_lo:[0,0,1] neg_hi:[0,1,0]
	s_waitcnt lgkmcnt(4)
; HD float2 cmul(float2 a, float2 b){ return make_float2(a.x*b.x - a.y*b.y, a.x*b.y + a.y*b.x); }
; HD float2 cmulc(float2 a, float2 b){ return make_float2(a.x*b.x + a.y*b.y, a.y*b.x - a.x*b.y); }
; template<bool INV, bool NOTW>
; HD void bf4c(float2* Z, int i0, int i1, int i2, int i3, float2 w1, float2 w2, float2 w3){
;   float2 a0=Z[i0], a1=Z[i1], a2=Z[i2], a3=Z[i3];
;   if (INV && !NOTW){ a1=cmulc(a1,w1); a2=cmulc(a2,w2); a3=cmulc(a3,w3); }
;   float2 s02=make_float2(a0.x+a2.x,a0.y+a2.y), d02=make_float2(a0.x-a2.x,a0.y-a2.y);
;   float2 s13=make_float2(a1.x+a3.x,a1.y+a3.y), d13=make_float2(a1.x-a3.x,a1.y-a3.y);
;   float2 y0=make_float2(s02.x+s13.x,s02.y+s13.y), y2=make_float2(s02.x-s13.x,s02.y-s13.y);
;   float2 ym=make_float2(d02.x+d13.y,d02.y-d13.x);
;   float2 yp=make_float2(d02.x-d13.y,d02.y+d13.x);
;   float2 y1, y3;
;   if (INV){ y1=yp; y3=ym; } else if (NOTW){ y1=ym; y3=yp; } else { y1=cmul(ym,w1); y2=cmul(y2,w2); y3=cmul(yp,w3); }
;   Z[i0]=y0; Z[i1]=y1; Z[i2]=y2; Z[i3]=y3;
; }
; template<bool INV, int LQ, bool BARRIER=true>
; HD void fft_pass(float2* Z, const float2* twA, const float2* twB, int tid){
;     ...
;     _Pragma("unroll") for (int e=0;e<2;++e){ int j=tid+512*e; int k=j*tws;
;       float2 w1=cmul(twA[k>>6],twB[k&63]), w2=cmul(w1,w1), w3=cmul(w2,w1);
;       _Pragma("unroll") for (int ip=0;ip<4;++ip){ int base=ip*4096+j; bf4c<INV,false>(Z,base,base+q,base+2*q,base+3*q,w1,w2,w3); } }
	v_pk_add_f32 v[242:243], v[4:5], v[20:21]
	v_pk_add_f32 v[244:245], v[4:5], v[20:21] neg_lo:[0,1] neg_hi:[0,1]
	v_pk_add_f32 v[246:247], v[12:13], v[28:29]
	v_pk_add_f32 v[248:249], v[12:13], v[28:29] neg_lo:[0,1] neg_hi:[0,1]
	v_pk_add_f32 v[4:5], v[242:243], v[246:247]
	v_pk_add_f32 v[12:13], v[244:245], v[248:249] op_sel:[0,1] op_sel_hi:[1,0] neg_hi:[0,1]
	v_pk_mul_f32 v[250:251], v[12:13], v[80:81] op_sel:[1,1] op_sel_hi:[1,0]
	v_pk_fma_f32 v[12:13], v[12:13], v[80:81], v[250:251] op_sel:[0,0,0] op_sel_hi:[0,1,1] neg_lo:[0,0,1]
	v_pk_mul_f32 v[250:251], v[12:13], v[224:225] op_sel:[1,1] op_sel_hi:[1,0] neg_lo:[0,1] neg_hi:[0,0]
	v_pk_fma_f32 v[12:13], v[12:13], v[224:225], v[250:251] op_sel:[0,0,0] op_sel_hi:[0,1,1] neg_lo:[0,0,1] neg_hi:[0,1,0]
	v_pk_add_f32 v[20:21], v[242:243], v[246:247] neg_lo:[0,1] neg_hi:[0,1]
	v_pk_mul_f32 v[250:251], v[20:21], v[82:83] op_sel:[1,1] op_sel_hi:[1,0]
	v_pk_fma_f32 v[20:21], v[20:21], v[82:83], v[250:251] op_sel:[0,0,0] op_sel_hi:[0,1,1] neg_lo:[0,0,1]
	v_pk_add_f32 v[20:21], v[20:21], 0 op_sel:[1,0] op_sel_hi:[0,0] neg_hi:[1,0]
	v_pk_add_f32 v[28:29], v[244:245], v[248:249] op_sel:[0,1] op_sel_hi:[1,0] neg_lo:[0,1]
	v_pk_mul_f32 v[250:251], v[28:29], v[84:85] op_sel:[1,1] op_sel_hi:[1,0]
	v_pk_fma_f32 v[28:29], v[28:29], v[84:85], v[250:251] op_sel:[0,0,0] op_sel_hi:[0,1,1] neg_lo:[0,0,1]
	v_pk_mul_f32 v[250:251], v[28:29], v[224:225] op_sel:[1,1] op_sel_hi:[1,0] neg_lo:[0,1] neg_hi:[0,1]
	v_pk_fma_f32 v[28:29], v[28:29], v[224:225], v[250:251] op_sel:[0,0,0] op_sel_hi:[0,1,1] neg_lo:[0,1,1] neg_hi:[0,1,0]
	s_waitcnt lgkmcnt(0)
	v_pk_add_f32 v[242:243], v[6:7], v[22:23]
	v_pk_add_f32 v[244:245], v[6:7], v[22:23] neg_lo:[0,1] neg_hi:[0,1]
	v_pk_add_f32 v[246:247], v[14:15], v[30:31]
	v_pk_add_f32 v[248:249], v[14:15], v[30:31] neg_lo:[0,1] neg_hi:[0,1]
	v_pk_add_f32 v[6:7], v[242:243], v[246:247]
	v_pk_add_f32 v[14:15], v[244:245], v[248:249] op_sel:[0,1] op_sel_hi:[1,0] neg_hi:[0,1]
	v_pk_mul_f32 v[250:251], v[14:15], v[80:81] op_sel:[1,1] op_sel_hi:[1,0]
	v_pk_fma_f32 v[14:15], v[14:15], v[80:81], v[250:251] op_sel:[0,0,0] op_sel_hi:[0,1,1] neg_lo:[0,0,1]
	v_pk_mul_f32 v[250:251], v[14:15], v[222:223] op_sel:[1,0] op_sel_hi:[1,1] neg_lo:[0,1] neg_hi:[0,0]
	v_pk_fma_f32 v[14:15], v[14:15], v[222:223], v[250:251] op_sel:[0,1,0] op_sel_hi:[0,0,1] neg_lo:[0,0,1] neg_hi:[0,1,0]
	v_pk_add_f32 v[22:23], v[242:243], v[246:247] neg_lo:[0,1] neg_hi:[0,1]
	v_pk_mul_f32 v[250:251], v[22:23], v[82:83] op_sel:[1,1] op_sel_hi:[1,0]
	v_pk_fma_f32 v[22:23], v[22:23], v[82:83], v[250:251] op_sel:[0,0,0] op_sel_hi:[0,1,1] neg_lo:[0,0,1]
	v_pk_mul_f32 v[250:251], v[22:23], v[224:225] op_sel:[1,1] op_sel_hi:[1,0] neg_lo:[0,1] neg_hi:[0,1]
	v_pk_fma_f32 v[22:23], v[22:23], v[224:225], v[250:251] op_sel:[0,0,0] op_sel_hi:[0,1,1] neg_lo:[0,1,1] neg_hi:[0,1,0]
	v_pk_add_f32 v[30:31], v[244:245], v[248:249] op_sel:[0,1] op_sel_hi:[1,0] neg_lo:[0,1]
	v_pk_mul_f32 v[250:251], v[30:31], v[84:85] op_sel:[1,1] op_sel_hi:[1,0]
	v_pk_fma_f32 v[30:31], v[30:31], v[84:85], v[250:251] op_sel:[0,0,0] op_sel_hi:[0,1,1] neg_lo:[0,0,1]
	v_pk_mul_f32 v[250:251], v[30:31], v[222:223] op_sel:[1,1] op_sel_hi:[1,0] neg_lo:[0,0] neg_hi:[0,1]
	v_pk_fma_f32 v[30:31], v[30:31], v[222:223], v[250:251] op_sel:[0,0,0] op_sel_hi:[0,1,1] neg_lo:[0,1,1] neg_hi:[0,0,0]
	v_pk_add_f32 v[242:243], v[0:1], v[4:5]
	v_pk_add_f32 v[244:245], v[0:1], v[4:5] neg_lo:[0,1] neg_hi:[0,1]
	v_pk_add_f32 v[246:247], v[2:3], v[6:7]
	v_pk_add_f32 v[248:249], v[2:3], v[6:7] neg_lo:[0,1] neg_hi:[0,1]
	v_pk_add_f32 v[0:1], v[242:243], v[246:247]
	ds_write_b64 v227, v[0:1] offset:0
	v_pk_add_f32 v[2:3], v[244:245], v[248:249] op_sel:[0,1] op_sel_hi:[1,0] neg_hi:[0,1]
	v_pk_mul_f32 v[250:251], v[2:3], v[236:237] op_sel:[1,1] op_sel_hi:[1,0]
	v_pk_fma_f32 v[2:3], v[2:3], v[236:237], v[250:251] op_sel:[0,0,0] op_sel_hi:[0,1,1] neg_lo:[0,0,1]
	ds_write_b64 v227, v[2:3] offset:2048
	v_pk_add_f32 v[4:5], v[242:243], v[246:247] neg_lo:[0,1] neg_hi:[0,1]
	v_pk_mul_f32 v[250:251], v[4:5], v[238:239] op_sel:[1,1] op_sel_hi:[1,0]
	v_pk_fma_f32 v[4:5], v[4:5], v[238:239], v[250:251] op_sel:[0,0,0] op_sel_hi:[0,1,1] neg_lo:[0,0,1]
	ds_write_b64 v227, v[4:5] offset:4096
	v_pk_add_f32 v[6:7], v[244:245], v[248:249] op_sel:[0,1] op_sel_hi:[1,0] neg_lo:[0,1]
	v_pk_mul_f32 v[250:251], v[6:7], v[240:241] op_sel:[1,1] op_sel_hi:[1,0]
	v_pk_fma_f32 v[6:7], v[6:7], v[240:241], v[250:251] op_sel:[0,0,0] op_sel_hi:[0,1,1] neg_lo:[0,0,1]
	ds_write_b64 v227, v[6:7] offset:6144
	v_pk_add_f32 v[242:243], v[8:9], v[12:13]
	v_pk_add_f32 v[244:245], v[8:9], v[12:13] neg_lo:[0,1] neg_hi:[0,1]
	v_pk_add_f32 v[246:247], v[10:11], v[14:15]
	v_pk_add_f32 v[248:249], v[10:11], v[14:15] neg_lo:[0,1] neg_hi:[0,1]
	v_pk_add_f32 v[8:9], v[242:243], v[246:247]
	ds_write_b64 v227, v[8:9] offset:8192
	v_pk_add_f32 v[10:11], v[244:245], v[248:249] op_sel:[0,1] op_sel_hi:[1,0] neg_hi:[0,1]
	v_pk_mul_f32 v[250:251], v[10:11], v[236:237] op_sel:[1,1] op_sel_hi:[1,0]
	v_pk_fma_f32 v[10:11], v[10:11], v[236:237], v[250:251] op_sel:[0,0,0] op_sel_hi:[0,1,1] neg_lo:[0,0,1]
	ds_write_b64 v227, v[10:11] offset:10240
	v_pk_add_f32 v[12:13], v[242:243], v[246:247] neg_lo:[0,1] neg_hi:[0,1]
	v_pk_mul_f32 v[250:251], v[12:13], v[238:239] op_sel:[1,1] op_sel_hi:[1,0]
	v_pk_fma_f32 v[12:13], v[12:13], v[238:239], v[250:251] op_sel:[0,0,0] op_sel_hi:[0,1,1] neg_lo:[0,0,1]
	ds_write_b64 v227, v[12:13] offset:12288
	v_pk_add_f32 v[14:15], v[244:245], v[248:249] op_sel:[0,1] op_sel_hi:[1,0] neg_lo:[0,1]
	v_pk_mul_f32 v[250:251], v[14:15], v[240:241] op_sel:[1,1] op_sel_hi:[1,0]
; HD float2 cmul(float2 a, float2 b){ return make_float2(a.x*b.x - a.y*b.y, a.x*b.y + a.y*b.x); }
; HD float2 cmulc(float2 a, float2 b){ return make_float2(a.x*b.x + a.y*b.y, a.y*b.x - a.x*b.y); }
; template<bool INV, bool NOTW>
; HD void bf4c(float2* Z, int i0, int i1, int i2, int i3, float2 w1, float2 w2, float2 w3){
;   float2 a0=Z[i0], a1=Z[i1], a2=Z[i2], a3=Z[i3];
;   if (INV && !NOTW){ a1=cmulc(a1,w1); a2=cmulc(a2,w2); a3=cmulc(a3,w3); }
;   float2 s02=make_float2(a0.x+a2.x,a0.y+a2.y), d02=make_float2(a0.x-a2.x,a0.y-a2.y);
;   float2 s13=make_float2(a1.x+a3.x,a1.y+a3.y), d13=make_float2(a1.x-a3.x,a1.y-a3.y);
;   float2 y0=make_float2(s02.x+s13.x,s02.y+s13.y), y2=make_float2(s02.x-s13.x,s02.y-s13.y);
;   float2 ym=make_float2(d02.x+d13.y,d02.y-d13.x);
;   float2 yp=make_float2(d02.x-d13.y,d02.y+d13.x);
;   float2 y1, y3;
;   if (INV){ y1=yp; y3=ym; } else if (NOTW){ y1=ym; y3=yp; } else { y1=cmul(ym,w1); y2=cmul(y2,w2); y3=cmul(yp,w3); }
;   Z[i0]=y0; Z[i1]=y1; Z[i2]=y2; Z[i3]=y3;
; }
; template<bool INV, int LQ, bool BARRIER=true>
; HD void fft_pass(float2* Z, const float2* twA, const float2* twB, int tid){
;     ...
;     int j=tid&(q-1); int base0=((tid>>LQ)<<(LQ+2))+j;
;     float2 w1=make_float2(1.f,0.f), w2=w1, w3=w1;
;     if (LQ>0){ int k=j*tws; w1=cmul(twA[k>>6],twB[k&63]); w2=cmul(w1,w1); w3=cmul(w2,w1); }
;     _Pragma("unroll") for (int i=0;i<8;++i){ int base=base0+i*2048; bf4c<INV,(LQ==0)>(Z,base,base+q,base+2*q,base+3*q,w1,w2,w3); }
;   }
;   if (BARRIER) __syncthreads(); else asm volatile("s_waitcnt lgkmcnt(0)" ::: "memory");
	v_pk_fma_f32 v[14:15], v[14:15], v[240:241], v[250:251] op_sel:[0,0,0] op_sel_hi:[0,1,1] neg_lo:[0,0,1]
	ds_write_b64 v227, v[14:15] offset:14336
	v_pk_add_f32 v[242:243], v[16:17], v[20:21]
	v_pk_add_f32 v[244:245], v[16:17], v[20:21] neg_lo:[0,1] neg_hi:[0,1]
	v_pk_add_f32 v[246:247], v[18:19], v[22:23]
	v_pk_add_f32 v[248:249], v[18:19], v[22:23] neg_lo:[0,1] neg_hi:[0,1]
	v_pk_add_f32 v[16:17], v[242:243], v[246:247]
	ds_write_b64 v227, v[16:17] offset:16384
	v_pk_add_f32 v[18:19], v[244:245], v[248:249] op_sel:[0,1] op_sel_hi:[1,0] neg_hi:[0,1]
	v_pk_mul_f32 v[250:251], v[18:19], v[236:237] op_sel:[1,1] op_sel_hi:[1,0]
	v_pk_fma_f32 v[18:19], v[18:19], v[236:237], v[250:251] op_sel:[0,0,0] op_sel_hi:[0,1,1] neg_lo:[0,0,1]
	ds_write_b64 v227, v[18:19] offset:18432
	v_pk_add_f32 v[20:21], v[242:243], v[246:247] neg_lo:[0,1] neg_hi:[0,1]
	v_pk_mul_f32 v[250:251], v[20:21], v[238:239] op_sel:[1,1] op_sel_hi:[1,0]
	v_pk_fma_f32 v[20:21], v[20:21], v[238:239], v[250:251] op_sel:[0,0,0] op_sel_hi:[0,1,1] neg_lo:[0,0,1]
	ds_write_b64 v227, v[20:21] offset:20480
	v_pk_add_f32 v[22:23], v[244:245], v[248:249] op_sel:[0,1] op_sel_hi:[1,0] neg_lo:[0,1]
	v_pk_mul_f32 v[250:251], v[22:23], v[240:241] op_sel:[1,1] op_sel_hi:[1,0]
	v_pk_fma_f32 v[22:23], v[22:23], v[240:241], v[250:251] op_sel:[0,0,0] op_sel_hi:[0,1,1] neg_lo:[0,0,1]
	ds_write_b64 v227, v[22:23] offset:22528
	v_pk_add_f32 v[242:243], v[24:25], v[28:29]
	v_pk_add_f32 v[244:245], v[24:25], v[28:29] neg_lo:[0,1] neg_hi:[0,1]
	v_pk_add_f32 v[246:247], v[26:27], v[30:31]
	v_pk_add_f32 v[248:249], v[26:27], v[30:31] neg_lo:[0,1] neg_hi:[0,1]
	v_pk_add_f32 v[24:25], v[242:243], v[246:247]
	ds_write_b64 v227, v[24:25] offset:24576
	v_pk_add_f32 v[26:27], v[244:245], v[248:249] op_sel:[0,1] op_sel_hi:[1,0] neg_hi:[0,1]
	v_pk_mul_f32 v[250:251], v[26:27], v[236:237] op_sel:[1,1] op_sel_hi:[1,0]
	v_pk_fma_f32 v[26:27], v[26:27], v[236:237], v[250:251] op_sel:[0,0,0] op_sel_hi:[0,1,1] neg_lo:[0,0,1]
	ds_write_b64 v227, v[26:27] offset:26624
	v_pk_add_f32 v[28:29], v[242:243], v[246:247] neg_lo:[0,1] neg_hi:[0,1]
	v_pk_mul_f32 v[250:251], v[28:29], v[238:239] op_sel:[1,1] op_sel_hi:[1,0]
	v_pk_fma_f32 v[28:29], v[28:29], v[238:239], v[250:251] op_sel:[0,0,0] op_sel_hi:[0,1,1] neg_lo:[0,0,1]
	ds_write_b64 v227, v[28:29] offset:28672
	v_pk_add_f32 v[30:31], v[244:245], v[248:249] op_sel:[0,1] op_sel_hi:[1,0] neg_lo:[0,1]
	v_pk_mul_f32 v[250:251], v[30:31], v[240:241] op_sel:[1,1] op_sel_hi:[1,0]
	v_pk_fma_f32 v[30:31], v[30:31], v[240:241], v[250:251] op_sel:[0,0,0] op_sel_hi:[0,1,1] neg_lo:[0,0,1]
	ds_write_b64 v227, v[30:31] offset:30720
	s_waitcnt lgkmcnt(0)
	s_barrier
	v_and_b32_e32 v8, 15, v154
	v_lshlrev_b32_e32 v9, 3, v8
	v_add_u32_e32 v9, 0x20800, v9
	v_mov_b32_e32 v10, 0x20a00
	ds_read_b64 v[0:1], v9
	ds_read_b64 v[2:3], v10
	s_waitcnt lgkmcnt(0)
	v_pk_mul_f32 v[250:251], v[0:1], v[2:3] op_sel:[1,1] op_sel_hi:[1,0]
	v_pk_fma_f32 v[80:81], v[0:1], v[2:3], v[250:251] op_sel:[0,0,0] op_sel_hi:[0,1,1] neg_lo:[0,0,1]
	v_pk_mul_f32 v[250:251], v[80:81], v[80:81] op_sel:[1,1] op_sel_hi:[1,0]
	v_pk_fma_f32 v[82:83], v[80:81], v[80:81], v[250:251] op_sel:[0,0,0] op_sel_hi:[0,1,1] neg_lo:[0,0,1]
	v_pk_mul_f32 v[250:251], v[82:83], v[80:81] op_sel:[1,1] op_sel_hi:[1,0]
	v_pk_fma_f32 v[84:85], v[82:83], v[80:81], v[250:251] op_sel:[0,0,0] op_sel_hi:[0,1,1] neg_lo:[0,0,1]
	v_lshlrev_b32_e32 v9, 5, v8
	v_add_u32_e32 v9, 0x20800, v9
	v_mov_b32_e32 v10, 0x20a00
	ds_read_b64 v[0:1], v9
	ds_read_b64 v[2:3], v10
	s_waitcnt lgkmcnt(0)
	v_pk_mul_f32 v[250:251], v[0:1], v[2:3] op_sel:[1,1] op_sel_hi:[1,0]
	v_pk_fma_f32 v[236:237], v[0:1], v[2:3], v[250:251] op_sel:[0,0,0] op_sel_hi:[0,1,1] neg_lo:[0,0,1]
	v_pk_mul_f32 v[250:251], v[236:237], v[236:237] op_sel:[1,1] op_sel_hi:[1,0]
	v_pk_fma_f32 v[238:239], v[236:237], v[236:237], v[250:251] op_sel:[0,0,0] op_sel_hi:[0,1,1] neg_lo:[0,0,1]
	v_pk_mul_f32 v[250:251], v[238:239], v[236:237] op_sel:[1,1] op_sel_hi:[1,0]
	v_pk_fma_f32 v[240:241], v[238:239], v[236:237], v[250:251] op_sel:[0,0,0] op_sel_hi:[0,1,1] neg_lo:[0,0,1]
	v_lshrrev_b32_e32 v226, 6, v154
	v_bfe_u32 v227, v154, 4, 2
	v_lshl_add_u32 v226, v227, 3, v226
	v_lshlrev_b32_e32 v226, 8, v226
	v_and_b32_e32 v227, 15, v154
	v_add_u32_e32 v226, v226, v227
	v_lshlrev_b32_e32 v226, 3, v226
	v_add_u32_e32 v227, 0x10000, v226
	ds_read_b64 v[0:1], v226 offset:0
	ds_read_b64 v[8:9], v226 offset:512
	ds_read_b64 v[16:17], v226 offset:1024
	ds_read_b64 v[24:25], v226 offset:1536
	ds_read_b64 v[2:3], v226 offset:128
	ds_read_b64 v[10:11], v226 offset:640
	ds_read_b64 v[18:19], v226 offset:1152
	ds_read_b64 v[26:27], v226 offset:1664
	ds_read_b64 v[4:5], v226 offset:256
	ds_read_b64 v[12:13], v226 offset:768
	ds_read_b64 v[20:21], v226 offset:1280
	ds_read_b64 v[28:29], v226 offset:1792
	ds_read_b64 v[6:7], v226 offset:384
	ds_read_b64 v[14:15], v226 offset:896
	ds_read_b64 v[22:23], v226 offset:1408
	ds_read_b64 v[30:31], v226 offset:1920
	s_waitcnt lgkmcnt(12)
	v_pk_add_f32 v[242:243], v[0:1], v[16:17]
	v_pk_add_f32 v[244:245], v[0:1], v[16:17] neg_lo:[0,1] neg_hi:[0,1]
	v_pk_add_f32 v[246:247], v[8:9], v[24:25]
	v_pk_add_f32 v[248:249], v[8:9], v[24:25] neg_lo:[0,1] neg_hi:[0,1]
	v_pk_add_f32 v[0:1], v[242:243], v[246:247]
	v_pk_add_f32 v[8:9], v[244:245], v[248:249] op_sel:[0,1] op_sel_hi:[1,0] neg_hi:[0,1]
	v_pk_mul_f32 v[250:251], v[8:9], v[80:81] op_sel:[1,1] op_sel_hi:[1,0]
	v_pk_fma_f32 v[8:9], v[8:9], v[80:81], v[250:251] op_sel:[0,0,0] op_sel_hi:[0,1,1] neg_lo:[0,0,1]
	v_pk_add_f32 v[16:17], v[242:243], v[246:247] neg_lo:[0,1] neg_hi:[0,1]
	v_pk_mul_f32 v[250:251], v[16:17], v[82:83] op_sel:[1,1] op_sel_hi:[1,0]
	v_pk_fma_f32 v[16:17], v[16:17], v[82:83], v[250:251] op_sel:[0,0,0] op_sel_hi:[0,1,1] neg_lo:[0,0,1]
	v_pk_add_f32 v[24:25], v[244:245], v[248:249] op_sel:[0,1] op_sel_hi:[1,0] neg_lo:[0,1]
	v_pk_mul_f32 v[250:251], v[24:25], v[84:85] op_sel:[1,1] op_sel_hi:[1,0]
	v_pk_fma_f32 v[24:25], v[24:25], v[84:85], v[250:251] op_sel:[0,0,0] op_sel_hi:[0,1,1] neg_lo:[0,0,1]
	s_waitcnt lgkmcnt(8)
; HD float2 cmul(float2 a, float2 b){ return make_float2(a.x*b.x - a.y*b.y, a.x*b.y + a.y*b.x); }
; HD float2 cmulc(float2 a, float2 b){ return make_float2(a.x*b.x + a.y*b.y, a.y*b.x - a.x*b.y); }
; template<bool INV, bool NOTW>
; HD void bf4c(float2* Z, int i0, int i1, int i2, int i3, float2 w1, float2 w2, float2 w3){
;   float2 a0=Z[i0], a1=Z[i1], a2=Z[i2], a3=Z[i3];
;   if (INV && !NOTW){ a1=cmulc(a1,w1); a2=cmulc(a2,w2); a3=cmulc(a3,w3); }
;   float2 s02=make_float2(a0.x+a2.x,a0.y+a2.y), d02=make_float2(a0.x-a2.x,a0.y-a2.y);
;   float2 s13=make_float2(a1.x+a3.x,a1.y+a3.y), d13=make_float2(a1.x-a3.x,a1.y-a3.y);
;   float2 y0=make_float2(s02.x+s13.x,s02.y+s13.y), y2=make_float2(s02.x-s13.x,s02.y-s13.y);
;   float2 ym=make_float2(d02.x+d13.y,d02.y-d13.x);
;   float2 yp=make_float2(d02.x-d13.y,d02.y+d13.x);
;   float2 y1, y3;
;   if (INV){ y1=yp; y3=ym; } else if (NOTW){ y1=ym; y3=yp; } else { y1=cmul(ym,w1); y2=cmul(y2,w2); y3=cmul(yp,w3); }
;   Z[i0]=y0; Z[i1]=y1; Z[i2]=y2; Z[i3]=y3;
; }
; template<bool INV, int LQ, bool BARRIER=true>
; HD void fft_pass(float2* Z, const float2* twA, const float2* twB, int tid){
;     ...
;     int j=tid&(q-1); int base0=((tid>>LQ)<<(LQ+2))+j;
;     float2 w1=make_float2(1.f,0.f), w2=w1, w3=w1;
;     if (LQ>0){ int k=j*tws; w1=cmul(twA[k>>6],twB[k&63]); w2=cmul(w1,w1); w3=cmul(w2,w1); }
;     _Pragma("unroll") for (int i=0;i<8;++i){ int base=base0+i*2048; bf4c<INV,(LQ==0)>(Z,base,base+q,base+2*q,base+3*q,w1,w2,w3); }
;   }
;   if (BARRIER) __syncthreads(); else asm volatile("s_waitcnt lgkmcnt(0)" ::: "memory");
	v_pk_add_f32 v[242:243], v[2:3], v[18:19]
	v_pk_add_f32 v[244:245], v[2:3], v[18:19] neg_lo:[0,1] neg_hi:[0,1]
	v_pk_add_f32 v[246:247], v[10:11], v[26:27]
	v_pk_add_f32 v[248:249], v[10:11], v[26:27] neg_lo:[0,1] neg_hi:[0,1]
	v_pk_add_f32 v[2:3], v[242:243], v[246:247]
	v_pk_add_f32 v[10:11], v[244:245], v[248:249] op_sel:[0,1] op_sel_hi:[1,0] neg_hi:[0,1]
	v_pk_mul_f32 v[250:251], v[10:11], v[80:81] op_sel:[1,1] op_sel_hi:[1,0]
	v_pk_fma_f32 v[10:11], v[10:11], v[80:81], v[250:251] op_sel:[0,0,0] op_sel_hi:[0,1,1] neg_lo:[0,0,1]
	v_pk_mul_f32 v[250:251], v[10:11], v[222:223] op_sel:[1,1] op_sel_hi:[1,0] neg_lo:[0,1] neg_hi:[0,0]
	v_pk_fma_f32 v[10:11], v[10:11], v[222:223], v[250:251] op_sel:[0,0,0] op_sel_hi:[0,1,1] neg_lo:[0,0,1] neg_hi:[0,1,0]
	v_pk_add_f32 v[18:19], v[242:243], v[246:247] neg_lo:[0,1] neg_hi:[0,1]
	v_pk_mul_f32 v[250:251], v[18:19], v[82:83] op_sel:[1,1] op_sel_hi:[1,0]
	v_pk_fma_f32 v[18:19], v[18:19], v[82:83], v[250:251] op_sel:[0,0,0] op_sel_hi:[0,1,1] neg_lo:[0,0,1]
	v_pk_mul_f32 v[250:251], v[18:19], v[224:225] op_sel:[1,1] op_sel_hi:[1,0] neg_lo:[0,1] neg_hi:[0,0]
	v_pk_fma_f32 v[18:19], v[18:19], v[224:225], v[250:251] op_sel:[0,0,0] op_sel_hi:[0,1,1] neg_lo:[0,0,1] neg_hi:[0,1,0]
	v_pk_add_f32 v[26:27], v[244:245], v[248:249] op_sel:[0,1] op_sel_hi:[1,0] neg_lo:[0,1]
	v_pk_mul_f32 v[250:251], v[26:27], v[84:85] op_sel:[1,1] op_sel_hi:[1,0]
	v_pk_fma_f32 v[26:27], v[26:27], v[84:85], v[250:251] op_sel:[0,0,0] op_sel_hi:[0,1,1] neg_lo:[0,0,1]
	v_pk_mul_f32 v[250:251], v[26:27], v[222:223] op_sel:[1,0] op_sel_hi:[1,1] neg_lo:[0,1] neg_hi:[0,0]
	v_pk_fma_f32 v[26:27], v[26:27], v[222:223], v[250:251] op_sel:[0,1,0] op_sel_hi:[0,0,1] neg_lo:[0,0,1] neg_hi:[0,1,0]
	s_waitcnt lgkmcnt(4)
	v_pk_add_f32 v[242:243], v[4:5], v[20:21]
	v_pk_add_f32 v[244:245], v[4:5], v[20:21] neg_lo:[0,1] neg_hi:[0,1]
	v_pk_add_f32 v[246:247], v[12:13], v[28:29]
	v_pk_add_f32 v[248:249], v[12:13], v[28:29] neg_lo:[0,1] neg_hi:[0,1]
	v_pk_add_f32 v[4:5], v[242:243], v[246:247]
	v_pk_add_f32 v[12:13], v[244:245], v[248:249] op_sel:[0,1] op_sel_hi:[1,0] neg_hi:[0,1]
	v_pk_mul_f32 v[250:251], v[12:13], v[80:81] op_sel:[1,1] op_sel_hi:[1,0]
	v_pk_fma_f32 v[12:13], v[12:13], v[80:81], v[250:251] op_sel:[0,0,0] op_sel_hi:[0,1,1] neg_lo:[0,0,1]
	v_pk_mul_f32 v[250:251], v[12:13], v[224:225] op_sel:[1,1] op_sel_hi:[1,0] neg_lo:[0,1] neg_hi:[0,0]
	v_pk_fma_f32 v[12:13], v[12:13], v[224:225], v[250:251] op_sel:[0,0,0] op_sel_hi:[0,1,1] neg_lo:[0,0,1] neg_hi:[0,1,0]
	v_pk_add_f32 v[20:21], v[242:243], v[246:247] neg_lo:[0,1] neg_hi:[0,1]
	v_pk_mul_f32 v[250:251], v[20:21], v[82:83] op_sel:[1,1] op_sel_hi:[1,0]
	v_pk_fma_f32 v[20:21], v[20:21], v[82:83], v[250:251] op_sel:[0,0,0] op_sel_hi:[0,1,1] neg_lo:[0,0,1]
	v_pk_add_f32 v[20:21], v[20:21], 0 op_sel:[1,0] op_sel_hi:[0,0] neg_hi:[1,0]
	v_pk_add_f32 v[28:29], v[244:245], v[248:249] op_sel:[0,1] op_sel_hi:[1,0] neg_lo:[0,1]
	v_pk_mul_f32 v[250:251], v[28:29], v[84:85] op_sel:[1,1] op_sel_hi:[1,0]
	v_pk_fma_f32 v[28:29], v[28:29], v[84:85], v[250:251] op_sel:[0,0,0] op_sel_hi:[0,1,1] neg_lo:[0,0,1]
	v_pk_mul_f32 v[250:251], v[28:29], v[224:225] op_sel:[1,1] op_sel_hi:[1,0] neg_lo:[0,1] neg_hi:[0,1]
	v_pk_fma_f32 v[28:29], v[28:29], v[224:225], v[250:251] op_sel:[0,0,0] op_sel_hi:[0,1,1] neg_lo:[0,1,1] neg_hi:[0,1,0]
	s_waitcnt lgkmcnt(0)
	v_pk_add_f32 v[242:243], v[6:7], v[22:23]
	v_pk_add_f32 v[244:245], v[6:7], v[22:23] neg_lo:[0,1] neg_hi:[0,1]
	v_pk_add_f32 v[246:247], v[14:15], v[30:31]
	v_pk_add_f32 v[248:249], v[14:15], v[30:31] neg_lo:[0,1] neg_hi:[0,1]
	v_pk_add_f32 v[6:7], v[242:243], v[246:247]
	v_pk_add_f32 v[14:15], v[244:245], v[248:249] op_sel:[0,1] op_sel_hi:[1,0] neg_hi:[0,1]
	v_pk_mul_f32 v[250:251], v[14:15], v[80:81] op_sel:[1,1] op_sel_hi:[1,0]
	v_pk_fma_f32 v[14:15], v[14:15], v[80:81], v[250:251] op_sel:[0,0,0] op_sel_hi:[0,1,1] neg_lo:[0,0,1]
	v_pk_mul_f32 v[250:251], v[14:15], v[222:223] op_sel:[1,0] op_sel_hi:[1,1] neg_lo:[0,1] neg_hi:[0,0]
	v_pk_fma_f32 v[14:15], v[14:15], v[222:223], v[250:251] op_sel:[0,1,0] op_sel_hi:[0,0,1] neg_lo:[0,0,1] neg_hi:[0,1,0]
	v_pk_add_f32 v[22:23], v[242:243], v[246:247] neg_lo:[0,1] neg_hi:[0,1]
	v_pk_mul_f32 v[250:251], v[22:23], v[82:83] op_sel:[1,1] op_sel_hi:[1,0]
	v_pk_fma_f32 v[22:23], v[22:23], v[82:83], v[250:251] op_sel:[0,0,0] op_sel_hi:[0,1,1] neg_lo:[0,0,1]
	v_pk_mul_f32 v[250:251], v[22:23], v[224:225] op_sel:[1,1] op_sel_hi:[1,0] neg_lo:[0,1] neg_hi:[0,1]
	v_pk_fma_f32 v[22:23], v[22:23], v[224:225], v[250:251] op_sel:[0,0,0] op_sel_hi:[0,1,1] neg_lo:[0,1,1] neg_hi:[0,1,0]
	v_pk_add_f32 v[30:31], v[244:245], v[248:249] op_sel:[0,1] op_sel_hi:[1,0] neg_lo:[0,1]
	v_pk_mul_f32 v[250:251], v[30:31], v[84:85] op_sel:[1,1] op_sel_hi:[1,0]
	v_pk_fma_f32 v[30:31], v[30:31], v[84:85], v[250:251] op_sel:[0,0,0] op_sel_hi:[0,1,1] neg_lo:[0,0,1]
	v_pk_mul_f32 v[250:251], v[30:31], v[222:223] op_sel:[1,1] op_sel_hi:[1,0] neg_lo:[0,0] neg_hi:[0,1]
	v_pk_fma_f32 v[30:31], v[30:31], v[222:223], v[250:251] op_sel:[0,0,0] op_sel_hi:[0,1,1] neg_lo:[0,1,1] neg_hi:[0,0,0]
	v_pk_add_f32 v[242:243], v[0:1], v[4:5]
	v_pk_add_f32 v[244:245], v[0:1], v[4:5] neg_lo:[0,1] neg_hi:[0,1]
	v_pk_add_f32 v[246:247], v[2:3], v[6:7]
	v_pk_add_f32 v[248:249], v[2:3], v[6:7] neg_lo:[0,1] neg_hi:[0,1]
	v_pk_add_f32 v[0:1], v[242:243], v[246:247]
	ds_write_b64 v226, v[0:1] offset:0
	v_pk_add_f32 v[2:3], v[244:245], v[248:249] op_sel:[0,1] op_sel_hi:[1,0] neg_hi:[0,1]
	v_pk_mul_f32 v[250:251], v[2:3], v[236:237] op_sel:[1,1] op_sel_hi:[1,0]
	v_pk_fma_f32 v[2:3], v[2:3], v[236:237], v[250:251] op_sel:[0,0,0] op_sel_hi:[0,1,1] neg_lo:[0,0,1]
; HD float2 cmul(float2 a, float2 b){ return make_float2(a.x*b.x - a.y*b.y, a.x*b.y + a.y*b.x); }
; HD float2 cmulc(float2 a, float2 b){ return make_float2(a.x*b.x + a.y*b.y, a.y*b.x - a.x*b.y); }
; template<bool INV, bool NOTW>
; HD void bf4c(float2* Z, int i0, int i1, int i2, int i3, float2 w1, float2 w2, float2 w3){
;   float2 a0=Z[i0], a1=Z[i1], a2=Z[i2], a3=Z[i3];
;   if (INV && !NOTW){ a1=cmulc(a1,w1); a2=cmulc(a2,w2); a3=cmulc(a3,w3); }
;   float2 s02=make_float2(a0.x+a2.x,a0.y+a2.y), d02=make_float2(a0.x-a2.x,a0.y-a2.y);
;   float2 s13=make_float2(a1.x+a3.x,a1.y+a3.y), d13=make_float2(a1.x-a3.x,a1.y-a3.y);
;   float2 y0=make_float2(s02.x+s13.x,s02.y+s13.y), y2=make_float2(s02.x-s13.x,s02.y-s13.y);
;   float2 ym=make_float2(d02.x+d13.y,d02.y-d13.x);
;   float2 yp=make_float2(d02.x-d13.y,d02.y+d13.x);
;   float2 y1, y3;
;   if (INV){ y1=yp; y3=ym; } else if (NOTW){ y1=ym; y3=yp; } else { y1=cmul(ym,w1); y2=cmul(y2,w2); y3=cmul(yp,w3); }
;   Z[i0]=y0; Z[i1]=y1; Z[i2]=y2; Z[i3]=y3;
; }
; template<bool INV, int LQ, bool BARRIER=true>
; HD void fft_pass(float2* Z, const float2* twA, const float2* twB, int tid){
;     ...
;     int j=tid&(q-1); int base0=((tid>>LQ)<<(LQ+2))+j;
;     float2 w1=make_float2(1.f,0.f), w2=w1, w3=w1;
;     if (LQ>0){ int k=j*tws; w1=cmul(twA[k>>6],twB[k&63]); w2=cmul(w1,w1); w3=cmul(w2,w1); }
;     _Pragma("unroll") for (int i=0;i<8;++i){ int base=base0+i*2048; bf4c<INV,(LQ==0)>(Z,base,base+q,base+2*q,base+3*q,w1,w2,w3); }
;   }
;   if (BARRIER) __syncthreads(); else asm volatile("s_waitcnt lgkmcnt(0)" ::: "memory");
	ds_write_b64 v226, v[2:3] offset:128
	v_pk_add_f32 v[4:5], v[242:243], v[246:247] neg_lo:[0,1] neg_hi:[0,1]
	v_pk_mul_f32 v[250:251], v[4:5], v[238:239] op_sel:[1,1] op_sel_hi:[1,0]
	v_pk_fma_f32 v[4:5], v[4:5], v[238:239], v[250:251] op_sel:[0,0,0] op_sel_hi:[0,1,1] neg_lo:[0,0,1]
	ds_write_b64 v226, v[4:5] offset:256
	v_pk_add_f32 v[6:7], v[244:245], v[248:249] op_sel:[0,1] op_sel_hi:[1,0] neg_lo:[0,1]
	v_pk_mul_f32 v[250:251], v[6:7], v[240:241] op_sel:[1,1] op_sel_hi:[1,0]
	v_pk_fma_f32 v[6:7], v[6:7], v[240:241], v[250:251] op_sel:[0,0,0] op_sel_hi:[0,1,1] neg_lo:[0,0,1]
	ds_write_b64 v226, v[6:7] offset:384
	v_pk_add_f32 v[242:243], v[8:9], v[12:13]
	v_pk_add_f32 v[244:245], v[8:9], v[12:13] neg_lo:[0,1] neg_hi:[0,1]
	v_pk_add_f32 v[246:247], v[10:11], v[14:15]
	v_pk_add_f32 v[248:249], v[10:11], v[14:15] neg_lo:[0,1] neg_hi:[0,1]
	v_pk_add_f32 v[8:9], v[242:243], v[246:247]
	ds_write_b64 v226, v[8:9] offset:512
	v_pk_add_f32 v[10:11], v[244:245], v[248:249] op_sel:[0,1] op_sel_hi:[1,0] neg_hi:[0,1]
	v_pk_mul_f32 v[250:251], v[10:11], v[236:237] op_sel:[1,1] op_sel_hi:[1,0]
	v_pk_fma_f32 v[10:11], v[10:11], v[236:237], v[250:251] op_sel:[0,0,0] op_sel_hi:[0,1,1] neg_lo:[0,0,1]
	ds_write_b64 v226, v[10:11] offset:640
	v_pk_add_f32 v[12:13], v[242:243], v[246:247] neg_lo:[0,1] neg_hi:[0,1]
	v_pk_mul_f32 v[250:251], v[12:13], v[238:239] op_sel:[1,1] op_sel_hi:[1,0]
	v_pk_fma_f32 v[12:13], v[12:13], v[238:239], v[250:251] op_sel:[0,0,0] op_sel_hi:[0,1,1] neg_lo:[0,0,1]
	ds_write_b64 v226, v[12:13] offset:768
	v_pk_add_f32 v[14:15], v[244:245], v[248:249] op_sel:[0,1] op_sel_hi:[1,0] neg_lo:[0,1]
	v_pk_mul_f32 v[250:251], v[14:15], v[240:241] op_sel:[1,1] op_sel_hi:[1,0]
	v_pk_fma_f32 v[14:15], v[14:15], v[240:241], v[250:251] op_sel:[0,0,0] op_sel_hi:[0,1,1] neg_lo:[0,0,1]
	ds_write_b64 v226, v[14:15] offset:896
	v_pk_add_f32 v[242:243], v[16:17], v[20:21]
	v_pk_add_f32 v[244:245], v[16:17], v[20:21] neg_lo:[0,1] neg_hi:[0,1]
	v_pk_add_f32 v[246:247], v[18:19], v[22:23]
	v_pk_add_f32 v[248:249], v[18:19], v[22:23] neg_lo:[0,1] neg_hi:[0,1]
	v_pk_add_f32 v[16:17], v[242:243], v[246:247]
	ds_write_b64 v226, v[16:17] offset:1024
	v_pk_add_f32 v[18:19], v[244:245], v[248:249] op_sel:[0,1] op_sel_hi:[1,0] neg_hi:[0,1]
	v_pk_mul_f32 v[250:251], v[18:19], v[236:237] op_sel:[1,1] op_sel_hi:[1,0]
	v_pk_fma_f32 v[18:19], v[18:19], v[236:237], v[250:251] op_sel:[0,0,0] op_sel_hi:[0,1,1] neg_lo:[0,0,1]
	ds_write_b64 v226, v[18:19] offset:1152
	v_pk_add_f32 v[20:21], v[242:243], v[246:247] neg_lo:[0,1] neg_hi:[0,1]
	v_pk_mul_f32 v[250:251], v[20:21], v[238:239] op_sel:[1,1] op_sel_hi:[1,0]
	v_pk_fma_f32 v[20:21], v[20:21], v[238:239], v[250:251] op_sel:[0,0,0] op_sel_hi:[0,1,1] neg_lo:[0,0,1]
	ds_write_b64 v226, v[20:21] offset:1280
	v_pk_add_f32 v[22:23], v[244:245], v[248:249] op_sel:[0,1] op_sel_hi:[1,0] neg_lo:[0,1]
	v_pk_mul_f32 v[250:251], v[22:23], v[240:241] op_sel:[1,1] op_sel_hi:[1,0]
	v_pk_fma_f32 v[22:23], v[22:23], v[240:241], v[250:251] op_sel:[0,0,0] op_sel_hi:[0,1,1] neg_lo:[0,0,1]
	ds_write_b64 v226, v[22:23] offset:1408
	v_pk_add_f32 v[242:243], v[24:25], v[28:29]
	v_pk_add_f32 v[244:245], v[24:25], v[28:29] neg_lo:[0,1] neg_hi:[0,1]
	v_pk_add_f32 v[246:247], v[26:27], v[30:31]
	v_pk_add_f32 v[248:249], v[26:27], v[30:31] neg_lo:[0,1] neg_hi:[0,1]
	v_pk_add_f32 v[24:25], v[242:243], v[246:247]
	ds_write_b64 v226, v[24:25] offset:1536
	v_pk_add_f32 v[26:27], v[244:245], v[248:249] op_sel:[0,1] op_sel_hi:[1,0] neg_hi:[0,1]
	v_pk_mul_f32 v[250:251], v[26:27], v[236:237] op_sel:[1,1] op_sel_hi:[1,0]
	v_pk_fma_f32 v[26:27], v[26:27], v[236:237], v[250:251] op_sel:[0,0,0] op_sel_hi:[0,1,1] neg_lo:[0,0,1]
	ds_write_b64 v226, v[26:27] offset:1664
	v_pk_add_f32 v[28:29], v[242:243], v[246:247] neg_lo:[0,1] neg_hi:[0,1]
	v_pk_mul_f32 v[250:251], v[28:29], v[238:239] op_sel:[1,1] op_sel_hi:[1,0]
	v_pk_fma_f32 v[28:29], v[28:29], v[238:239], v[250:251] op_sel:[0,0,0] op_sel_hi:[0,1,1] neg_lo:[0,0,1]
	ds_write_b64 v226, v[28:29] offset:1792
	v_pk_add_f32 v[30:31], v[244:245], v[248:249] op_sel:[0,1] op_sel_hi:[1,0] neg_lo:[0,1]
	v_pk_mul_f32 v[250:251], v[30:31], v[240:241] op_sel:[1,1] op_sel_hi:[1,0]
	v_pk_fma_f32 v[30:31], v[30:31], v[240:241], v[250:251] op_sel:[0,0,0] op_sel_hi:[0,1,1] neg_lo:[0,0,1]
	ds_write_b64 v226, v[30:31] offset:1920
	ds_read_b64 v[0:1], v227 offset:0
	ds_read_b64 v[8:9], v227 offset:512
	ds_read_b64 v[16:17], v227 offset:1024
	ds_read_b64 v[24:25], v227 offset:1536
	ds_read_b64 v[2:3], v227 offset:128
	ds_read_b64 v[10:11], v227 offset:640
	ds_read_b64 v[18:19], v227 offset:1152
	ds_read_b64 v[26:27], v227 offset:1664
	ds_read_b64 v[4:5], v227 offset:256
	ds_read_b64 v[12:13], v227 offset:768
	ds_read_b64 v[20:21], v227 offset:1280
	ds_read_b64 v[28:29], v227 offset:1792
	ds_read_b64 v[6:7], v227 offset:384
	ds_read_b64 v[14:15], v227 offset:896
	ds_read_b64 v[22:23], v227 offset:1408
	ds_read_b64 v[30:31], v227 offset:1920
	s_waitcnt lgkmcnt(12)
	v_pk_add_f32 v[242:243], v[0:1], v[16:17]
	v_pk_add_f32 v[244:245], v[0:1], v[16:17] neg_lo:[0,1] neg_hi:[0,1]
	v_pk_add_f32 v[246:247], v[8:9], v[24:25]
	v_pk_add_f32 v[248:249], v[8:9], v[24:25] neg_lo:[0,1] neg_hi:[0,1]
	v_pk_add_f32 v[0:1], v[242:243], v[246:247]
	v_pk_add_f32 v[8:9], v[244:245], v[248:249] op_sel:[0,1] op_sel_hi:[1,0] neg_hi:[0,1]
	v_pk_mul_f32 v[250:251], v[8:9], v[80:81] op_sel:[1,1] op_sel_hi:[1,0]
	v_pk_fma_f32 v[8:9], v[8:9], v[80:81], v[250:251] op_sel:[0,0,0] op_sel_hi:[0,1,1] neg_lo:[0,0,1]
	v_pk_add_f32 v[16:17], v[242:243], v[246:247] neg_lo:[0,1] neg_hi:[0,1]
	v_pk_mul_f32 v[250:251], v[16:17], v[82:83] op_sel:[1,1] op_sel_hi:[1,0]
	v_pk_fma_f32 v[16:17], v[16:17], v[82:83], v[250:251] op_sel:[0,0,0] op_sel_hi:[0,1,1] neg_lo:[0,0,1]
	v_pk_add_f32 v[24:25], v[244:245], v[248:249] op_sel:[0,1] op_sel_hi:[1,0] neg_lo:[0,1]
	v_pk_mul_f32 v[250:251], v[24:25], v[84:85] op_sel:[1,1] op_sel_hi:[1,0]
	v_pk_fma_f32 v[24:25], v[24:25], v[84:85], v[250:251] op_sel:[0,0,0] op_sel_hi:[0,1,1] neg_lo:[0,0,1]
	s_waitcnt lgkmcnt(8)
; HD float2 cmul(float2 a, float2 b){ return make_float2(a.x*b.x - a.y*b.y, a.x*b.y + a.y*b.x); }
; HD float2 cmulc(float2 a, float2 b){ return make_float2(a.x*b.x + a.y*b.y, a.y*b.x - a.x*b.y); }
; template<bool INV, bool NOTW>
; HD void bf4c(float2* Z, int i0, int i1, int i2, int i3, float2 w1, float2 w2, float2 w3){
;   float2 a0=Z[i0], a1=Z[i1], a2=Z[i2], a3=Z[i3];
;   if (INV && !NOTW){ a1=cmulc(a1,w1); a2=cmulc(a2,w2); a3=cmulc(a3,w3); }
;   float2 s02=make_float2(a0.x+a2.x,a0.y+a2.y), d02=make_float2(a0.x-a2.x,a0.y-a2.y);
;   float2 s13=make_float2(a1.x+a3.x,a1.y+a3.y), d13=make_float2(a1.x-a3.x,a1.y-a3.y);
;   float2 y0=make_float2(s02.x+s13.x,s02.y+s13.y), y2=make_float2(s02.x-s13.x,s02.y-s13.y);
;   float2 ym=make_float2(d02.x+d13.y,d02.y-d13.x);
;   float2 yp=make_float2(d02.x-d13.y,d02.y+d13.x);
;   float2 y1, y3;
;   if (INV){ y1=yp; y3=ym; } else if (NOTW){ y1=ym; y3=yp; } else { y1=cmul(ym,w1); y2=cmul(y2,w2); y3=cmul(yp,w3); }
;   Z[i0]=y0; Z[i1]=y1; Z[i2]=y2; Z[i3]=y3;
; }
; template<bool INV, int LQ, bool BARRIER=true>
; HD void fft_pass(float2* Z, const float2* twA, const float2* twB, int tid){
;     ...
;     int j=tid&(q-1); int base0=((tid>>LQ)<<(LQ+2))+j;
;     float2 w1=make_float2(1.f,0.f), w2=w1, w3=w1;
;     if (LQ>0){ int k=j*tws; w1=cmul(twA[k>>6],twB[k&63]); w2=cmul(w1,w1); w3=cmul(w2,w1); }
;     _Pragma("unroll") for (int i=0;i<8;++i){ int base=base0+i*2048; bf4c<INV,(LQ==0)>(Z,base,base+q,base+2*q,base+3*q,w1,w2,w3); }
;   }
;   if (BARRIER) __syncthreads(); else asm volatile("s_waitcnt lgkmcnt(0)" ::: "memory");
	v_pk_add_f32 v[242:243], v[2:3], v[18:19]
	v_pk_add_f32 v[244:245], v[2:3], v[18:19] neg_lo:[0,1] neg_hi:[0,1]
	v_pk_add_f32 v[246:247], v[10:11], v[26:27]
	v_pk_add_f32 v[248:249], v[10:11], v[26:27] neg_lo:[0,1] neg_hi:[0,1]
	v_pk_add_f32 v[2:3], v[242:243], v[246:247]
	v_pk_add_f32 v[10:11], v[244:245], v[248:249] op_sel:[0,1] op_sel_hi:[1,0] neg_hi:[0,1]
	v_pk_mul_f32 v[250:251], v[10:11], v[80:81] op_sel:[1,1] op_sel_hi:[1,0]
	v_pk_fma_f32 v[10:11], v[10:11], v[80:81], v[250:251] op_sel:[0,0,0] op_sel_hi:[0,1,1] neg_lo:[0,0,1]
	v_pk_mul_f32 v[250:251], v[10:11], v[222:223] op_sel:[1,1] op_sel_hi:[1,0] neg_lo:[0,1] neg_hi:[0,0]
	v_pk_fma_f32 v[10:11], v[10:11], v[222:223], v[250:251] op_sel:[0,0,0] op_sel_hi:[0,1,1] neg_lo:[0,0,1] neg_hi:[0,1,0]
	v_pk_add_f32 v[18:19], v[242:243], v[246:247] neg_lo:[0,1] neg_hi:[0,1]
	v_pk_mul_f32 v[250:251], v[18:19], v[82:83] op_sel:[1,1] op_sel_hi:[1,0]
	v_pk_fma_f32 v[18:19], v[18:19], v[82:83], v[250:251] op_sel:[0,0,0] op_sel_hi:[0,1,1] neg_lo:[0,0,1]
	v_pk_mul_f32 v[250:251], v[18:19], v[224:225] op_sel:[1,1] op_sel_hi:[1,0] neg_lo:[0,1] neg_hi:[0,0]
	v_pk_fma_f32 v[18:19], v[18:19], v[224:225], v[250:251] op_sel:[0,0,0] op_sel_hi:[0,1,1] neg_lo:[0,0,1] neg_hi:[0,1,0]
	v_pk_add_f32 v[26:27], v[244:245], v[248:249] op_sel:[0,1] op_sel_hi:[1,0] neg_lo:[0,1]
	v_pk_mul_f32 v[250:251], v[26:27], v[84:85] op_sel:[1,1] op_sel_hi:[1,0]
	v_pk_fma_f32 v[26:27], v[26:27], v[84:85], v[250:251] op_sel:[0,0,0] op_sel_hi:[0,1,1] neg_lo:[0,0,1]
	v_pk_mul_f32 v[250:251], v[26:27], v[222:223] op_sel:[1,0] op_sel_hi:[1,1] neg_lo:[0,1] neg_hi:[0,0]
	v_pk_fma_f32 v[26:27], v[26:27], v[222:223], v[250:251] op_sel:[0,1,0] op_sel_hi:[0,0,1] neg_lo:[0,0,1] neg_hi:[0,1,0]
	s_waitcnt lgkmcnt(4)
	v_pk_add_f32 v[242:243], v[4:5], v[20:21]
	v_pk_add_f32 v[244:245], v[4:5], v[20:21] neg_lo:[0,1] neg_hi:[0,1]
	v_pk_add_f32 v[246:247], v[12:13], v[28:29]
	v_pk_add_f32 v[248:249], v[12:13], v[28:29] neg_lo:[0,1] neg_hi:[0,1]
	v_pk_add_f32 v[4:5], v[242:243], v[246:247]
	v_pk_add_f32 v[12:13], v[244:245], v[248:249] op_sel:[0,1] op_sel_hi:[1,0] neg_hi:[0,1]
	v_pk_mul_f32 v[250:251], v[12:13], v[80:81] op_sel:[1,1] op_sel_hi:[1,0]
	v_pk_fma_f32 v[12:13], v[12:13], v[80:81], v[250:251] op_sel:[0,0,0] op_sel_hi:[0,1,1] neg_lo:[0,0,1]
	v_pk_mul_f32 v[250:251], v[12:13], v[224:225] op_sel:[1,1] op_sel_hi:[1,0] neg_lo:[0,1] neg_hi:[0,0]
	v_pk_fma_f32 v[12:13], v[12:13], v[224:225], v[250:251] op_sel:[0,0,0] op_sel_hi:[0,1,1] neg_lo:[0,0,1] neg_hi:[0,1,0]
	v_pk_add_f32 v[20:21], v[242:243], v[246:247] neg_lo:[0,1] neg_hi:[0,1]
	v_pk_mul_f32 v[250:251], v[20:21], v[82:83] op_sel:[1,1] op_sel_hi:[1,0]
	v_pk_fma_f32 v[20:21], v[20:21], v[82:83], v[250:251] op_sel:[0,0,0] op_sel_hi:[0,1,1] neg_lo:[0,0,1]
	v_pk_add_f32 v[20:21], v[20:21], 0 op_sel:[1,0] op_sel_hi:[0,0] neg_hi:[1,0]
	v_pk_add_f32 v[28:29], v[244:245], v[248:249] op_sel:[0,1] op_sel_hi:[1,0] neg_lo:[0,1]
	v_pk_mul_f32 v[250:251], v[28:29], v[84:85] op_sel:[1,1] op_sel_hi:[1,0]
	v_pk_fma_f32 v[28:29], v[28:29], v[84:85], v[250:251] op_sel:[0,0,0] op_sel_hi:[0,1,1] neg_lo:[0,0,1]
	v_pk_mul_f32 v[250:251], v[28:29], v[224:225] op_sel:[1,1] op_sel_hi:[1,0] neg_lo:[0,1] neg_hi:[0,1]
	v_pk_fma_f32 v[28:29], v[28:29], v[224:225], v[250:251] op_sel:[0,0,0] op_sel_hi:[0,1,1] neg_lo:[0,1,1] neg_hi:[0,1,0]
	s_waitcnt lgkmcnt(0)
	v_pk_add_f32 v[242:243], v[6:7], v[22:23]
	v_pk_add_f32 v[244:245], v[6:7], v[22:23] neg_lo:[0,1] neg_hi:[0,1]
	v_pk_add_f32 v[246:247], v[14:15], v[30:31]
	v_pk_add_f32 v[248:249], v[14:15], v[30:31] neg_lo:[0,1] neg_hi:[0,1]
	v_pk_add_f32 v[6:7], v[242:243], v[246:247]
	v_pk_add_f32 v[14:15], v[244:245], v[248:249] op_sel:[0,1] op_sel_hi:[1,0] neg_hi:[0,1]
	v_pk_mul_f32 v[250:251], v[14:15], v[80:81] op_sel:[1,1] op_sel_hi:[1,0]
	v_pk_fma_f32 v[14:15], v[14:15], v[80:81], v[250:251] op_sel:[0,0,0] op_sel_hi:[0,1,1] neg_lo:[0,0,1]
	v_pk_mul_f32 v[250:251], v[14:15], v[222:223] op_sel:[1,0] op_sel_hi:[1,1] neg_lo:[0,1] neg_hi:[0,0]
	v_pk_fma_f32 v[14:15], v[14:15], v[222:223], v[250:251] op_sel:[0,1,0] op_sel_hi:[0,0,1] neg_lo:[0,0,1] neg_hi:[0,1,0]
	v_pk_add_f32 v[22:23], v[242:243], v[246:247] neg_lo:[0,1] neg_hi:[0,1]
	v_pk_mul_f32 v[250:251], v[22:23], v[82:83] op_sel:[1,1] op_sel_hi:[1,0]
	v_pk_fma_f32 v[22:23], v[22:23], v[82:83], v[250:251] op_sel:[0,0,0] op_sel_hi:[0,1,1] neg_lo:[0,0,1]
	v_pk_mul_f32 v[250:251], v[22:23], v[224:225] op_sel:[1,1] op_sel_hi:[1,0] neg_lo:[0,1] neg_hi:[0,1]
	v_pk_fma_f32 v[22:23], v[22:23], v[224:225], v[250:251] op_sel:[0,0,0] op_sel_hi:[0,1,1] neg_lo:[0,1,1] neg_hi:[0,1,0]
	v_pk_add_f32 v[30:31], v[244:245], v[248:249] op_sel:[0,1] op_sel_hi:[1,0] neg_lo:[0,1]
	v_pk_mul_f32 v[250:251], v[30:31], v[84:85] op_sel:[1,1] op_sel_hi:[1,0]
	v_pk_fma_f32 v[30:31], v[30:31], v[84:85], v[250:251] op_sel:[0,0,0] op_sel_hi:[0,1,1] neg_lo:[0,0,1]
	v_pk_mul_f32 v[250:251], v[30:31], v[222:223] op_sel:[1,1] op_sel_hi:[1,0] neg_lo:[0,0] neg_hi:[0,1]
	v_pk_fma_f32 v[30:31], v[30:31], v[222:223], v[250:251] op_sel:[0,0,0] op_sel_hi:[0,1,1] neg_lo:[0,1,1] neg_hi:[0,0,0]
	v_pk_add_f32 v[242:243], v[0:1], v[4:5]
	v_pk_add_f32 v[244:245], v[0:1], v[4:5] neg_lo:[0,1] neg_hi:[0,1]
	v_pk_add_f32 v[246:247], v[2:3], v[6:7]
	v_pk_add_f32 v[248:249], v[2:3], v[6:7] neg_lo:[0,1] neg_hi:[0,1]
	v_pk_add_f32 v[0:1], v[242:243], v[246:247]
	ds_write_b64 v227, v[0:1] offset:0
	v_pk_add_f32 v[2:3], v[244:245], v[248:249] op_sel:[0,1] op_sel_hi:[1,0] neg_hi:[0,1]
	v_pk_mul_f32 v[250:251], v[2:3], v[236:237] op_sel:[1,1] op_sel_hi:[1,0]
	v_pk_fma_f32 v[2:3], v[2:3], v[236:237], v[250:251] op_sel:[0,0,0] op_sel_hi:[0,1,1] neg_lo:[0,0,1]
; HD float2 cmul(float2 a, float2 b){ return make_float2(a.x*b.x - a.y*b.y, a.x*b.y + a.y*b.x); }
; template<bool INV, int LQ, bool BARRIER=true>
; HD void fft_pass(float2* Z, const float2* twA, const float2* twB, int tid){
;     ...
;     int j=tid&(q-1); int base0=((tid>>LQ)<<(LQ+2))+j;
;     float2 w1=make_float2(1.f,0.f), w2=w1, w3=w1;
;     if (LQ>0){ int k=j*tws; w1=cmul(twA[k>>6],twB[k&63]); w2=cmul(w1,w1); w3=cmul(w2,w1); }
;     _Pragma("unroll") for (int i=0;i<8;++i){ int base=base0+i*2048; bf4c<INV,(LQ==0)>(Z,base,base+q,base+2*q,base+3*q,w1,w2,w3); }
;   }
;   if (BARRIER) __syncthreads(); else asm volatile("s_waitcnt lgkmcnt(0)" ::: "memory");
; }
; __device__ __forceinline__ void fft_fwd_head(float2* Z, const float2* twA, const float2* twB, int tid){
;   fft_pass<false,10>(Z,twA,twB,tid); fft_pass<false,8>(Z,twA,twB,tid); fft_pass<false,6,false>(Z,twA,twB,tid);
;   fft_pass<false,4,false>(Z,twA,twB,tid); fft_pass<false,2,false>(Z,twA,twB,tid);
	ds_write_b64 v227, v[2:3] offset:128
	v_pk_add_f32 v[4:5], v[242:243], v[246:247] neg_lo:[0,1] neg_hi:[0,1]
	v_pk_mul_f32 v[250:251], v[4:5], v[238:239] op_sel:[1,1] op_sel_hi:[1,0]
	v_pk_fma_f32 v[4:5], v[4:5], v[238:239], v[250:251] op_sel:[0,0,0] op_sel_hi:[0,1,1] neg_lo:[0,0,1]
	ds_write_b64 v227, v[4:5] offset:256
	v_pk_add_f32 v[6:7], v[244:245], v[248:249] op_sel:[0,1] op_sel_hi:[1,0] neg_lo:[0,1]
	v_pk_mul_f32 v[250:251], v[6:7], v[240:241] op_sel:[1,1] op_sel_hi:[1,0]
	v_pk_fma_f32 v[6:7], v[6:7], v[240:241], v[250:251] op_sel:[0,0,0] op_sel_hi:[0,1,1] neg_lo:[0,0,1]
	ds_write_b64 v227, v[6:7] offset:384
	v_pk_add_f32 v[242:243], v[8:9], v[12:13]
	v_pk_add_f32 v[244:245], v[8:9], v[12:13] neg_lo:[0,1] neg_hi:[0,1]
	v_pk_add_f32 v[246:247], v[10:11], v[14:15]
	v_pk_add_f32 v[248:249], v[10:11], v[14:15] neg_lo:[0,1] neg_hi:[0,1]
	v_pk_add_f32 v[8:9], v[242:243], v[246:247]
	ds_write_b64 v227, v[8:9] offset:512
	v_pk_add_f32 v[10:11], v[244:245], v[248:249] op_sel:[0,1] op_sel_hi:[1,0] neg_hi:[0,1]
	v_pk_mul_f32 v[250:251], v[10:11], v[236:237] op_sel:[1,1] op_sel_hi:[1,0]
	v_pk_fma_f32 v[10:11], v[10:11], v[236:237], v[250:251] op_sel:[0,0,0] op_sel_hi:[0,1,1] neg_lo:[0,0,1]
	ds_write_b64 v227, v[10:11] offset:640
	v_pk_add_f32 v[12:13], v[242:243], v[246:247] neg_lo:[0,1] neg_hi:[0,1]
	v_pk_mul_f32 v[250:251], v[12:13], v[238:239] op_sel:[1,1] op_sel_hi:[1,0]
	v_pk_fma_f32 v[12:13], v[12:13], v[238:239], v[250:251] op_sel:[0,0,0] op_sel_hi:[0,1,1] neg_lo:[0,0,1]
	ds_write_b64 v227, v[12:13] offset:768
	v_pk_add_f32 v[14:15], v[244:245], v[248:249] op_sel:[0,1] op_sel_hi:[1,0] neg_lo:[0,1]
	v_pk_mul_f32 v[250:251], v[14:15], v[240:241] op_sel:[1,1] op_sel_hi:[1,0]
	v_pk_fma_f32 v[14:15], v[14:15], v[240:241], v[250:251] op_sel:[0,0,0] op_sel_hi:[0,1,1] neg_lo:[0,0,1]
	ds_write_b64 v227, v[14:15] offset:896
	v_pk_add_f32 v[242:243], v[16:17], v[20:21]
	v_pk_add_f32 v[244:245], v[16:17], v[20:21] neg_lo:[0,1] neg_hi:[0,1]
	v_pk_add_f32 v[246:247], v[18:19], v[22:23]
	v_pk_add_f32 v[248:249], v[18:19], v[22:23] neg_lo:[0,1] neg_hi:[0,1]
	v_pk_add_f32 v[16:17], v[242:243], v[246:247]
	ds_write_b64 v227, v[16:17] offset:1024
	v_pk_add_f32 v[18:19], v[244:245], v[248:249] op_sel:[0,1] op_sel_hi:[1,0] neg_hi:[0,1]
	v_pk_mul_f32 v[250:251], v[18:19], v[236:237] op_sel:[1,1] op_sel_hi:[1,0]
	v_pk_fma_f32 v[18:19], v[18:19], v[236:237], v[250:251] op_sel:[0,0,0] op_sel_hi:[0,1,1] neg_lo:[0,0,1]
	ds_write_b64 v227, v[18:19] offset:1152
	v_pk_add_f32 v[20:21], v[242:243], v[246:247] neg_lo:[0,1] neg_hi:[0,1]
	v_pk_mul_f32 v[250:251], v[20:21], v[238:239] op_sel:[1,1] op_sel_hi:[1,0]
	v_pk_fma_f32 v[20:21], v[20:21], v[238:239], v[250:251] op_sel:[0,0,0] op_sel_hi:[0,1,1] neg_lo:[0,0,1]
	ds_write_b64 v227, v[20:21] offset:1280
	v_pk_add_f32 v[22:23], v[244:245], v[248:249] op_sel:[0,1] op_sel_hi:[1,0] neg_lo:[0,1]
	v_pk_mul_f32 v[250:251], v[22:23], v[240:241] op_sel:[1,1] op_sel_hi:[1,0]
	v_pk_fma_f32 v[22:23], v[22:23], v[240:241], v[250:251] op_sel:[0,0,0] op_sel_hi:[0,1,1] neg_lo:[0,0,1]
	ds_write_b64 v227, v[22:23] offset:1408
	v_pk_add_f32 v[242:243], v[24:25], v[28:29]
	v_pk_add_f32 v[244:245], v[24:25], v[28:29] neg_lo:[0,1] neg_hi:[0,1]
	v_pk_add_f32 v[246:247], v[26:27], v[30:31]
	v_pk_add_f32 v[248:249], v[26:27], v[30:31] neg_lo:[0,1] neg_hi:[0,1]
	v_pk_add_f32 v[24:25], v[242:243], v[246:247]
	ds_write_b64 v227, v[24:25] offset:1536
	v_pk_add_f32 v[26:27], v[244:245], v[248:249] op_sel:[0,1] op_sel_hi:[1,0] neg_hi:[0,1]
	v_pk_mul_f32 v[250:251], v[26:27], v[236:237] op_sel:[1,1] op_sel_hi:[1,0]
	v_pk_fma_f32 v[26:27], v[26:27], v[236:237], v[250:251] op_sel:[0,0,0] op_sel_hi:[0,1,1] neg_lo:[0,0,1]
	ds_write_b64 v227, v[26:27] offset:1664
	v_pk_add_f32 v[28:29], v[242:243], v[246:247] neg_lo:[0,1] neg_hi:[0,1]
	v_pk_mul_f32 v[250:251], v[28:29], v[238:239] op_sel:[1,1] op_sel_hi:[1,0]
	v_pk_fma_f32 v[28:29], v[28:29], v[238:239], v[250:251] op_sel:[0,0,0] op_sel_hi:[0,1,1] neg_lo:[0,0,1]
	ds_write_b64 v227, v[28:29] offset:1792
	v_pk_add_f32 v[30:31], v[244:245], v[248:249] op_sel:[0,1] op_sel_hi:[1,0] neg_lo:[0,1]
	v_pk_mul_f32 v[250:251], v[30:31], v[240:241] op_sel:[1,1] op_sel_hi:[1,0]
	v_pk_fma_f32 v[30:31], v[30:31], v[240:241], v[250:251] op_sel:[0,0,0] op_sel_hi:[0,1,1] neg_lo:[0,0,1]
	ds_write_b64 v227, v[30:31] offset:1920
	s_waitcnt lgkmcnt(0)
	s_cmp_lg_u32 s89, 0
	s_cbranch_scc1 .Lmy_skip_lq2
; HD float2 cmul(float2 a, float2 b){ return make_float2(a.x*b.x - a.y*b.y, a.x*b.y + a.y*b.x); }
; HD float2 cmulc(float2 a, float2 b){ return make_float2(a.x*b.x + a.y*b.y, a.y*b.x - a.x*b.y); }
; template<bool INV, bool NOTW>
; HD void bf4c(float2* Z, int i0, int i1, int i2, int i3, float2 w1, float2 w2, float2 w3){
;   float2 a0=Z[i0], a1=Z[i1], a2=Z[i2], a3=Z[i3];
;   if (INV && !NOTW){ a1=cmulc(a1,w1); a2=cmulc(a2,w2); a3=cmulc(a3,w3); }
;   float2 s02=make_float2(a0.x+a2.x,a0.y+a2.y), d02=make_float2(a0.x-a2.x,a0.y-a2.y);
;   float2 s13=make_float2(a1.x+a3.x,a1.y+a3.y), d13=make_float2(a1.x-a3.x,a1.y-a3.y);
;   float2 y0=make_float2(s02.x+s13.x,s02.y+s13.y), y2=make_float2(s02.x-s13.x,s02.y-s13.y);
;   float2 ym=make_float2(d02.x+d13.y,d02.y-d13.x);
;   float2 yp=make_float2(d02.x-d13.y,d02.y+d13.x);
;   float2 y1, y3;
;   if (INV){ y1=yp; y3=ym; } else if (NOTW){ y1=ym; y3=yp; } else { y1=cmul(ym,w1); y2=cmul(y2,w2); y3=cmul(yp,w3); }
;   Z[i0]=y0; Z[i1]=y1; Z[i2]=y2; Z[i3]=y3;
; }
; template<bool INV, int LQ, bool BARRIER=true>
; HD void fft_pass(float2* Z, const float2* twA, const float2* twB, int tid){
;     ...
;     int j=tid&(q-1); int base0=((tid>>LQ)<<(LQ+2))+j;
;     float2 w1=make_float2(1.f,0.f), w2=w1, w3=w1;
;     if (LQ>0){ int k=j*tws; w1=cmul(twA[k>>6],twB[k&63]); w2=cmul(w1,w1); w3=cmul(w2,w1); }
;     _Pragma("unroll") for (int i=0;i<8;++i){ int base=base0+i*2048; bf4c<INV,(LQ==0)>(Z,base,base+q,base+2*q,base+3*q,w1,w2,w3); }
;   }
;   if (BARRIER) __syncthreads(); else asm volatile("s_waitcnt lgkmcnt(0)" ::: "memory");
	v_and_b32_e32 v226, 3, v154
	v_lshlrev_b32_e32 v224, 7, v226
	v_add_u32_e32 v224, 0x20800, v224
	v_mov_b32_e32 v225, 0x20a00
	ds_read_b64 v[238:239], v224
	ds_read_b64 v[240:241], v225
	s_waitcnt lgkmcnt(0)
	v_pk_mul_f32 v[30:31], v[238:239], v[240:241] op_sel:[1,1] op_sel_hi:[1,0]
	v_pk_fma_f32 v[16:17], v[238:239], v[240:241], v[30:31] op_sel:[0,0,0] op_sel_hi:[0,1,1] neg_lo:[0,0,1]
	v_pk_mul_f32 v[30:31], v[16:17], v[16:17] op_sel:[1,1] op_sel_hi:[1,0]
	v_pk_fma_f32 v[18:19], v[16:17], v[16:17], v[30:31] op_sel:[0,0,0] op_sel_hi:[0,1,1] neg_lo:[0,0,1]
	v_pk_mul_f32 v[30:31], v[18:19], v[16:17] op_sel:[1,1] op_sel_hi:[1,0]
	v_pk_fma_f32 v[20:21], v[18:19], v[16:17], v[30:31] op_sel:[0,0,0] op_sel_hi:[0,1,1] neg_lo:[0,0,1]
	v_lshrrev_b32_e32 v222, 2, v154
	v_lshlrev_b32_e32 v222, 4, v222
	v_add_u32_e32 v222, v222, v226
	v_lshlrev_b32_e32 v222, 3, v222
	v_add_u32_e32 v223, 0x10000, v222
	ds_read_b64 v[0:1], v222 offset:0
	ds_read_b64 v[2:3], v222 offset:32
	ds_read_b64 v[4:5], v222 offset:64
	ds_read_b64 v[6:7], v222 offset:96
	ds_read_b64 v[8:9], v222 offset:16384
	ds_read_b64 v[10:11], v222 offset:16416
	ds_read_b64 v[12:13], v222 offset:16448
	ds_read_b64 v[14:15], v222 offset:16480
	s_waitcnt lgkmcnt(4)
	v_pk_add_f32 v[22:23], v[0:1], v[4:5]
	v_pk_add_f32 v[24:25], v[0:1], v[4:5] neg_lo:[0,1] neg_hi:[0,1]
	v_pk_add_f32 v[26:27], v[2:3], v[6:7]
	v_pk_add_f32 v[28:29], v[2:3], v[6:7] neg_lo:[0,1] neg_hi:[0,1]
	v_pk_add_f32 v[80:81], v[22:23], v[26:27]
	ds_write_b64 v222, v[80:81] offset:0
	v_pk_add_f32 v[244:245], v[24:25], v[28:29] op_sel:[0,1] op_sel_hi:[1,0] neg_hi:[0,1]
	v_pk_mul_f32 v[30:31], v[244:245], v[16:17] op_sel:[1,1] op_sel_hi:[1,0]
	v_pk_fma_f32 v[82:83], v[244:245], v[16:17], v[30:31] op_sel:[0,0,0] op_sel_hi:[0,1,1] neg_lo:[0,0,1]
	ds_write_b64 v222, v[82:83] offset:32
	v_pk_add_f32 v[242:243], v[22:23], v[26:27] neg_lo:[0,1] neg_hi:[0,1]
	v_pk_mul_f32 v[30:31], v[242:243], v[18:19] op_sel:[1,1] op_sel_hi:[1,0]
	v_pk_fma_f32 v[84:85], v[242:243], v[18:19], v[30:31] op_sel:[0,0,0] op_sel_hi:[0,1,1] neg_lo:[0,0,1]
	ds_write_b64 v222, v[84:85] offset:64
	v_pk_add_f32 v[246:247], v[24:25], v[28:29] op_sel:[0,1] op_sel_hi:[1,0] neg_lo:[0,1]
	v_pk_mul_f32 v[30:31], v[246:247], v[20:21] op_sel:[1,1] op_sel_hi:[1,0]
	v_pk_fma_f32 v[236:237], v[246:247], v[20:21], v[30:31] op_sel:[0,0,0] op_sel_hi:[0,1,1] neg_lo:[0,0,1]
	ds_write_b64 v222, v[236:237] offset:96
	ds_read_b64 v[0:1], v222 offset:32768
	ds_read_b64 v[2:3], v222 offset:32800
	ds_read_b64 v[4:5], v222 offset:32832
	ds_read_b64 v[6:7], v222 offset:32864
	s_waitcnt lgkmcnt(8)
	v_pk_add_f32 v[22:23], v[8:9], v[12:13]
	v_pk_add_f32 v[24:25], v[8:9], v[12:13] neg_lo:[0,1] neg_hi:[0,1]
	v_pk_add_f32 v[26:27], v[10:11], v[14:15]
	v_pk_add_f32 v[28:29], v[10:11], v[14:15] neg_lo:[0,1] neg_hi:[0,1]
	v_pk_add_f32 v[80:81], v[22:23], v[26:27]
	ds_write_b64 v222, v[80:81] offset:16384
	v_pk_add_f32 v[244:245], v[24:25], v[28:29] op_sel:[0,1] op_sel_hi:[1,0] neg_hi:[0,1]
	v_pk_mul_f32 v[30:31], v[244:245], v[16:17] op_sel:[1,1] op_sel_hi:[1,0]
	v_pk_fma_f32 v[82:83], v[244:245], v[16:17], v[30:31] op_sel:[0,0,0] op_sel_hi:[0,1,1] neg_lo:[0,0,1]
	ds_write_b64 v222, v[82:83] offset:16416
	v_pk_add_f32 v[242:243], v[22:23], v[26:27] neg_lo:[0,1] neg_hi:[0,1]
	v_pk_mul_f32 v[30:31], v[242:243], v[18:19] op_sel:[1,1] op_sel_hi:[1,0]
	v_pk_fma_f32 v[84:85], v[242:243], v[18:19], v[30:31] op_sel:[0,0,0] op_sel_hi:[0,1,1] neg_lo:[0,0,1]
	ds_write_b64 v222, v[84:85] offset:16448
	v_pk_add_f32 v[246:247], v[24:25], v[28:29] op_sel:[0,1] op_sel_hi:[1,0] neg_lo:[0,1]
	v_pk_mul_f32 v[30:31], v[246:247], v[20:21] op_sel:[1,1] op_sel_hi:[1,0]
	v_pk_fma_f32 v[236:237], v[246:247], v[20:21], v[30:31] op_sel:[0,0,0] op_sel_hi:[0,1,1] neg_lo:[0,0,1]
	ds_write_b64 v222, v[236:237] offset:16480
	ds_read_b64 v[8:9], v222 offset:49152
	ds_read_b64 v[10:11], v222 offset:49184
	ds_read_b64 v[12:13], v222 offset:49216
	ds_read_b64 v[14:15], v222 offset:49248
	s_waitcnt lgkmcnt(8)
	v_pk_add_f32 v[22:23], v[0:1], v[4:5]
	v_pk_add_f32 v[24:25], v[0:1], v[4:5] neg_lo:[0,1] neg_hi:[0,1]
	v_pk_add_f32 v[26:27], v[2:3], v[6:7]
	v_pk_add_f32 v[28:29], v[2:3], v[6:7] neg_lo:[0,1] neg_hi:[0,1]
	v_pk_add_f32 v[80:81], v[22:23], v[26:27]
	ds_write_b64 v222, v[80:81] offset:32768
	v_pk_add_f32 v[244:245], v[24:25], v[28:29] op_sel:[0,1] op_sel_hi:[1,0] neg_hi:[0,1]
	v_pk_mul_f32 v[30:31], v[244:245], v[16:17] op_sel:[1,1] op_sel_hi:[1,0]
	v_pk_fma_f32 v[82:83], v[244:245], v[16:17], v[30:31] op_sel:[0,0,0] op_sel_hi:[0,1,1] neg_lo:[0,0,1]
	ds_write_b64 v222, v[82:83] offset:32800
	v_pk_add_f32 v[242:243], v[22:23], v[26:27] neg_lo:[0,1] neg_hi:[0,1]
	v_pk_mul_f32 v[30:31], v[242:243], v[18:19] op_sel:[1,1] op_sel_hi:[1,0]
	v_pk_fma_f32 v[84:85], v[242:243], v[18:19], v[30:31] op_sel:[0,0,0] op_sel_hi:[0,1,1] neg_lo:[0,0,1]
	ds_write_b64 v222, v[84:85] offset:32832
	v_pk_add_f32 v[246:247], v[24:25], v[28:29] op_sel:[0,1] op_sel_hi:[1,0] neg_lo:[0,1]
	v_pk_mul_f32 v[30:31], v[246:247], v[20:21] op_sel:[1,1] op_sel_hi:[1,0]
	v_pk_fma_f32 v[236:237], v[246:247], v[20:21], v[30:31] op_sel:[0,0,0] op_sel_hi:[0,1,1] neg_lo:[0,0,1]
	ds_write_b64 v222, v[236:237] offset:32864
	ds_read_b64 v[0:1], v223 offset:0
	ds_read_b64 v[2:3], v223 offset:32
	ds_read_b64 v[4:5], v223 offset:64
	ds_read_b64 v[6:7], v223 offset:96
	s_waitcnt lgkmcnt(8)
; HD float2 cmul(float2 a, float2 b){ return make_float2(a.x*b.x - a.y*b.y, a.x*b.y + a.y*b.x); }
; HD float2 cmulc(float2 a, float2 b){ return make_float2(a.x*b.x + a.y*b.y, a.y*b.x - a.x*b.y); }
; template<bool INV, bool NOTW>
; HD void bf4c(float2* Z, int i0, int i1, int i2, int i3, float2 w1, float2 w2, float2 w3){
;   float2 a0=Z[i0], a1=Z[i1], a2=Z[i2], a3=Z[i3];
;   if (INV && !NOTW){ a1=cmulc(a1,w1); a2=cmulc(a2,w2); a3=cmulc(a3,w3); }
;   float2 s02=make_float2(a0.x+a2.x,a0.y+a2.y), d02=make_float2(a0.x-a2.x,a0.y-a2.y);
;   float2 s13=make_float2(a1.x+a3.x,a1.y+a3.y), d13=make_float2(a1.x-a3.x,a1.y-a3.y);
;   float2 y0=make_float2(s02.x+s13.x,s02.y+s13.y), y2=make_float2(s02.x-s13.x,s02.y-s13.y);
;   float2 ym=make_float2(d02.x+d13.y,d02.y-d13.x);
;   float2 yp=make_float2(d02.x-d13.y,d02.y+d13.x);
;   float2 y1, y3;
;   if (INV){ y1=yp; y3=ym; } else if (NOTW){ y1=ym; y3=yp; } else { y1=cmul(ym,w1); y2=cmul(y2,w2); y3=cmul(yp,w3); }
;   Z[i0]=y0; Z[i1]=y1; Z[i2]=y2; Z[i3]=y3;
; }
; template<bool INV, int LQ, bool BARRIER=true>
; HD void fft_pass(float2* Z, const float2* twA, const float2* twB, int tid){
;     ...
;     int j=tid&(q-1); int base0=((tid>>LQ)<<(LQ+2))+j;
;     float2 w1=make_float2(1.f,0.f), w2=w1, w3=w1;
;     if (LQ>0){ int k=j*tws; w1=cmul(twA[k>>6],twB[k&63]); w2=cmul(w1,w1); w3=cmul(w2,w1); }
;     _Pragma("unroll") for (int i=0;i<8;++i){ int base=base0+i*2048; bf4c<INV,(LQ==0)>(Z,base,base+q,base+2*q,base+3*q,w1,w2,w3); }
;   }
;   if (BARRIER) __syncthreads(); else asm volatile("s_waitcnt lgkmcnt(0)" ::: "memory");
	v_pk_add_f32 v[22:23], v[8:9], v[12:13]
	v_pk_add_f32 v[24:25], v[8:9], v[12:13] neg_lo:[0,1] neg_hi:[0,1]
	v_pk_add_f32 v[26:27], v[10:11], v[14:15]
	v_pk_add_f32 v[28:29], v[10:11], v[14:15] neg_lo:[0,1] neg_hi:[0,1]
	v_pk_add_f32 v[80:81], v[22:23], v[26:27]
	ds_write_b64 v222, v[80:81] offset:49152
	v_pk_add_f32 v[244:245], v[24:25], v[28:29] op_sel:[0,1] op_sel_hi:[1,0] neg_hi:[0,1]
	v_pk_mul_f32 v[30:31], v[244:245], v[16:17] op_sel:[1,1] op_sel_hi:[1,0]
	v_pk_fma_f32 v[82:83], v[244:245], v[16:17], v[30:31] op_sel:[0,0,0] op_sel_hi:[0,1,1] neg_lo:[0,0,1]
	ds_write_b64 v222, v[82:83] offset:49184
	v_pk_add_f32 v[242:243], v[22:23], v[26:27] neg_lo:[0,1] neg_hi:[0,1]
	v_pk_mul_f32 v[30:31], v[242:243], v[18:19] op_sel:[1,1] op_sel_hi:[1,0]
	v_pk_fma_f32 v[84:85], v[242:243], v[18:19], v[30:31] op_sel:[0,0,0] op_sel_hi:[0,1,1] neg_lo:[0,0,1]
	ds_write_b64 v222, v[84:85] offset:49216
	v_pk_add_f32 v[246:247], v[24:25], v[28:29] op_sel:[0,1] op_sel_hi:[1,0] neg_lo:[0,1]
	v_pk_mul_f32 v[30:31], v[246:247], v[20:21] op_sel:[1,1] op_sel_hi:[1,0]
	v_pk_fma_f32 v[236:237], v[246:247], v[20:21], v[30:31] op_sel:[0,0,0] op_sel_hi:[0,1,1] neg_lo:[0,0,1]
	ds_write_b64 v222, v[236:237] offset:49248
	ds_read_b64 v[8:9], v223 offset:16384
	ds_read_b64 v[10:11], v223 offset:16416
	ds_read_b64 v[12:13], v223 offset:16448
	ds_read_b64 v[14:15], v223 offset:16480
	s_waitcnt lgkmcnt(8)
	v_pk_add_f32 v[22:23], v[0:1], v[4:5]
	v_pk_add_f32 v[24:25], v[0:1], v[4:5] neg_lo:[0,1] neg_hi:[0,1]
	v_pk_add_f32 v[26:27], v[2:3], v[6:7]
	v_pk_add_f32 v[28:29], v[2:3], v[6:7] neg_lo:[0,1] neg_hi:[0,1]
	v_pk_add_f32 v[80:81], v[22:23], v[26:27]
	ds_write_b64 v223, v[80:81] offset:0
	v_pk_add_f32 v[244:245], v[24:25], v[28:29] op_sel:[0,1] op_sel_hi:[1,0] neg_hi:[0,1]
	v_pk_mul_f32 v[30:31], v[244:245], v[16:17] op_sel:[1,1] op_sel_hi:[1,0]
	v_pk_fma_f32 v[82:83], v[244:245], v[16:17], v[30:31] op_sel:[0,0,0] op_sel_hi:[0,1,1] neg_lo:[0,0,1]
	ds_write_b64 v223, v[82:83] offset:32
	v_pk_add_f32 v[242:243], v[22:23], v[26:27] neg_lo:[0,1] neg_hi:[0,1]
	v_pk_mul_f32 v[30:31], v[242:243], v[18:19] op_sel:[1,1] op_sel_hi:[1,0]
	v_pk_fma_f32 v[84:85], v[242:243], v[18:19], v[30:31] op_sel:[0,0,0] op_sel_hi:[0,1,1] neg_lo:[0,0,1]
	ds_write_b64 v223, v[84:85] offset:64
	v_pk_add_f32 v[246:247], v[24:25], v[28:29] op_sel:[0,1] op_sel_hi:[1,0] neg_lo:[0,1]
	v_pk_mul_f32 v[30:31], v[246:247], v[20:21] op_sel:[1,1] op_sel_hi:[1,0]
	v_pk_fma_f32 v[236:237], v[246:247], v[20:21], v[30:31] op_sel:[0,0,0] op_sel_hi:[0,1,1] neg_lo:[0,0,1]
	ds_write_b64 v223, v[236:237] offset:96
	ds_read_b64 v[0:1], v223 offset:32768
	ds_read_b64 v[2:3], v223 offset:32800
	ds_read_b64 v[4:5], v223 offset:32832
	ds_read_b64 v[6:7], v223 offset:32864
	s_waitcnt lgkmcnt(8)
	v_pk_add_f32 v[22:23], v[8:9], v[12:13]
	v_pk_add_f32 v[24:25], v[8:9], v[12:13] neg_lo:[0,1] neg_hi:[0,1]
	v_pk_add_f32 v[26:27], v[10:11], v[14:15]
	v_pk_add_f32 v[28:29], v[10:11], v[14:15] neg_lo:[0,1] neg_hi:[0,1]
	v_pk_add_f32 v[80:81], v[22:23], v[26:27]
	ds_write_b64 v223, v[80:81] offset:16384
	v_pk_add_f32 v[244:245], v[24:25], v[28:29] op_sel:[0,1] op_sel_hi:[1,0] neg_hi:[0,1]
	v_pk_mul_f32 v[30:31], v[244:245], v[16:17] op_sel:[1,1] op_sel_hi:[1,0]
	v_pk_fma_f32 v[82:83], v[244:245], v[16:17], v[30:31] op_sel:[0,0,0] op_sel_hi:[0,1,1] neg_lo:[0,0,1]
	ds_write_b64 v223, v[82:83] offset:16416
	v_pk_add_f32 v[242:243], v[22:23], v[26:27] neg_lo:[0,1] neg_hi:[0,1]
	v_pk_mul_f32 v[30:31], v[242:243], v[18:19] op_sel:[1,1] op_sel_hi:[1,0]
	v_pk_fma_f32 v[84:85], v[242:243], v[18:19], v[30:31] op_sel:[0,0,0] op_sel_hi:[0,1,1] neg_lo:[0,0,1]
	ds_write_b64 v223, v[84:85] offset:16448
	v_pk_add_f32 v[246:247], v[24:25], v[28:29] op_sel:[0,1] op_sel_hi:[1,0] neg_lo:[0,1]
	v_pk_mul_f32 v[30:31], v[246:247], v[20:21] op_sel:[1,1] op_sel_hi:[1,0]
	v_pk_fma_f32 v[236:237], v[246:247], v[20:21], v[30:31] op_sel:[0,0,0] op_sel_hi:[0,1,1] neg_lo:[0,0,1]
	ds_write_b64 v223, v[236:237] offset:16480
	ds_read_b64 v[8:9], v223 offset:49152
	ds_read_b64 v[10:11], v223 offset:49184
	ds_read_b64 v[12:13], v223 offset:49216
	ds_read_b64 v[14:15], v223 offset:49248
	s_waitcnt lgkmcnt(8)
	v_pk_add_f32 v[22:23], v[0:1], v[4:5]
	v_pk_add_f32 v[24:25], v[0:1], v[4:5] neg_lo:[0,1] neg_hi:[0,1]
	v_pk_add_f32 v[26:27], v[2:3], v[6:7]
	v_pk_add_f32 v[28:29], v[2:3], v[6:7] neg_lo:[0,1] neg_hi:[0,1]
	v_pk_add_f32 v[80:81], v[22:23], v[26:27]
	ds_write_b64 v223, v[80:81] offset:32768
	v_pk_add_f32 v[244:245], v[24:25], v[28:29] op_sel:[0,1] op_sel_hi:[1,0] neg_hi:[0,1]
	v_pk_mul_f32 v[30:31], v[244:245], v[16:17] op_sel:[1,1] op_sel_hi:[1,0]
	v_pk_fma_f32 v[82:83], v[244:245], v[16:17], v[30:31] op_sel:[0,0,0] op_sel_hi:[0,1,1] neg_lo:[0,0,1]
	ds_write_b64 v223, v[82:83] offset:32800
	v_pk_add_f32 v[242:243], v[22:23], v[26:27] neg_lo:[0,1] neg_hi:[0,1]
	v_pk_mul_f32 v[30:31], v[242:243], v[18:19] op_sel:[1,1] op_sel_hi:[1,0]
	v_pk_fma_f32 v[84:85], v[242:243], v[18:19], v[30:31] op_sel:[0,0,0] op_sel_hi:[0,1,1] neg_lo:[0,0,1]
	ds_write_b64 v223, v[84:85] offset:32832
	v_pk_add_f32 v[246:247], v[24:25], v[28:29] op_sel:[0,1] op_sel_hi:[1,0] neg_lo:[0,1]
	v_pk_mul_f32 v[30:31], v[246:247], v[20:21] op_sel:[1,1] op_sel_hi:[1,0]
	v_pk_fma_f32 v[236:237], v[246:247], v[20:21], v[30:31] op_sel:[0,0,0] op_sel_hi:[0,1,1] neg_lo:[0,0,1]
	ds_write_b64 v223, v[236:237] offset:32864
	s_waitcnt lgkmcnt(4)
	v_pk_add_f32 v[22:23], v[8:9], v[12:13]
	v_pk_add_f32 v[24:25], v[8:9], v[12:13] neg_lo:[0,1] neg_hi:[0,1]
	v_pk_add_f32 v[26:27], v[10:11], v[14:15]
	v_pk_add_f32 v[28:29], v[10:11], v[14:15] neg_lo:[0,1] neg_hi:[0,1]
	v_pk_add_f32 v[80:81], v[22:23], v[26:27]
	ds_write_b64 v223, v[80:81] offset:49152
	v_pk_add_f32 v[244:245], v[24:25], v[28:29] op_sel:[0,1] op_sel_hi:[1,0] neg_hi:[0,1]
	v_pk_mul_f32 v[30:31], v[244:245], v[16:17] op_sel:[1,1] op_sel_hi:[1,0]
	v_pk_fma_f32 v[82:83], v[244:245], v[16:17], v[30:31] op_sel:[0,0,0] op_sel_hi:[0,1,1] neg_lo:[0,0,1]
	ds_write_b64 v223, v[82:83] offset:49184
	v_pk_add_f32 v[242:243], v[22:23], v[26:27] neg_lo:[0,1] neg_hi:[0,1]
	v_pk_mul_f32 v[30:31], v[242:243], v[18:19] op_sel:[1,1] op_sel_hi:[1,0]
	v_pk_fma_f32 v[84:85], v[242:243], v[18:19], v[30:31] op_sel:[0,0,0] op_sel_hi:[0,1,1] neg_lo:[0,0,1]
	ds_write_b64 v223, v[84:85] offset:49216
	v_pk_add_f32 v[246:247], v[24:25], v[28:29] op_sel:[0,1] op_sel_hi:[1,0] neg_lo:[0,1]
	v_pk_mul_f32 v[30:31], v[246:247], v[20:21] op_sel:[1,1] op_sel_hi:[1,0]
	v_pk_fma_f32 v[236:237], v[246:247], v[20:21], v[30:31] op_sel:[0,0,0] op_sel_hi:[0,1,1] neg_lo:[0,0,1]
	ds_write_b64 v223, v[236:237] offset:49248
	s_waitcnt lgkmcnt(0)
; HD float2 cmul(float2 a, float2 b){ return make_float2(a.x*b.x - a.y*b.y, a.x*b.y + a.y*b.x); }
; template<bool INV, bool NOTW>
; HD void bf4c(float2* Z, int i0, int i1, int i2, int i3, float2 w1, float2 w2, float2 w3){
;   float2 a0=Z[i0], a1=Z[i1], a2=Z[i2], a3=Z[i3];
;   if (INV && !NOTW){ a1=cmulc(a1,w1); a2=cmulc(a2,w2); a3=cmulc(a3,w3); }
;   float2 s02=make_float2(a0.x+a2.x,a0.y+a2.y), d02=make_float2(a0.x-a2.x,a0.y-a2.y);
;   float2 s13=make_float2(a1.x+a3.x,a1.y+a3.y), d13=make_float2(a1.x-a3.x,a1.y-a3.y);
;   float2 y0=make_float2(s02.x+s13.x,s02.y+s13.y), y2=make_float2(s02.x-s13.x,s02.y-s13.y);
;   float2 ym=make_float2(d02.x+d13.y,d02.y-d13.x);
;   float2 yp=make_float2(d02.x-d13.y,d02.y+d13.x);
;   float2 y1, y3;
;   if (INV){ y1=yp; y3=ym; } else if (NOTW){ y1=ym; y3=yp; } else { y1=cmul(ym,w1); y2=cmul(y2,w2); y3=cmul(yp,w3); }
;   Z[i0]=y0; Z[i1]=y1; Z[i2]=y2; Z[i3]=y3;
; __device__ __forceinline__ void fft_mid(float2* Z, const f16x2* Hp, int tid){
;   _Pragma("unroll 4") for (int i=0;i<8;++i){ int base=(tid<<2)+i*2048;
;     u32x4 hw=*(const u32x4*)(Hp+base);
;     unsigned hw0=hw[0], hw1=hw[1], hw2=hw[2], hw3=hw[3];
;     float2 a0=Z[base], a1=Z[base+1], a2=Z[base+2], a3=Z[base+3];
;     float2 s02=make_float2(a0.x+a2.x,a0.y+a2.y), d02=make_float2(a0.x-a2.x,a0.y-a2.y);
;     float2 s13=make_float2(a1.x+a3.x,a1.y+a3.y), d13=make_float2(a1.x-a3.x,a1.y-a3.y);
;     float2 y0=make_float2(s02.x+s13.x,s02.y+s13.y), y2=make_float2(s02.x-s13.x,s02.y-s13.y);
;     float2 y1=make_float2(d02.x+d13.y,d02.y-d13.x);
;     float2 y3=make_float2(d02.x-d13.y,d02.y+d13.x);
;     f16x2 h0=__builtin_bit_cast(f16x2,hw0), h1=__builtin_bit_cast(f16x2,hw1), h2=__builtin_bit_cast(f16x2,hw2), h3=__builtin_bit_cast(f16x2,hw3);
;     float2 b0=cmul(y0,make_float2((float)h0[0],(float)h0[1])), b1=cmul(y1,make_float2((float)h1[0],(float)h1[1]));
;     float2 b2=cmul(y2,make_float2((float)h2[0],(float)h2[1])), b3=cmul(y3,make_float2((float)h3[0],(float)h3[1]));
;     float2 t02=make_float2(b0.x+b2.x,b0.y+b2.y), e02=make_float2(b0.x-b2.x,b0.y-b2.y);
;     float2 t13=make_float2(b1.x+b3.x,b1.y+b3.y), e13=make_float2(b1.x-b3.x,b1.y-b3.y);
;     Z[base]=make_float2(t02.x+t13.x,t02.y+t13.y); Z[base+2]=make_float2(t02.x-t13.x,t02.y-t13.y);
;     Z[base+1]=make_float2(e02.x-e13.y,e02.y+e13.x);
;     Z[base+3]=make_float2(e02.x+e13.y,e02.y-e13.x);
;   }
.Lmy_skip_lq2:
	v_add_u32_e32 v14, 0x4000, v169
	v_add_u32_e32 v15, 0x8000, v169
	v_add_u32_e32 v16, 0xc000, v169
	v_add_u32_e32 v17, 0x4000, v186
	v_add_u32_e32 v18, 0x8000, v186
	v_add_u32_e32 v19, 0xc000, v186
	s_mov_b64 s[12:13], -1
	s_and_b64 vcc, exec, s[68:69]
	s_cbranch_vccz .LBB0_1344
	s_cmp_lg_u32 s89, 1
	s_cselect_b64 s[50:51], -1, 0
	s_cmp_eq_u32 s89, 1
	s_cselect_b32 s69, s77, s79
	s_cselect_b32 s68, s76, s78
	v_mov_b32_e32 v68, 0x3f6c835e
	v_mov_b32_e32 v69, 0x3ec3ef15
	v_mov_b32_e32 v70, 0x3f3504f3
	v_mov_b32_e32 v71, 0x3f3504f3
	v_lshrrev_b32_e32 v225, 6, v154
	v_bfe_u32 v226, v154, 4, 2
	v_lshlrev_b32_e32 v225, 8, v225
	v_lshl_add_u32 v225, v226, 11, v225
	v_and_b32_e32 v226, 15, v154
	v_lshl_add_u32 v225, v226, 4, v225
	v_lshlrev_b32_e32 v222, 3, v225
	v_add_u32_e32 v223, 0x10000, v222
	v_lshlrev_b32_e32 v224, 2, v225
	global_load_dwordx4 v[236:239], v224, s[68:69] offset:0
	global_load_dwordx4 v[240:243], v224, s[68:69] offset:16
	global_load_dwordx4 v[244:247], v224, s[68:69] offset:32
	global_load_dwordx4 v[248:251], v224, s[68:69] offset:48
	v_add_u32_e32 v224, 0x8000, v224
	ds_read_b128 v[0:3], v222 offset:0
	ds_read_b128 v[4:7], v222 offset:16
	ds_read_b128 v[8:11], v222 offset:32
	ds_read_b128 v[12:15], v222 offset:48
	ds_read_b128 v[16:19], v222 offset:64
	ds_read_b128 v[20:23], v222 offset:80
	ds_read_b128 v[24:27], v222 offset:96
	ds_read_b128 v[28:31], v222 offset:112
	s_waitcnt lgkmcnt(0)
	v_pk_add_f32 v[58:59], v[0:1], v[16:17]
	v_pk_add_f32 v[60:61], v[0:1], v[16:17] neg_lo:[0,1] neg_hi:[0,1]
	v_pk_add_f32 v[62:63], v[8:9], v[24:25]
	v_pk_add_f32 v[64:65], v[8:9], v[24:25] neg_lo:[0,1] neg_hi:[0,1]
	v_pk_add_f32 v[0:1], v[58:59], v[62:63]
	v_pk_add_f32 v[16:17], v[58:59], v[62:63] neg_lo:[0,1] neg_hi:[0,1]
	v_pk_add_f32 v[8:9], v[60:61], v[64:65] op_sel:[0,1] op_sel_hi:[1,0] neg_hi:[0,1]
	v_pk_add_f32 v[24:25], v[60:61], v[64:65] op_sel:[0,1] op_sel_hi:[1,0] neg_lo:[0,1]
	v_pk_add_f32 v[58:59], v[2:3], v[18:19]
	v_pk_add_f32 v[60:61], v[2:3], v[18:19] neg_lo:[0,1] neg_hi:[0,1]
	v_pk_add_f32 v[62:63], v[10:11], v[26:27]
	v_pk_add_f32 v[64:65], v[10:11], v[26:27] neg_lo:[0,1] neg_hi:[0,1]
	v_pk_add_f32 v[2:3], v[58:59], v[62:63]
	v_pk_add_f32 v[18:19], v[58:59], v[62:63] neg_lo:[0,1] neg_hi:[0,1]
	v_pk_add_f32 v[10:11], v[60:61], v[64:65] op_sel:[0,1] op_sel_hi:[1,0] neg_hi:[0,1]
	v_pk_add_f32 v[26:27], v[60:61], v[64:65] op_sel:[0,1] op_sel_hi:[1,0] neg_lo:[0,1]
	v_pk_mul_f32 v[66:67], v[10:11], v[68:69] op_sel:[1,1] op_sel_hi:[1,0] neg_lo:[0,1] neg_hi:[0,0]
	v_pk_fma_f32 v[10:11], v[10:11], v[68:69], v[66:67] op_sel:[0,0,0] op_sel_hi:[0,1,1] neg_lo:[0,0,1] neg_hi:[0,1,0]
	v_pk_mul_f32 v[66:67], v[18:19], v[70:71] op_sel:[1,1] op_sel_hi:[1,0] neg_lo:[0,1] neg_hi:[0,0]
	v_pk_fma_f32 v[18:19], v[18:19], v[70:71], v[66:67] op_sel:[0,0,0] op_sel_hi:[0,1,1] neg_lo:[0,0,1] neg_hi:[0,1,0]
	v_pk_mul_f32 v[66:67], v[26:27], v[68:69] op_sel:[1,0] op_sel_hi:[1,1] neg_lo:[0,1] neg_hi:[0,0]
	v_pk_fma_f32 v[26:27], v[26:27], v[68:69], v[66:67] op_sel:[0,1,0] op_sel_hi:[0,0,1] neg_lo:[0,0,1] neg_hi:[0,1,0]
	v_pk_add_f32 v[58:59], v[4:5], v[20:21]
	v_pk_add_f32 v[60:61], v[4:5], v[20:21] neg_lo:[0,1] neg_hi:[0,1]
	v_pk_add_f32 v[62:63], v[12:13], v[28:29]
	v_pk_add_f32 v[64:65], v[12:13], v[28:29] neg_lo:[0,1] neg_hi:[0,1]
	v_pk_add_f32 v[4:5], v[58:59], v[62:63]
	v_pk_add_f32 v[20:21], v[58:59], v[62:63] neg_lo:[0,1] neg_hi:[0,1]
	v_pk_add_f32 v[12:13], v[60:61], v[64:65] op_sel:[0,1] op_sel_hi:[1,0] neg_hi:[0,1]
	v_pk_add_f32 v[28:29], v[60:61], v[64:65] op_sel:[0,1] op_sel_hi:[1,0] neg_lo:[0,1]
	v_pk_mul_f32 v[66:67], v[12:13], v[70:71] op_sel:[1,1] op_sel_hi:[1,0] neg_lo:[0,1] neg_hi:[0,0]
	v_pk_fma_f32 v[12:13], v[12:13], v[70:71], v[66:67] op_sel:[0,0,0] op_sel_hi:[0,1,1] neg_lo:[0,0,1] neg_hi:[0,1,0]
	v_pk_add_f32 v[20:21], v[20:21], 0 op_sel:[1,0] op_sel_hi:[0,0] neg_hi:[1,0]
	v_pk_mul_f32 v[66:67], v[28:29], v[70:71] op_sel:[1,1] op_sel_hi:[1,0] neg_lo:[0,1] neg_hi:[0,1]
	v_pk_fma_f32 v[28:29], v[28:29], v[70:71], v[66:67] op_sel:[0,0,0] op_sel_hi:[0,1,1] neg_lo:[0,1,1] neg_hi:[0,1,0]
	v_pk_add_f32 v[58:59], v[6:7], v[22:23]
	v_pk_add_f32 v[60:61], v[6:7], v[22:23] neg_lo:[0,1] neg_hi:[0,1]
	v_pk_add_f32 v[62:63], v[14:15], v[30:31]
	v_pk_add_f32 v[64:65], v[14:15], v[30:31] neg_lo:[0,1] neg_hi:[0,1]
	v_pk_add_f32 v[6:7], v[58:59], v[62:63]
	v_pk_add_f32 v[22:23], v[58:59], v[62:63] neg_lo:[0,1] neg_hi:[0,1]
	v_pk_add_f32 v[14:15], v[60:61], v[64:65] op_sel:[0,1] op_sel_hi:[1,0] neg_hi:[0,1]
	v_pk_add_f32 v[30:31], v[60:61], v[64:65] op_sel:[0,1] op_sel_hi:[1,0] neg_lo:[0,1]
	v_pk_mul_f32 v[66:67], v[14:15], v[68:69] op_sel:[1,0] op_sel_hi:[1,1] neg_lo:[0,1] neg_hi:[0,0]
	v_pk_fma_f32 v[14:15], v[14:15], v[68:69], v[66:67] op_sel:[0,1,0] op_sel_hi:[0,0,1] neg_lo:[0,0,1] neg_hi:[0,1,0]
	v_pk_mul_f32 v[66:67], v[22:23], v[70:71] op_sel:[1,1] op_sel_hi:[1,0] neg_lo:[0,1] neg_hi:[0,1]
	v_pk_fma_f32 v[22:23], v[22:23], v[70:71], v[66:67] op_sel:[0,0,0] op_sel_hi:[0,1,1] neg_lo:[0,1,1] neg_hi:[0,1,0]
	v_pk_mul_f32 v[66:67], v[30:31], v[68:69] op_sel:[1,1] op_sel_hi:[1,0] neg_lo:[0,0] neg_hi:[0,1]
	v_pk_fma_f32 v[30:31], v[30:31], v[68:69], v[66:67] op_sel:[0,0,0] op_sel_hi:[0,1,1] neg_lo:[0,1,1] neg_hi:[0,0,0]
	v_pk_add_f32 v[58:59], v[0:1], v[4:5]
	v_pk_add_f32 v[60:61], v[0:1], v[4:5] neg_lo:[0,1] neg_hi:[0,1]
	v_pk_add_f32 v[62:63], v[2:3], v[6:7]
	v_pk_add_f32 v[64:65], v[2:3], v[6:7] neg_lo:[0,1] neg_hi:[0,1]
	v_pk_add_f32 v[0:1], v[58:59], v[62:63]
	v_pk_add_f32 v[4:5], v[58:59], v[62:63] neg_lo:[0,1] neg_hi:[0,1]
	v_pk_add_f32 v[2:3], v[60:61], v[64:65] op_sel:[0,1] op_sel_hi:[1,0] neg_hi:[0,1]
; HD float2 cmul(float2 a, float2 b){ return make_float2(a.x*b.x - a.y*b.y, a.x*b.y + a.y*b.x); }
; __device__ __forceinline__ void fft_mid(float2* Z, const f16x2* Hp, int tid){
;     ...
;     float2 s02=make_float2(a0.x+a2.x,a0.y+a2.y), d02=make_float2(a0.x-a2.x,a0.y-a2.y);
;     float2 s13=make_float2(a1.x+a3.x,a1.y+a3.y), d13=make_float2(a1.x-a3.x,a1.y-a3.y);
;     float2 y0=make_float2(s02.x+s13.x,s02.y+s13.y), y2=make_float2(s02.x-s13.x,s02.y-s13.y);
;     float2 y1=make_float2(d02.x+d13.y,d02.y-d13.x);
;     float2 y3=make_float2(d02.x-d13.y,d02.y+d13.x);
;     f16x2 h0=__builtin_bit_cast(f16x2,hw0), h1=__builtin_bit_cast(f16x2,hw1), h2=__builtin_bit_cast(f16x2,hw2), h3=__builtin_bit_cast(f16x2,hw3);
;     float2 b0=cmul(y0,make_float2((float)h0[0],(float)h0[1])), b1=cmul(y1,make_float2((float)h1[0],(float)h1[1]));
;     float2 b2=cmul(y2,make_float2((float)h2[0],(float)h2[1])), b3=cmul(y3,make_float2((float)h3[0],(float)h3[1]));
	v_pk_add_f32 v[6:7], v[60:61], v[64:65] op_sel:[0,1] op_sel_hi:[1,0] neg_lo:[0,1]
	v_pk_add_f32 v[58:59], v[8:9], v[12:13]
	v_pk_add_f32 v[60:61], v[8:9], v[12:13] neg_lo:[0,1] neg_hi:[0,1]
	v_pk_add_f32 v[62:63], v[10:11], v[14:15]
	v_pk_add_f32 v[64:65], v[10:11], v[14:15] neg_lo:[0,1] neg_hi:[0,1]
	v_pk_add_f32 v[8:9], v[58:59], v[62:63]
	v_pk_add_f32 v[12:13], v[58:59], v[62:63] neg_lo:[0,1] neg_hi:[0,1]
	v_pk_add_f32 v[10:11], v[60:61], v[64:65] op_sel:[0,1] op_sel_hi:[1,0] neg_hi:[0,1]
	v_pk_add_f32 v[14:15], v[60:61], v[64:65] op_sel:[0,1] op_sel_hi:[1,0] neg_lo:[0,1]
	v_pk_add_f32 v[58:59], v[16:17], v[20:21]
	v_pk_add_f32 v[60:61], v[16:17], v[20:21] neg_lo:[0,1] neg_hi:[0,1]
	v_pk_add_f32 v[62:63], v[18:19], v[22:23]
	v_pk_add_f32 v[64:65], v[18:19], v[22:23] neg_lo:[0,1] neg_hi:[0,1]
	v_pk_add_f32 v[16:17], v[58:59], v[62:63]
	v_pk_add_f32 v[20:21], v[58:59], v[62:63] neg_lo:[0,1] neg_hi:[0,1]
	v_pk_add_f32 v[18:19], v[60:61], v[64:65] op_sel:[0,1] op_sel_hi:[1,0] neg_hi:[0,1]
	v_pk_add_f32 v[22:23], v[60:61], v[64:65] op_sel:[0,1] op_sel_hi:[1,0] neg_lo:[0,1]
	v_pk_add_f32 v[58:59], v[24:25], v[28:29]
	v_pk_add_f32 v[60:61], v[24:25], v[28:29] neg_lo:[0,1] neg_hi:[0,1]
	v_pk_add_f32 v[62:63], v[26:27], v[30:31]
	v_pk_add_f32 v[64:65], v[26:27], v[30:31] neg_lo:[0,1] neg_hi:[0,1]
	v_pk_add_f32 v[24:25], v[58:59], v[62:63]
	v_pk_add_f32 v[28:29], v[58:59], v[62:63] neg_lo:[0,1] neg_hi:[0,1]
	v_pk_add_f32 v[26:27], v[60:61], v[64:65] op_sel:[0,1] op_sel_hi:[1,0] neg_hi:[0,1]
	v_pk_add_f32 v[30:31], v[60:61], v[64:65] op_sel:[0,1] op_sel_hi:[1,0] neg_lo:[0,1]
	s_waitcnt vmcnt(0)
	v_cvt_f32_f16_e32 v72, v236
	v_cvt_f32_f16_sdwa v73, v236 dst_sel:DWORD dst_unused:UNUSED_PAD src0_sel:WORD_1
	s_nop 0
	v_pk_mul_f32 v[66:67], v[0:1], v[72:73] op_sel:[1,1] op_sel_hi:[1,0]
	v_pk_fma_f32 v[0:1], v[0:1], v[72:73], v[66:67] op_sel:[0,0,0] op_sel_hi:[0,1,1] neg_lo:[0,0,1]
	v_cvt_f32_f16_e32 v72, v237
	v_cvt_f32_f16_sdwa v73, v237 dst_sel:DWORD dst_unused:UNUSED_PAD src0_sel:WORD_1
	s_nop 0
	v_pk_mul_f32 v[66:67], v[2:3], v[72:73] op_sel:[1,1] op_sel_hi:[1,0]
	v_pk_fma_f32 v[2:3], v[2:3], v[72:73], v[66:67] op_sel:[0,0,0] op_sel_hi:[0,1,1] neg_lo:[0,0,1]
	v_cvt_f32_f16_e32 v72, v238
	v_cvt_f32_f16_sdwa v73, v238 dst_sel:DWORD dst_unused:UNUSED_PAD src0_sel:WORD_1
	s_nop 0
	v_pk_mul_f32 v[66:67], v[4:5], v[72:73] op_sel:[1,1] op_sel_hi:[1,0]
	v_pk_fma_f32 v[4:5], v[4:5], v[72:73], v[66:67] op_sel:[0,0,0] op_sel_hi:[0,1,1] neg_lo:[0,0,1]
	v_cvt_f32_f16_e32 v72, v239
	v_cvt_f32_f16_sdwa v73, v239 dst_sel:DWORD dst_unused:UNUSED_PAD src0_sel:WORD_1
	s_nop 0
	v_pk_mul_f32 v[66:67], v[6:7], v[72:73] op_sel:[1,1] op_sel_hi:[1,0]
	v_pk_fma_f32 v[6:7], v[6:7], v[72:73], v[66:67] op_sel:[0,0,0] op_sel_hi:[0,1,1] neg_lo:[0,0,1]
	v_cvt_f32_f16_e32 v72, v240
	v_cvt_f32_f16_sdwa v73, v240 dst_sel:DWORD dst_unused:UNUSED_PAD src0_sel:WORD_1
	s_nop 0
	v_pk_mul_f32 v[66:67], v[8:9], v[72:73] op_sel:[1,1] op_sel_hi:[1,0]
	v_pk_fma_f32 v[8:9], v[8:9], v[72:73], v[66:67] op_sel:[0,0,0] op_sel_hi:[0,1,1] neg_lo:[0,0,1]
	v_cvt_f32_f16_e32 v72, v241
	v_cvt_f32_f16_sdwa v73, v241 dst_sel:DWORD dst_unused:UNUSED_PAD src0_sel:WORD_1
	s_nop 0
	v_pk_mul_f32 v[66:67], v[10:11], v[72:73] op_sel:[1,1] op_sel_hi:[1,0]
	v_pk_fma_f32 v[10:11], v[10:11], v[72:73], v[66:67] op_sel:[0,0,0] op_sel_hi:[0,1,1] neg_lo:[0,0,1]
	v_cvt_f32_f16_e32 v72, v242
	v_cvt_f32_f16_sdwa v73, v242 dst_sel:DWORD dst_unused:UNUSED_PAD src0_sel:WORD_1
	s_nop 0
	v_pk_mul_f32 v[66:67], v[12:13], v[72:73] op_sel:[1,1] op_sel_hi:[1,0]
	v_pk_fma_f32 v[12:13], v[12:13], v[72:73], v[66:67] op_sel:[0,0,0] op_sel_hi:[0,1,1] neg_lo:[0,0,1]
	v_cvt_f32_f16_e32 v72, v243
	v_cvt_f32_f16_sdwa v73, v243 dst_sel:DWORD dst_unused:UNUSED_PAD src0_sel:WORD_1
	s_nop 0
	v_pk_mul_f32 v[66:67], v[14:15], v[72:73] op_sel:[1,1] op_sel_hi:[1,0]
	v_pk_fma_f32 v[14:15], v[14:15], v[72:73], v[66:67] op_sel:[0,0,0] op_sel_hi:[0,1,1] neg_lo:[0,0,1]
	v_cvt_f32_f16_e32 v72, v244
	v_cvt_f32_f16_sdwa v73, v244 dst_sel:DWORD dst_unused:UNUSED_PAD src0_sel:WORD_1
	s_nop 0
	v_pk_mul_f32 v[66:67], v[16:17], v[72:73] op_sel:[1,1] op_sel_hi:[1,0]
	v_pk_fma_f32 v[16:17], v[16:17], v[72:73], v[66:67] op_sel:[0,0,0] op_sel_hi:[0,1,1] neg_lo:[0,0,1]
	v_cvt_f32_f16_e32 v72, v245
	v_cvt_f32_f16_sdwa v73, v245 dst_sel:DWORD dst_unused:UNUSED_PAD src0_sel:WORD_1
	s_nop 0
	v_pk_mul_f32 v[66:67], v[18:19], v[72:73] op_sel:[1,1] op_sel_hi:[1,0]
	v_pk_fma_f32 v[18:19], v[18:19], v[72:73], v[66:67] op_sel:[0,0,0] op_sel_hi:[0,1,1] neg_lo:[0,0,1]
	v_cvt_f32_f16_e32 v72, v246
	v_cvt_f32_f16_sdwa v73, v246 dst_sel:DWORD dst_unused:UNUSED_PAD src0_sel:WORD_1
	s_nop 0
	v_pk_mul_f32 v[66:67], v[20:21], v[72:73] op_sel:[1,1] op_sel_hi:[1,0]
	v_pk_fma_f32 v[20:21], v[20:21], v[72:73], v[66:67] op_sel:[0,0,0] op_sel_hi:[0,1,1] neg_lo:[0,0,1]
	v_cvt_f32_f16_e32 v72, v247
	v_cvt_f32_f16_sdwa v73, v247 dst_sel:DWORD dst_unused:UNUSED_PAD src0_sel:WORD_1
	s_nop 0
	v_pk_mul_f32 v[66:67], v[22:23], v[72:73] op_sel:[1,1] op_sel_hi:[1,0]
	v_pk_fma_f32 v[22:23], v[22:23], v[72:73], v[66:67] op_sel:[0,0,0] op_sel_hi:[0,1,1] neg_lo:[0,0,1]
	v_cvt_f32_f16_e32 v72, v248
	v_cvt_f32_f16_sdwa v73, v248 dst_sel:DWORD dst_unused:UNUSED_PAD src0_sel:WORD_1
	s_nop 0
	v_pk_mul_f32 v[66:67], v[24:25], v[72:73] op_sel:[1,1] op_sel_hi:[1,0]
	v_pk_fma_f32 v[24:25], v[24:25], v[72:73], v[66:67] op_sel:[0,0,0] op_sel_hi:[0,1,1] neg_lo:[0,0,1]
	v_cvt_f32_f16_e32 v72, v249
	v_cvt_f32_f16_sdwa v73, v249 dst_sel:DWORD dst_unused:UNUSED_PAD src0_sel:WORD_1
	s_nop 0
	v_pk_mul_f32 v[66:67], v[26:27], v[72:73] op_sel:[1,1] op_sel_hi:[1,0]
	v_pk_fma_f32 v[26:27], v[26:27], v[72:73], v[66:67] op_sel:[0,0,0] op_sel_hi:[0,1,1] neg_lo:[0,0,1]
; HD float2 cmul(float2 a, float2 b){ return make_float2(a.x*b.x - a.y*b.y, a.x*b.y + a.y*b.x); }
; HD float2 cmulc(float2 a, float2 b){ return make_float2(a.x*b.x + a.y*b.y, a.y*b.x - a.x*b.y); }
; template<bool INV, bool NOTW>
; HD void bf4c(float2* Z, int i0, int i1, int i2, int i3, float2 w1, float2 w2, float2 w3){
;   float2 a0=Z[i0], a1=Z[i1], a2=Z[i2], a3=Z[i3];
;   if (INV && !NOTW){ a1=cmulc(a1,w1); a2=cmulc(a2,w2); a3=cmulc(a3,w3); }
;   float2 s02=make_float2(a0.x+a2.x,a0.y+a2.y), d02=make_float2(a0.x-a2.x,a0.y-a2.y);
;   float2 s13=make_float2(a1.x+a3.x,a1.y+a3.y), d13=make_float2(a1.x-a3.x,a1.y-a3.y);
;   float2 y0=make_float2(s02.x+s13.x,s02.y+s13.y), y2=make_float2(s02.x-s13.x,s02.y-s13.y);
;   float2 ym=make_float2(d02.x+d13.y,d02.y-d13.x);
;   float2 yp=make_float2(d02.x-d13.y,d02.y+d13.x);
;   float2 y1, y3;
;   if (INV){ y1=yp; y3=ym; } else if (NOTW){ y1=ym; y3=yp; } else { y1=cmul(ym,w1); y2=cmul(y2,w2); y3=cmul(yp,w3); }
;   Z[i0]=y0; Z[i1]=y1; Z[i2]=y2; Z[i3]=y3;
; __device__ __forceinline__ void fft_mid(float2* Z, const f16x2* Hp, int tid){
;     ...
;     float2 t02=make_float2(b0.x+b2.x,b0.y+b2.y), e02=make_float2(b0.x-b2.x,b0.y-b2.y);
;     float2 t13=make_float2(b1.x+b3.x,b1.y+b3.y), e13=make_float2(b1.x-b3.x,b1.y-b3.y);
;     Z[base]=make_float2(t02.x+t13.x,t02.y+t13.y); Z[base+2]=make_float2(t02.x-t13.x,t02.y-t13.y);
;     Z[base+1]=make_float2(e02.x-e13.y,e02.y+e13.x);
;     Z[base+3]=make_float2(e02.x+e13.y,e02.y-e13.x);
	v_cvt_f32_f16_e32 v72, v250
	v_cvt_f32_f16_sdwa v73, v250 dst_sel:DWORD dst_unused:UNUSED_PAD src0_sel:WORD_1
	s_nop 0
	v_pk_mul_f32 v[66:67], v[28:29], v[72:73] op_sel:[1,1] op_sel_hi:[1,0]
	v_pk_fma_f32 v[28:29], v[28:29], v[72:73], v[66:67] op_sel:[0,0,0] op_sel_hi:[0,1,1] neg_lo:[0,0,1]
	v_cvt_f32_f16_e32 v72, v251
	v_cvt_f32_f16_sdwa v73, v251 dst_sel:DWORD dst_unused:UNUSED_PAD src0_sel:WORD_1
	s_nop 0
	v_pk_mul_f32 v[66:67], v[30:31], v[72:73] op_sel:[1,1] op_sel_hi:[1,0]
	v_pk_fma_f32 v[30:31], v[30:31], v[72:73], v[66:67] op_sel:[0,0,0] op_sel_hi:[0,1,1] neg_lo:[0,0,1]
	v_pk_add_f32 v[58:59], v[0:1], v[4:5]
	v_pk_add_f32 v[60:61], v[0:1], v[4:5] neg_lo:[0,1] neg_hi:[0,1]
	v_pk_add_f32 v[62:63], v[2:3], v[6:7]
	v_pk_add_f32 v[64:65], v[2:3], v[6:7] neg_lo:[0,1] neg_hi:[0,1]
	v_pk_add_f32 v[0:1], v[58:59], v[62:63]
	v_pk_add_f32 v[4:5], v[58:59], v[62:63] neg_lo:[0,1] neg_hi:[0,1]
	v_pk_add_f32 v[2:3], v[60:61], v[64:65] op_sel:[0,1] op_sel_hi:[1,0] neg_lo:[0,1]
	v_pk_add_f32 v[6:7], v[60:61], v[64:65] op_sel:[0,1] op_sel_hi:[1,0] neg_hi:[0,1]
	v_pk_add_f32 v[58:59], v[8:9], v[12:13]
	v_pk_add_f32 v[60:61], v[8:9], v[12:13] neg_lo:[0,1] neg_hi:[0,1]
	v_pk_add_f32 v[62:63], v[10:11], v[14:15]
	v_pk_add_f32 v[64:65], v[10:11], v[14:15] neg_lo:[0,1] neg_hi:[0,1]
	v_pk_add_f32 v[8:9], v[58:59], v[62:63]
	v_pk_add_f32 v[12:13], v[58:59], v[62:63] neg_lo:[0,1] neg_hi:[0,1]
	v_pk_add_f32 v[10:11], v[60:61], v[64:65] op_sel:[0,1] op_sel_hi:[1,0] neg_lo:[0,1]
	v_pk_add_f32 v[14:15], v[60:61], v[64:65] op_sel:[0,1] op_sel_hi:[1,0] neg_hi:[0,1]
	v_pk_add_f32 v[58:59], v[16:17], v[20:21]
	v_pk_add_f32 v[60:61], v[16:17], v[20:21] neg_lo:[0,1] neg_hi:[0,1]
	v_pk_add_f32 v[62:63], v[18:19], v[22:23]
	v_pk_add_f32 v[64:65], v[18:19], v[22:23] neg_lo:[0,1] neg_hi:[0,1]
	v_pk_add_f32 v[16:17], v[58:59], v[62:63]
	v_pk_add_f32 v[20:21], v[58:59], v[62:63] neg_lo:[0,1] neg_hi:[0,1]
	v_pk_add_f32 v[18:19], v[60:61], v[64:65] op_sel:[0,1] op_sel_hi:[1,0] neg_lo:[0,1]
	v_pk_add_f32 v[22:23], v[60:61], v[64:65] op_sel:[0,1] op_sel_hi:[1,0] neg_hi:[0,1]
	v_pk_add_f32 v[58:59], v[24:25], v[28:29]
	v_pk_add_f32 v[60:61], v[24:25], v[28:29] neg_lo:[0,1] neg_hi:[0,1]
	v_pk_add_f32 v[62:63], v[26:27], v[30:31]
	v_pk_add_f32 v[64:65], v[26:27], v[30:31] neg_lo:[0,1] neg_hi:[0,1]
	v_pk_add_f32 v[24:25], v[58:59], v[62:63]
	v_pk_add_f32 v[28:29], v[58:59], v[62:63] neg_lo:[0,1] neg_hi:[0,1]
	v_pk_add_f32 v[26:27], v[60:61], v[64:65] op_sel:[0,1] op_sel_hi:[1,0] neg_lo:[0,1]
	v_pk_add_f32 v[30:31], v[60:61], v[64:65] op_sel:[0,1] op_sel_hi:[1,0] neg_hi:[0,1]
	v_pk_add_f32 v[58:59], v[0:1], v[16:17]
	v_pk_add_f32 v[60:61], v[0:1], v[16:17] neg_lo:[0,1] neg_hi:[0,1]
	v_pk_add_f32 v[62:63], v[8:9], v[24:25]
	v_pk_add_f32 v[64:65], v[8:9], v[24:25] neg_lo:[0,1] neg_hi:[0,1]
	v_pk_add_f32 v[0:1], v[58:59], v[62:63]
	v_pk_add_f32 v[16:17], v[58:59], v[62:63] neg_lo:[0,1] neg_hi:[0,1]
	v_pk_add_f32 v[8:9], v[60:61], v[64:65] op_sel:[0,1] op_sel_hi:[1,0] neg_lo:[0,1]
	v_pk_add_f32 v[24:25], v[60:61], v[64:65] op_sel:[0,1] op_sel_hi:[1,0] neg_hi:[0,1]
	v_pk_mul_f32 v[66:67], v[10:11], v[68:69] op_sel:[1,1] op_sel_hi:[1,0] neg_lo:[0,0] neg_hi:[0,0]
	v_pk_fma_f32 v[10:11], v[10:11], v[68:69], v[66:67] op_sel:[0,0,0] op_sel_hi:[0,1,1] neg_lo:[0,0,1] neg_hi:[0,0,0]
	v_pk_mul_f32 v[66:67], v[18:19], v[70:71] op_sel:[1,1] op_sel_hi:[1,0] neg_lo:[0,0] neg_hi:[0,0]
	v_pk_fma_f32 v[18:19], v[18:19], v[70:71], v[66:67] op_sel:[0,0,0] op_sel_hi:[0,1,1] neg_lo:[0,0,1] neg_hi:[0,0,0]
	v_pk_mul_f32 v[66:67], v[26:27], v[68:69] op_sel:[1,0] op_sel_hi:[1,1] neg_lo:[0,0] neg_hi:[0,0]
	v_pk_fma_f32 v[26:27], v[26:27], v[68:69], v[66:67] op_sel:[0,1,0] op_sel_hi:[0,0,1] neg_lo:[0,0,1] neg_hi:[0,0,0]
	v_pk_add_f32 v[58:59], v[2:3], v[18:19]
	v_pk_add_f32 v[60:61], v[2:3], v[18:19] neg_lo:[0,1] neg_hi:[0,1]
	v_pk_add_f32 v[62:63], v[10:11], v[26:27]
	v_pk_add_f32 v[64:65], v[10:11], v[26:27] neg_lo:[0,1] neg_hi:[0,1]
	v_pk_add_f32 v[2:3], v[58:59], v[62:63]
	v_pk_add_f32 v[18:19], v[58:59], v[62:63] neg_lo:[0,1] neg_hi:[0,1]
	v_pk_add_f32 v[10:11], v[60:61], v[64:65] op_sel:[0,1] op_sel_hi:[1,0] neg_lo:[0,1]
	v_pk_add_f32 v[26:27], v[60:61], v[64:65] op_sel:[0,1] op_sel_hi:[1,0] neg_hi:[0,1]
	v_pk_mul_f32 v[66:67], v[12:13], v[70:71] op_sel:[1,1] op_sel_hi:[1,0] neg_lo:[0,0] neg_hi:[0,0]
	v_pk_fma_f32 v[12:13], v[12:13], v[70:71], v[66:67] op_sel:[0,0,0] op_sel_hi:[0,1,1] neg_lo:[0,0,1] neg_hi:[0,0,0]
	v_pk_add_f32 v[20:21], v[20:21], 0 op_sel:[1,0] op_sel_hi:[0,0] neg_lo:[1,0]
	v_pk_mul_f32 v[66:67], v[28:29], v[70:71] op_sel:[1,1] op_sel_hi:[1,0] neg_lo:[0,0] neg_hi:[0,1]
	v_pk_fma_f32 v[28:29], v[28:29], v[70:71], v[66:67] op_sel:[0,0,0] op_sel_hi:[0,1,1] neg_lo:[0,1,1] neg_hi:[0,0,0]
	v_pk_add_f32 v[58:59], v[4:5], v[20:21]
	v_pk_add_f32 v[60:61], v[4:5], v[20:21] neg_lo:[0,1] neg_hi:[0,1]
	v_pk_add_f32 v[62:63], v[12:13], v[28:29]
	v_pk_add_f32 v[64:65], v[12:13], v[28:29] neg_lo:[0,1] neg_hi:[0,1]
	v_pk_add_f32 v[4:5], v[58:59], v[62:63]
	v_pk_add_f32 v[20:21], v[58:59], v[62:63] neg_lo:[0,1] neg_hi:[0,1]
	v_pk_add_f32 v[12:13], v[60:61], v[64:65] op_sel:[0,1] op_sel_hi:[1,0] neg_lo:[0,1]
	v_pk_add_f32 v[28:29], v[60:61], v[64:65] op_sel:[0,1] op_sel_hi:[1,0] neg_hi:[0,1]
	v_pk_mul_f32 v[66:67], v[14:15], v[68:69] op_sel:[1,0] op_sel_hi:[1,1] neg_lo:[0,0] neg_hi:[0,0]
	v_pk_fma_f32 v[14:15], v[14:15], v[68:69], v[66:67] op_sel:[0,1,0] op_sel_hi:[0,0,1] neg_lo:[0,0,1] neg_hi:[0,0,0]
	v_pk_mul_f32 v[66:67], v[22:23], v[70:71] op_sel:[1,1] op_sel_hi:[1,0] neg_lo:[0,0] neg_hi:[0,1]
	v_pk_fma_f32 v[22:23], v[22:23], v[70:71], v[66:67] op_sel:[0,0,0] op_sel_hi:[0,1,1] neg_lo:[0,1,1] neg_hi:[0,0,0]
; HD float2 cmul(float2 a, float2 b){ return make_float2(a.x*b.x - a.y*b.y, a.x*b.y + a.y*b.x); }
; template<bool INV, bool NOTW>
; HD void bf4c(float2* Z, int i0, int i1, int i2, int i3, float2 w1, float2 w2, float2 w3){
;   float2 a0=Z[i0], a1=Z[i1], a2=Z[i2], a3=Z[i3];
;   if (INV && !NOTW){ a1=cmulc(a1,w1); a2=cmulc(a2,w2); a3=cmulc(a3,w3); }
;   float2 s02=make_float2(a0.x+a2.x,a0.y+a2.y), d02=make_float2(a0.x-a2.x,a0.y-a2.y);
;   float2 s13=make_float2(a1.x+a3.x,a1.y+a3.y), d13=make_float2(a1.x-a3.x,a1.y-a3.y);
;   float2 y0=make_float2(s02.x+s13.x,s02.y+s13.y), y2=make_float2(s02.x-s13.x,s02.y-s13.y);
;   float2 ym=make_float2(d02.x+d13.y,d02.y-d13.x);
;   float2 yp=make_float2(d02.x-d13.y,d02.y+d13.x);
;   float2 y1, y3;
;   if (INV){ y1=yp; y3=ym; } else if (NOTW){ y1=ym; y3=yp; } else { y1=cmul(ym,w1); y2=cmul(y2,w2); y3=cmul(yp,w3); }
;   Z[i0]=y0; Z[i1]=y1; Z[i2]=y2; Z[i3]=y3;
; __device__ __forceinline__ void fft_mid(float2* Z, const f16x2* Hp, int tid){
;   _Pragma("unroll 4") for (int i=0;i<8;++i){ int base=(tid<<2)+i*2048;
;     u32x4 hw=*(const u32x4*)(Hp+base);
;     unsigned hw0=hw[0], hw1=hw[1], hw2=hw[2], hw3=hw[3];
;     float2 a0=Z[base], a1=Z[base+1], a2=Z[base+2], a3=Z[base+3];
;     float2 s02=make_float2(a0.x+a2.x,a0.y+a2.y), d02=make_float2(a0.x-a2.x,a0.y-a2.y);
;     float2 s13=make_float2(a1.x+a3.x,a1.y+a3.y), d13=make_float2(a1.x-a3.x,a1.y-a3.y);
;     float2 y0=make_float2(s02.x+s13.x,s02.y+s13.y), y2=make_float2(s02.x-s13.x,s02.y-s13.y);
;     float2 y1=make_float2(d02.x+d13.y,d02.y-d13.x);
;     float2 y3=make_float2(d02.x-d13.y,d02.y+d13.x);
;     f16x2 h0=__builtin_bit_cast(f16x2,hw0), h1=__builtin_bit_cast(f16x2,hw1), h2=__builtin_bit_cast(f16x2,hw2), h3=__builtin_bit_cast(f16x2,hw3);
;     float2 b0=cmul(y0,make_float2((float)h0[0],(float)h0[1])), b1=cmul(y1,make_float2((float)h1[0],(float)h1[1]));
;     float2 b2=cmul(y2,make_float2((float)h2[0],(float)h2[1])), b3=cmul(y3,make_float2((float)h3[0],(float)h3[1]));
;     float2 t02=make_float2(b0.x+b2.x,b0.y+b2.y), e02=make_float2(b0.x-b2.x,b0.y-b2.y);
;     float2 t13=make_float2(b1.x+b3.x,b1.y+b3.y), e13=make_float2(b1.x-b3.x,b1.y-b3.y);
;     Z[base]=make_float2(t02.x+t13.x,t02.y+t13.y); Z[base+2]=make_float2(t02.x-t13.x,t02.y-t13.y);
;     Z[base+1]=make_float2(e02.x-e13.y,e02.y+e13.x);
;     Z[base+3]=make_float2(e02.x+e13.y,e02.y-e13.x);
;   }
	v_pk_mul_f32 v[66:67], v[30:31], v[68:69] op_sel:[1,1] op_sel_hi:[1,0] neg_lo:[0,1] neg_hi:[0,1]
	v_pk_fma_f32 v[30:31], v[30:31], v[68:69], v[66:67] op_sel:[0,0,0] op_sel_hi:[0,1,1] neg_lo:[0,1,1] neg_hi:[0,1,0]
	v_pk_add_f32 v[58:59], v[6:7], v[22:23]
	v_pk_add_f32 v[60:61], v[6:7], v[22:23] neg_lo:[0,1] neg_hi:[0,1]
	v_pk_add_f32 v[62:63], v[14:15], v[30:31]
	v_pk_add_f32 v[64:65], v[14:15], v[30:31] neg_lo:[0,1] neg_hi:[0,1]
	v_pk_add_f32 v[6:7], v[58:59], v[62:63]
	v_pk_add_f32 v[22:23], v[58:59], v[62:63] neg_lo:[0,1] neg_hi:[0,1]
	v_pk_add_f32 v[14:15], v[60:61], v[64:65] op_sel:[0,1] op_sel_hi:[1,0] neg_lo:[0,1]
	v_pk_add_f32 v[30:31], v[60:61], v[64:65] op_sel:[0,1] op_sel_hi:[1,0] neg_hi:[0,1]
	ds_write_b128 v222, v[0:3] offset:0
	ds_write_b128 v222, v[4:7] offset:16
	ds_write_b128 v222, v[8:11] offset:32
	ds_write_b128 v222, v[12:15] offset:48
	ds_write_b128 v222, v[16:19] offset:64
	ds_write_b128 v222, v[20:23] offset:80
	ds_write_b128 v222, v[24:27] offset:96
	ds_write_b128 v222, v[28:31] offset:112
	global_load_dwordx4 v[236:239], v224, s[68:69] offset:0
	global_load_dwordx4 v[240:243], v224, s[68:69] offset:16
	global_load_dwordx4 v[244:247], v224, s[68:69] offset:32
	global_load_dwordx4 v[248:251], v224, s[68:69] offset:48
	ds_read_b128 v[0:3], v223 offset:0
	ds_read_b128 v[4:7], v223 offset:16
	ds_read_b128 v[8:11], v223 offset:32
	ds_read_b128 v[12:15], v223 offset:48
	ds_read_b128 v[16:19], v223 offset:64
	ds_read_b128 v[20:23], v223 offset:80
	ds_read_b128 v[24:27], v223 offset:96
	ds_read_b128 v[28:31], v223 offset:112
	s_waitcnt lgkmcnt(0)
	v_pk_add_f32 v[58:59], v[0:1], v[16:17]
	v_pk_add_f32 v[60:61], v[0:1], v[16:17] neg_lo:[0,1] neg_hi:[0,1]
	v_pk_add_f32 v[62:63], v[8:9], v[24:25]
	v_pk_add_f32 v[64:65], v[8:9], v[24:25] neg_lo:[0,1] neg_hi:[0,1]
	v_pk_add_f32 v[0:1], v[58:59], v[62:63]
	v_pk_add_f32 v[16:17], v[58:59], v[62:63] neg_lo:[0,1] neg_hi:[0,1]
	v_pk_add_f32 v[8:9], v[60:61], v[64:65] op_sel:[0,1] op_sel_hi:[1,0] neg_hi:[0,1]
	v_pk_add_f32 v[24:25], v[60:61], v[64:65] op_sel:[0,1] op_sel_hi:[1,0] neg_lo:[0,1]
	v_pk_add_f32 v[58:59], v[2:3], v[18:19]
	v_pk_add_f32 v[60:61], v[2:3], v[18:19] neg_lo:[0,1] neg_hi:[0,1]
	v_pk_add_f32 v[62:63], v[10:11], v[26:27]
	v_pk_add_f32 v[64:65], v[10:11], v[26:27] neg_lo:[0,1] neg_hi:[0,1]
	v_pk_add_f32 v[2:3], v[58:59], v[62:63]
	v_pk_add_f32 v[18:19], v[58:59], v[62:63] neg_lo:[0,1] neg_hi:[0,1]
	v_pk_add_f32 v[10:11], v[60:61], v[64:65] op_sel:[0,1] op_sel_hi:[1,0] neg_hi:[0,1]
	v_pk_add_f32 v[26:27], v[60:61], v[64:65] op_sel:[0,1] op_sel_hi:[1,0] neg_lo:[0,1]
	v_pk_mul_f32 v[66:67], v[10:11], v[68:69] op_sel:[1,1] op_sel_hi:[1,0] neg_lo:[0,1] neg_hi:[0,0]
	v_pk_fma_f32 v[10:11], v[10:11], v[68:69], v[66:67] op_sel:[0,0,0] op_sel_hi:[0,1,1] neg_lo:[0,0,1] neg_hi:[0,1,0]
	v_pk_mul_f32 v[66:67], v[18:19], v[70:71] op_sel:[1,1] op_sel_hi:[1,0] neg_lo:[0,1] neg_hi:[0,0]
	v_pk_fma_f32 v[18:19], v[18:19], v[70:71], v[66:67] op_sel:[0,0,0] op_sel_hi:[0,1,1] neg_lo:[0,0,1] neg_hi:[0,1,0]
	v_pk_mul_f32 v[66:67], v[26:27], v[68:69] op_sel:[1,0] op_sel_hi:[1,1] neg_lo:[0,1] neg_hi:[0,0]
	v_pk_fma_f32 v[26:27], v[26:27], v[68:69], v[66:67] op_sel:[0,1,0] op_sel_hi:[0,0,1] neg_lo:[0,0,1] neg_hi:[0,1,0]
	v_pk_add_f32 v[58:59], v[4:5], v[20:21]
	v_pk_add_f32 v[60:61], v[4:5], v[20:21] neg_lo:[0,1] neg_hi:[0,1]
	v_pk_add_f32 v[62:63], v[12:13], v[28:29]
	v_pk_add_f32 v[64:65], v[12:13], v[28:29] neg_lo:[0,1] neg_hi:[0,1]
	v_pk_add_f32 v[4:5], v[58:59], v[62:63]
	v_pk_add_f32 v[20:21], v[58:59], v[62:63] neg_lo:[0,1] neg_hi:[0,1]
	v_pk_add_f32 v[12:13], v[60:61], v[64:65] op_sel:[0,1] op_sel_hi:[1,0] neg_hi:[0,1]
	v_pk_add_f32 v[28:29], v[60:61], v[64:65] op_sel:[0,1] op_sel_hi:[1,0] neg_lo:[0,1]
	v_pk_mul_f32 v[66:67], v[12:13], v[70:71] op_sel:[1,1] op_sel_hi:[1,0] neg_lo:[0,1] neg_hi:[0,0]
	v_pk_fma_f32 v[12:13], v[12:13], v[70:71], v[66:67] op_sel:[0,0,0] op_sel_hi:[0,1,1] neg_lo:[0,0,1] neg_hi:[0,1,0]
	v_pk_add_f32 v[20:21], v[20:21], 0 op_sel:[1,0] op_sel_hi:[0,0] neg_hi:[1,0]
	v_pk_mul_f32 v[66:67], v[28:29], v[70:71] op_sel:[1,1] op_sel_hi:[1,0] neg_lo:[0,1] neg_hi:[0,1]
	v_pk_fma_f32 v[28:29], v[28:29], v[70:71], v[66:67] op_sel:[0,0,0] op_sel_hi:[0,1,1] neg_lo:[0,1,1] neg_hi:[0,1,0]
	v_pk_add_f32 v[58:59], v[6:7], v[22:23]
	v_pk_add_f32 v[60:61], v[6:7], v[22:23] neg_lo:[0,1] neg_hi:[0,1]
	v_pk_add_f32 v[62:63], v[14:15], v[30:31]
	v_pk_add_f32 v[64:65], v[14:15], v[30:31] neg_lo:[0,1] neg_hi:[0,1]
	v_pk_add_f32 v[6:7], v[58:59], v[62:63]
	v_pk_add_f32 v[22:23], v[58:59], v[62:63] neg_lo:[0,1] neg_hi:[0,1]
	v_pk_add_f32 v[14:15], v[60:61], v[64:65] op_sel:[0,1] op_sel_hi:[1,0] neg_hi:[0,1]
	v_pk_add_f32 v[30:31], v[60:61], v[64:65] op_sel:[0,1] op_sel_hi:[1,0] neg_lo:[0,1]
	v_pk_mul_f32 v[66:67], v[14:15], v[68:69] op_sel:[1,0] op_sel_hi:[1,1] neg_lo:[0,1] neg_hi:[0,0]
	v_pk_fma_f32 v[14:15], v[14:15], v[68:69], v[66:67] op_sel:[0,1,0] op_sel_hi:[0,0,1] neg_lo:[0,0,1] neg_hi:[0,1,0]
	v_pk_mul_f32 v[66:67], v[22:23], v[70:71] op_sel:[1,1] op_sel_hi:[1,0] neg_lo:[0,1] neg_hi:[0,1]
	v_pk_fma_f32 v[22:23], v[22:23], v[70:71], v[66:67] op_sel:[0,0,0] op_sel_hi:[0,1,1] neg_lo:[0,1,1] neg_hi:[0,1,0]
	v_pk_mul_f32 v[66:67], v[30:31], v[68:69] op_sel:[1,1] op_sel_hi:[1,0] neg_lo:[0,0] neg_hi:[0,1]
	v_pk_fma_f32 v[30:31], v[30:31], v[68:69], v[66:67] op_sel:[0,0,0] op_sel_hi:[0,1,1] neg_lo:[0,1,1] neg_hi:[0,0,0]
	v_pk_add_f32 v[58:59], v[0:1], v[4:5]
	v_pk_add_f32 v[60:61], v[0:1], v[4:5] neg_lo:[0,1] neg_hi:[0,1]
	v_pk_add_f32 v[62:63], v[2:3], v[6:7]
	v_pk_add_f32 v[64:65], v[2:3], v[6:7] neg_lo:[0,1] neg_hi:[0,1]
	v_pk_add_f32 v[0:1], v[58:59], v[62:63]
; HD float2 cmul(float2 a, float2 b){ return make_float2(a.x*b.x - a.y*b.y, a.x*b.y + a.y*b.x); }
; __device__ __forceinline__ void fft_mid(float2* Z, const f16x2* Hp, int tid){
;     ...
;     float2 s02=make_float2(a0.x+a2.x,a0.y+a2.y), d02=make_float2(a0.x-a2.x,a0.y-a2.y);
;     float2 s13=make_float2(a1.x+a3.x,a1.y+a3.y), d13=make_float2(a1.x-a3.x,a1.y-a3.y);
;     float2 y0=make_float2(s02.x+s13.x,s02.y+s13.y), y2=make_float2(s02.x-s13.x,s02.y-s13.y);
;     float2 y1=make_float2(d02.x+d13.y,d02.y-d13.x);
;     float2 y3=make_float2(d02.x-d13.y,d02.y+d13.x);
;     f16x2 h0=__builtin_bit_cast(f16x2,hw0), h1=__builtin_bit_cast(f16x2,hw1), h2=__builtin_bit_cast(f16x2,hw2), h3=__builtin_bit_cast(f16x2,hw3);
;     float2 b0=cmul(y0,make_float2((float)h0[0],(float)h0[1])), b1=cmul(y1,make_float2((float)h1[0],(float)h1[1]));
;     float2 b2=cmul(y2,make_float2((float)h2[0],(float)h2[1])), b3=cmul(y3,make_float2((float)h3[0],(float)h3[1]));
	v_pk_add_f32 v[4:5], v[58:59], v[62:63] neg_lo:[0,1] neg_hi:[0,1]
	v_pk_add_f32 v[2:3], v[60:61], v[64:65] op_sel:[0,1] op_sel_hi:[1,0] neg_hi:[0,1]
	v_pk_add_f32 v[6:7], v[60:61], v[64:65] op_sel:[0,1] op_sel_hi:[1,0] neg_lo:[0,1]
	v_pk_add_f32 v[58:59], v[8:9], v[12:13]
	v_pk_add_f32 v[60:61], v[8:9], v[12:13] neg_lo:[0,1] neg_hi:[0,1]
	v_pk_add_f32 v[62:63], v[10:11], v[14:15]
	v_pk_add_f32 v[64:65], v[10:11], v[14:15] neg_lo:[0,1] neg_hi:[0,1]
	v_pk_add_f32 v[8:9], v[58:59], v[62:63]
	v_pk_add_f32 v[12:13], v[58:59], v[62:63] neg_lo:[0,1] neg_hi:[0,1]
	v_pk_add_f32 v[10:11], v[60:61], v[64:65] op_sel:[0,1] op_sel_hi:[1,0] neg_hi:[0,1]
	v_pk_add_f32 v[14:15], v[60:61], v[64:65] op_sel:[0,1] op_sel_hi:[1,0] neg_lo:[0,1]
	v_pk_add_f32 v[58:59], v[16:17], v[20:21]
	v_pk_add_f32 v[60:61], v[16:17], v[20:21] neg_lo:[0,1] neg_hi:[0,1]
	v_pk_add_f32 v[62:63], v[18:19], v[22:23]
	v_pk_add_f32 v[64:65], v[18:19], v[22:23] neg_lo:[0,1] neg_hi:[0,1]
	v_pk_add_f32 v[16:17], v[58:59], v[62:63]
	v_pk_add_f32 v[20:21], v[58:59], v[62:63] neg_lo:[0,1] neg_hi:[0,1]
	v_pk_add_f32 v[18:19], v[60:61], v[64:65] op_sel:[0,1] op_sel_hi:[1,0] neg_hi:[0,1]
	v_pk_add_f32 v[22:23], v[60:61], v[64:65] op_sel:[0,1] op_sel_hi:[1,0] neg_lo:[0,1]
	v_pk_add_f32 v[58:59], v[24:25], v[28:29]
	v_pk_add_f32 v[60:61], v[24:25], v[28:29] neg_lo:[0,1] neg_hi:[0,1]
	v_pk_add_f32 v[62:63], v[26:27], v[30:31]
	v_pk_add_f32 v[64:65], v[26:27], v[30:31] neg_lo:[0,1] neg_hi:[0,1]
	v_pk_add_f32 v[24:25], v[58:59], v[62:63]
	v_pk_add_f32 v[28:29], v[58:59], v[62:63] neg_lo:[0,1] neg_hi:[0,1]
	v_pk_add_f32 v[26:27], v[60:61], v[64:65] op_sel:[0,1] op_sel_hi:[1,0] neg_hi:[0,1]
	v_pk_add_f32 v[30:31], v[60:61], v[64:65] op_sel:[0,1] op_sel_hi:[1,0] neg_lo:[0,1]
	s_waitcnt vmcnt(0)
	v_cvt_f32_f16_e32 v72, v236
	v_cvt_f32_f16_sdwa v73, v236 dst_sel:DWORD dst_unused:UNUSED_PAD src0_sel:WORD_1
	s_nop 0
	v_pk_mul_f32 v[66:67], v[0:1], v[72:73] op_sel:[1,1] op_sel_hi:[1,0]
	v_pk_fma_f32 v[0:1], v[0:1], v[72:73], v[66:67] op_sel:[0,0,0] op_sel_hi:[0,1,1] neg_lo:[0,0,1]
	v_cvt_f32_f16_e32 v72, v237
	v_cvt_f32_f16_sdwa v73, v237 dst_sel:DWORD dst_unused:UNUSED_PAD src0_sel:WORD_1
	s_nop 0
	v_pk_mul_f32 v[66:67], v[2:3], v[72:73] op_sel:[1,1] op_sel_hi:[1,0]
	v_pk_fma_f32 v[2:3], v[2:3], v[72:73], v[66:67] op_sel:[0,0,0] op_sel_hi:[0,1,1] neg_lo:[0,0,1]
	v_cvt_f32_f16_e32 v72, v238
	v_cvt_f32_f16_sdwa v73, v238 dst_sel:DWORD dst_unused:UNUSED_PAD src0_sel:WORD_1
	s_nop 0
	v_pk_mul_f32 v[66:67], v[4:5], v[72:73] op_sel:[1,1] op_sel_hi:[1,0]
	v_pk_fma_f32 v[4:5], v[4:5], v[72:73], v[66:67] op_sel:[0,0,0] op_sel_hi:[0,1,1] neg_lo:[0,0,1]
	v_cvt_f32_f16_e32 v72, v239
	v_cvt_f32_f16_sdwa v73, v239 dst_sel:DWORD dst_unused:UNUSED_PAD src0_sel:WORD_1
	s_nop 0
	v_pk_mul_f32 v[66:67], v[6:7], v[72:73] op_sel:[1,1] op_sel_hi:[1,0]
	v_pk_fma_f32 v[6:7], v[6:7], v[72:73], v[66:67] op_sel:[0,0,0] op_sel_hi:[0,1,1] neg_lo:[0,0,1]
	v_cvt_f32_f16_e32 v72, v240
	v_cvt_f32_f16_sdwa v73, v240 dst_sel:DWORD dst_unused:UNUSED_PAD src0_sel:WORD_1
	s_nop 0
	v_pk_mul_f32 v[66:67], v[8:9], v[72:73] op_sel:[1,1] op_sel_hi:[1,0]
	v_pk_fma_f32 v[8:9], v[8:9], v[72:73], v[66:67] op_sel:[0,0,0] op_sel_hi:[0,1,1] neg_lo:[0,0,1]
	v_cvt_f32_f16_e32 v72, v241
	v_cvt_f32_f16_sdwa v73, v241 dst_sel:DWORD dst_unused:UNUSED_PAD src0_sel:WORD_1
	s_nop 0
	v_pk_mul_f32 v[66:67], v[10:11], v[72:73] op_sel:[1,1] op_sel_hi:[1,0]
	v_pk_fma_f32 v[10:11], v[10:11], v[72:73], v[66:67] op_sel:[0,0,0] op_sel_hi:[0,1,1] neg_lo:[0,0,1]
	v_cvt_f32_f16_e32 v72, v242
	v_cvt_f32_f16_sdwa v73, v242 dst_sel:DWORD dst_unused:UNUSED_PAD src0_sel:WORD_1
	s_nop 0
	v_pk_mul_f32 v[66:67], v[12:13], v[72:73] op_sel:[1,1] op_sel_hi:[1,0]
	v_pk_fma_f32 v[12:13], v[12:13], v[72:73], v[66:67] op_sel:[0,0,0] op_sel_hi:[0,1,1] neg_lo:[0,0,1]
	v_cvt_f32_f16_e32 v72, v243
	v_cvt_f32_f16_sdwa v73, v243 dst_sel:DWORD dst_unused:UNUSED_PAD src0_sel:WORD_1
	s_nop 0
	v_pk_mul_f32 v[66:67], v[14:15], v[72:73] op_sel:[1,1] op_sel_hi:[1,0]
	v_pk_fma_f32 v[14:15], v[14:15], v[72:73], v[66:67] op_sel:[0,0,0] op_sel_hi:[0,1,1] neg_lo:[0,0,1]
	v_cvt_f32_f16_e32 v72, v244
	v_cvt_f32_f16_sdwa v73, v244 dst_sel:DWORD dst_unused:UNUSED_PAD src0_sel:WORD_1
	s_nop 0
	v_pk_mul_f32 v[66:67], v[16:17], v[72:73] op_sel:[1,1] op_sel_hi:[1,0]
	v_pk_fma_f32 v[16:17], v[16:17], v[72:73], v[66:67] op_sel:[0,0,0] op_sel_hi:[0,1,1] neg_lo:[0,0,1]
	v_cvt_f32_f16_e32 v72, v245
	v_cvt_f32_f16_sdwa v73, v245 dst_sel:DWORD dst_unused:UNUSED_PAD src0_sel:WORD_1
	s_nop 0
	v_pk_mul_f32 v[66:67], v[18:19], v[72:73] op_sel:[1,1] op_sel_hi:[1,0]
	v_pk_fma_f32 v[18:19], v[18:19], v[72:73], v[66:67] op_sel:[0,0,0] op_sel_hi:[0,1,1] neg_lo:[0,0,1]
	v_cvt_f32_f16_e32 v72, v246
	v_cvt_f32_f16_sdwa v73, v246 dst_sel:DWORD dst_unused:UNUSED_PAD src0_sel:WORD_1
	s_nop 0
	v_pk_mul_f32 v[66:67], v[20:21], v[72:73] op_sel:[1,1] op_sel_hi:[1,0]
	v_pk_fma_f32 v[20:21], v[20:21], v[72:73], v[66:67] op_sel:[0,0,0] op_sel_hi:[0,1,1] neg_lo:[0,0,1]
	v_cvt_f32_f16_e32 v72, v247
	v_cvt_f32_f16_sdwa v73, v247 dst_sel:DWORD dst_unused:UNUSED_PAD src0_sel:WORD_1
	s_nop 0
	v_pk_mul_f32 v[66:67], v[22:23], v[72:73] op_sel:[1,1] op_sel_hi:[1,0]
	v_pk_fma_f32 v[22:23], v[22:23], v[72:73], v[66:67] op_sel:[0,0,0] op_sel_hi:[0,1,1] neg_lo:[0,0,1]
	v_cvt_f32_f16_e32 v72, v248
	v_cvt_f32_f16_sdwa v73, v248 dst_sel:DWORD dst_unused:UNUSED_PAD src0_sel:WORD_1
	s_nop 0
	v_pk_mul_f32 v[66:67], v[24:25], v[72:73] op_sel:[1,1] op_sel_hi:[1,0]
	v_pk_fma_f32 v[24:25], v[24:25], v[72:73], v[66:67] op_sel:[0,0,0] op_sel_hi:[0,1,1] neg_lo:[0,0,1]
	v_cvt_f32_f16_e32 v72, v249
	v_cvt_f32_f16_sdwa v73, v249 dst_sel:DWORD dst_unused:UNUSED_PAD src0_sel:WORD_1
; HD float2 cmul(float2 a, float2 b){ return make_float2(a.x*b.x - a.y*b.y, a.x*b.y + a.y*b.x); }
; HD float2 cmulc(float2 a, float2 b){ return make_float2(a.x*b.x + a.y*b.y, a.y*b.x - a.x*b.y); }
; template<bool INV, bool NOTW>
; HD void bf4c(float2* Z, int i0, int i1, int i2, int i3, float2 w1, float2 w2, float2 w3){
;   float2 a0=Z[i0], a1=Z[i1], a2=Z[i2], a3=Z[i3];
;   if (INV && !NOTW){ a1=cmulc(a1,w1); a2=cmulc(a2,w2); a3=cmulc(a3,w3); }
;   float2 s02=make_float2(a0.x+a2.x,a0.y+a2.y), d02=make_float2(a0.x-a2.x,a0.y-a2.y);
;   float2 s13=make_float2(a1.x+a3.x,a1.y+a3.y), d13=make_float2(a1.x-a3.x,a1.y-a3.y);
;   float2 y0=make_float2(s02.x+s13.x,s02.y+s13.y), y2=make_float2(s02.x-s13.x,s02.y-s13.y);
;   float2 ym=make_float2(d02.x+d13.y,d02.y-d13.x);
;   float2 yp=make_float2(d02.x-d13.y,d02.y+d13.x);
;   float2 y1, y3;
;   if (INV){ y1=yp; y3=ym; } else if (NOTW){ y1=ym; y3=yp; } else { y1=cmul(ym,w1); y2=cmul(y2,w2); y3=cmul(yp,w3); }
;   Z[i0]=y0; Z[i1]=y1; Z[i2]=y2; Z[i3]=y3;
; __device__ __forceinline__ void fft_mid(float2* Z, const f16x2* Hp, int tid){
;     ...
;     float2 t02=make_float2(b0.x+b2.x,b0.y+b2.y), e02=make_float2(b0.x-b2.x,b0.y-b2.y);
;     float2 t13=make_float2(b1.x+b3.x,b1.y+b3.y), e13=make_float2(b1.x-b3.x,b1.y-b3.y);
;     Z[base]=make_float2(t02.x+t13.x,t02.y+t13.y); Z[base+2]=make_float2(t02.x-t13.x,t02.y-t13.y);
;     Z[base+1]=make_float2(e02.x-e13.y,e02.y+e13.x);
;     Z[base+3]=make_float2(e02.x+e13.y,e02.y-e13.x);
	s_nop 0
	v_pk_mul_f32 v[66:67], v[26:27], v[72:73] op_sel:[1,1] op_sel_hi:[1,0]
	v_pk_fma_f32 v[26:27], v[26:27], v[72:73], v[66:67] op_sel:[0,0,0] op_sel_hi:[0,1,1] neg_lo:[0,0,1]
	v_cvt_f32_f16_e32 v72, v250
	v_cvt_f32_f16_sdwa v73, v250 dst_sel:DWORD dst_unused:UNUSED_PAD src0_sel:WORD_1
	s_nop 0
	v_pk_mul_f32 v[66:67], v[28:29], v[72:73] op_sel:[1,1] op_sel_hi:[1,0]
	v_pk_fma_f32 v[28:29], v[28:29], v[72:73], v[66:67] op_sel:[0,0,0] op_sel_hi:[0,1,1] neg_lo:[0,0,1]
	v_cvt_f32_f16_e32 v72, v251
	v_cvt_f32_f16_sdwa v73, v251 dst_sel:DWORD dst_unused:UNUSED_PAD src0_sel:WORD_1
	s_nop 0
	v_pk_mul_f32 v[66:67], v[30:31], v[72:73] op_sel:[1,1] op_sel_hi:[1,0]
	v_pk_fma_f32 v[30:31], v[30:31], v[72:73], v[66:67] op_sel:[0,0,0] op_sel_hi:[0,1,1] neg_lo:[0,0,1]
	v_pk_add_f32 v[58:59], v[0:1], v[4:5]
	v_pk_add_f32 v[60:61], v[0:1], v[4:5] neg_lo:[0,1] neg_hi:[0,1]
	v_pk_add_f32 v[62:63], v[2:3], v[6:7]
	v_pk_add_f32 v[64:65], v[2:3], v[6:7] neg_lo:[0,1] neg_hi:[0,1]
	v_pk_add_f32 v[0:1], v[58:59], v[62:63]
	v_pk_add_f32 v[4:5], v[58:59], v[62:63] neg_lo:[0,1] neg_hi:[0,1]
	v_pk_add_f32 v[2:3], v[60:61], v[64:65] op_sel:[0,1] op_sel_hi:[1,0] neg_lo:[0,1]
	v_pk_add_f32 v[6:7], v[60:61], v[64:65] op_sel:[0,1] op_sel_hi:[1,0] neg_hi:[0,1]
	v_pk_add_f32 v[58:59], v[8:9], v[12:13]
	v_pk_add_f32 v[60:61], v[8:9], v[12:13] neg_lo:[0,1] neg_hi:[0,1]
	v_pk_add_f32 v[62:63], v[10:11], v[14:15]
	v_pk_add_f32 v[64:65], v[10:11], v[14:15] neg_lo:[0,1] neg_hi:[0,1]
	v_pk_add_f32 v[8:9], v[58:59], v[62:63]
	v_pk_add_f32 v[12:13], v[58:59], v[62:63] neg_lo:[0,1] neg_hi:[0,1]
	v_pk_add_f32 v[10:11], v[60:61], v[64:65] op_sel:[0,1] op_sel_hi:[1,0] neg_lo:[0,1]
	v_pk_add_f32 v[14:15], v[60:61], v[64:65] op_sel:[0,1] op_sel_hi:[1,0] neg_hi:[0,1]
	v_pk_add_f32 v[58:59], v[16:17], v[20:21]
	v_pk_add_f32 v[60:61], v[16:17], v[20:21] neg_lo:[0,1] neg_hi:[0,1]
	v_pk_add_f32 v[62:63], v[18:19], v[22:23]
	v_pk_add_f32 v[64:65], v[18:19], v[22:23] neg_lo:[0,1] neg_hi:[0,1]
	v_pk_add_f32 v[16:17], v[58:59], v[62:63]
	v_pk_add_f32 v[20:21], v[58:59], v[62:63] neg_lo:[0,1] neg_hi:[0,1]
	v_pk_add_f32 v[18:19], v[60:61], v[64:65] op_sel:[0,1] op_sel_hi:[1,0] neg_lo:[0,1]
	v_pk_add_f32 v[22:23], v[60:61], v[64:65] op_sel:[0,1] op_sel_hi:[1,0] neg_hi:[0,1]
	v_pk_add_f32 v[58:59], v[24:25], v[28:29]
	v_pk_add_f32 v[60:61], v[24:25], v[28:29] neg_lo:[0,1] neg_hi:[0,1]
	v_pk_add_f32 v[62:63], v[26:27], v[30:31]
	v_pk_add_f32 v[64:65], v[26:27], v[30:31] neg_lo:[0,1] neg_hi:[0,1]
	v_pk_add_f32 v[24:25], v[58:59], v[62:63]
	v_pk_add_f32 v[28:29], v[58:59], v[62:63] neg_lo:[0,1] neg_hi:[0,1]
	v_pk_add_f32 v[26:27], v[60:61], v[64:65] op_sel:[0,1] op_sel_hi:[1,0] neg_lo:[0,1]
	v_pk_add_f32 v[30:31], v[60:61], v[64:65] op_sel:[0,1] op_sel_hi:[1,0] neg_hi:[0,1]
	v_pk_add_f32 v[58:59], v[0:1], v[16:17]
	v_pk_add_f32 v[60:61], v[0:1], v[16:17] neg_lo:[0,1] neg_hi:[0,1]
	v_pk_add_f32 v[62:63], v[8:9], v[24:25]
	v_pk_add_f32 v[64:65], v[8:9], v[24:25] neg_lo:[0,1] neg_hi:[0,1]
	v_pk_add_f32 v[0:1], v[58:59], v[62:63]
	v_pk_add_f32 v[16:17], v[58:59], v[62:63] neg_lo:[0,1] neg_hi:[0,1]
	v_pk_add_f32 v[8:9], v[60:61], v[64:65] op_sel:[0,1] op_sel_hi:[1,0] neg_lo:[0,1]
	v_pk_add_f32 v[24:25], v[60:61], v[64:65] op_sel:[0,1] op_sel_hi:[1,0] neg_hi:[0,1]
	v_pk_mul_f32 v[66:67], v[10:11], v[68:69] op_sel:[1,1] op_sel_hi:[1,0] neg_lo:[0,0] neg_hi:[0,0]
	v_pk_fma_f32 v[10:11], v[10:11], v[68:69], v[66:67] op_sel:[0,0,0] op_sel_hi:[0,1,1] neg_lo:[0,0,1] neg_hi:[0,0,0]
	v_pk_mul_f32 v[66:67], v[18:19], v[70:71] op_sel:[1,1] op_sel_hi:[1,0] neg_lo:[0,0] neg_hi:[0,0]
	v_pk_fma_f32 v[18:19], v[18:19], v[70:71], v[66:67] op_sel:[0,0,0] op_sel_hi:[0,1,1] neg_lo:[0,0,1] neg_hi:[0,0,0]
	v_pk_mul_f32 v[66:67], v[26:27], v[68:69] op_sel:[1,0] op_sel_hi:[1,1] neg_lo:[0,0] neg_hi:[0,0]
	v_pk_fma_f32 v[26:27], v[26:27], v[68:69], v[66:67] op_sel:[0,1,0] op_sel_hi:[0,0,1] neg_lo:[0,0,1] neg_hi:[0,0,0]
	v_pk_add_f32 v[58:59], v[2:3], v[18:19]
	v_pk_add_f32 v[60:61], v[2:3], v[18:19] neg_lo:[0,1] neg_hi:[0,1]
	v_pk_add_f32 v[62:63], v[10:11], v[26:27]
	v_pk_add_f32 v[64:65], v[10:11], v[26:27] neg_lo:[0,1] neg_hi:[0,1]
	v_pk_add_f32 v[2:3], v[58:59], v[62:63]
	v_pk_add_f32 v[18:19], v[58:59], v[62:63] neg_lo:[0,1] neg_hi:[0,1]
	v_pk_add_f32 v[10:11], v[60:61], v[64:65] op_sel:[0,1] op_sel_hi:[1,0] neg_lo:[0,1]
	v_pk_add_f32 v[26:27], v[60:61], v[64:65] op_sel:[0,1] op_sel_hi:[1,0] neg_hi:[0,1]
	v_pk_mul_f32 v[66:67], v[12:13], v[70:71] op_sel:[1,1] op_sel_hi:[1,0] neg_lo:[0,0] neg_hi:[0,0]
	v_pk_fma_f32 v[12:13], v[12:13], v[70:71], v[66:67] op_sel:[0,0,0] op_sel_hi:[0,1,1] neg_lo:[0,0,1] neg_hi:[0,0,0]
	v_pk_add_f32 v[20:21], v[20:21], 0 op_sel:[1,0] op_sel_hi:[0,0] neg_lo:[1,0]
	v_pk_mul_f32 v[66:67], v[28:29], v[70:71] op_sel:[1,1] op_sel_hi:[1,0] neg_lo:[0,0] neg_hi:[0,1]
	v_pk_fma_f32 v[28:29], v[28:29], v[70:71], v[66:67] op_sel:[0,0,0] op_sel_hi:[0,1,1] neg_lo:[0,1,1] neg_hi:[0,0,0]
	v_pk_add_f32 v[58:59], v[4:5], v[20:21]
	v_pk_add_f32 v[60:61], v[4:5], v[20:21] neg_lo:[0,1] neg_hi:[0,1]
	v_pk_add_f32 v[62:63], v[12:13], v[28:29]
	v_pk_add_f32 v[64:65], v[12:13], v[28:29] neg_lo:[0,1] neg_hi:[0,1]
	v_pk_add_f32 v[4:5], v[58:59], v[62:63]
	v_pk_add_f32 v[20:21], v[58:59], v[62:63] neg_lo:[0,1] neg_hi:[0,1]
	v_pk_add_f32 v[12:13], v[60:61], v[64:65] op_sel:[0,1] op_sel_hi:[1,0] neg_lo:[0,1]
	v_pk_add_f32 v[28:29], v[60:61], v[64:65] op_sel:[0,1] op_sel_hi:[1,0] neg_hi:[0,1]
	v_pk_mul_f32 v[66:67], v[14:15], v[68:69] op_sel:[1,0] op_sel_hi:[1,1] neg_lo:[0,0] neg_hi:[0,0]
	v_pk_fma_f32 v[14:15], v[14:15], v[68:69], v[66:67] op_sel:[0,1,0] op_sel_hi:[0,0,1] neg_lo:[0,0,1] neg_hi:[0,0,0]
	v_pk_mul_f32 v[66:67], v[22:23], v[70:71] op_sel:[1,1] op_sel_hi:[1,0] neg_lo:[0,0] neg_hi:[0,1]
	v_pk_fma_f32 v[22:23], v[22:23], v[70:71], v[66:67] op_sel:[0,0,0] op_sel_hi:[0,1,1] neg_lo:[0,1,1] neg_hi:[0,0,0]
	v_pk_mul_f32 v[66:67], v[30:31], v[68:69] op_sel:[1,1] op_sel_hi:[1,0] neg_lo:[0,1] neg_hi:[0,1]
	v_pk_fma_f32 v[30:31], v[30:31], v[68:69], v[66:67] op_sel:[0,0,0] op_sel_hi:[0,1,1] neg_lo:[0,1,1] neg_hi:[0,1,0]
	v_pk_add_f32 v[58:59], v[6:7], v[22:23]
	v_pk_add_f32 v[60:61], v[6:7], v[22:23] neg_lo:[0,1] neg_hi:[0,1]
	v_pk_add_f32 v[62:63], v[14:15], v[30:31]
	v_pk_add_f32 v[64:65], v[14:15], v[30:31] neg_lo:[0,1] neg_hi:[0,1]
	v_pk_add_f32 v[6:7], v[58:59], v[62:63]
	v_pk_add_f32 v[22:23], v[58:59], v[62:63] neg_lo:[0,1] neg_hi:[0,1]
	v_pk_add_f32 v[14:15], v[60:61], v[64:65] op_sel:[0,1] op_sel_hi:[1,0] neg_lo:[0,1]
	v_pk_add_f32 v[30:31], v[60:61], v[64:65] op_sel:[0,1] op_sel_hi:[1,0] neg_hi:[0,1]
	ds_write_b128 v223, v[0:3] offset:0
	ds_write_b128 v223, v[4:7] offset:16
	ds_write_b128 v223, v[8:11] offset:32
	ds_write_b128 v223, v[12:15] offset:48
	ds_write_b128 v223, v[16:19] offset:64
	ds_write_b128 v223, v[20:23] offset:80
	ds_write_b128 v223, v[24:27] offset:96
	ds_write_b128 v223, v[28:31] offset:112
	s_waitcnt lgkmcnt(0)
; HD float2 cmul(float2 a, float2 b){ return make_float2(a.x*b.x - a.y*b.y, a.x*b.y + a.y*b.x); }
; HD float2 cmulc(float2 a, float2 b){ return make_float2(a.x*b.x + a.y*b.y, a.y*b.x - a.x*b.y); }
; template<bool INV, bool NOTW>
; HD void bf4c(float2* Z, int i0, int i1, int i2, int i3, float2 w1, float2 w2, float2 w3){
;   float2 a0=Z[i0], a1=Z[i1], a2=Z[i2], a3=Z[i3];
;   if (INV && !NOTW){ a1=cmulc(a1,w1); a2=cmulc(a2,w2); a3=cmulc(a3,w3); }
;   float2 s02=make_float2(a0.x+a2.x,a0.y+a2.y), d02=make_float2(a0.x-a2.x,a0.y-a2.y);
;   float2 s13=make_float2(a1.x+a3.x,a1.y+a3.y), d13=make_float2(a1.x-a3.x,a1.y-a3.y);
;   float2 y0=make_float2(s02.x+s13.x,s02.y+s13.y), y2=make_float2(s02.x-s13.x,s02.y-s13.y);
;   float2 ym=make_float2(d02.x+d13.y,d02.y-d13.x);
;   float2 yp=make_float2(d02.x-d13.y,d02.y+d13.x);
;   float2 y1, y3;
;   if (INV){ y1=yp; y3=ym; } else if (NOTW){ y1=ym; y3=yp; } else { y1=cmul(ym,w1); y2=cmul(y2,w2); y3=cmul(yp,w3); }
;   Z[i0]=y0; Z[i1]=y1; Z[i2]=y2; Z[i3]=y3;
; template<bool INV, int LQ, bool BARRIER=true>
; HD void fft_pass(float2* Z, const float2* twA, const float2* twB, int tid){
;     ...
;   } else {
;     int j=tid&(q-1); int base0=((tid>>LQ)<<(LQ+2))+j;
;     float2 w1=make_float2(1.f,0.f), w2=w1, w3=w1;
;     if (LQ>0){ int k=j*tws; w1=cmul(twA[k>>6],twB[k&63]); w2=cmul(w1,w1); w3=cmul(w2,w1); }
;     _Pragma("unroll") for (int i=0;i<8;++i){ int base=base0+i*2048; bf4c<INV,(LQ==0)>(Z,base,base+q,base+2*q,base+3*q,w1,w2,w3); }
;   }
;   if (BARRIER) __syncthreads(); else asm volatile("s_waitcnt lgkmcnt(0)" ::: "memory");
	s_mov_b64 s[18:19], 0x8000
	v_lshlrev_b32_e32 v232, 4, v154
	s_lshl_b32 s100, s90, 15
	v_add_u32_e32 v233, 0x2000, v232
	v_add_u32_e32 v234, 0x4000, v232
	v_add_u32_e32 v235, 0x6000, v232
	s_add_u32 s98, s70, 0x42bd000
	s_addc_u32 s99, s71, 0
	s_add_u32 s98, s98, s100
	s_addc_u32 s99, s99, 0
	s_cmp_eq_u32 s89, 1
	s_cbranch_scc1 .Lmy_pf_st1
	s_add_u32 s98, s98, 0x2000000
	s_addc_u32 s99, s99, 0
.Lmy_pf_st1:
	global_load_dwordx4 v[228:231], v232, s[98:99]
	global_load_dwordx4 v[228:231], v233, s[98:99]
	global_load_dwordx4 v[228:231], v234, s[98:99]
	global_load_dwordx4 v[228:231], v235, s[98:99]
	s_add_u32 s98, s98, 0x1000000
	s_addc_u32 s99, s99, 0
	global_load_dwordx4 v[228:231], v232, s[98:99]
	global_load_dwordx4 v[228:231], v233, s[98:99]
	global_load_dwordx4 v[228:231], v234, s[98:99]
	global_load_dwordx4 v[228:231], v235, s[98:99]
	s_waitcnt lgkmcnt(0)
	v_mov_b32_e32 v222, 0x3f6c835e
	v_mov_b32_e32 v223, 0x3ec3ef15
	v_mov_b32_e32 v224, 0x3f3504f3
	v_mov_b32_e32 v225, 0x3f3504f3
	v_and_b32_e32 v8, 15, v154
	v_lshlrev_b32_e32 v9, 3, v8
	v_add_u32_e32 v9, 0x20800, v9
	v_mov_b32_e32 v10, 0x20a00
	ds_read_b64 v[0:1], v9
	ds_read_b64 v[2:3], v10
	s_waitcnt lgkmcnt(0)
	v_pk_mul_f32 v[250:251], v[0:1], v[2:3] op_sel:[1,1] op_sel_hi:[1,0]
	v_pk_fma_f32 v[80:81], v[0:1], v[2:3], v[250:251] op_sel:[0,0,0] op_sel_hi:[0,1,1] neg_lo:[0,0,1]
	v_pk_mul_f32 v[250:251], v[80:81], v[80:81] op_sel:[1,1] op_sel_hi:[1,0]
	v_pk_fma_f32 v[82:83], v[80:81], v[80:81], v[250:251] op_sel:[0,0,0] op_sel_hi:[0,1,1] neg_lo:[0,0,1]
	v_pk_mul_f32 v[250:251], v[82:83], v[80:81] op_sel:[1,1] op_sel_hi:[1,0]
	v_pk_fma_f32 v[84:85], v[82:83], v[80:81], v[250:251] op_sel:[0,0,0] op_sel_hi:[0,1,1] neg_lo:[0,0,1]
	v_lshlrev_b32_e32 v9, 5, v8
	v_add_u32_e32 v9, 0x20800, v9
	v_mov_b32_e32 v10, 0x20a00
	ds_read_b64 v[0:1], v9
	ds_read_b64 v[2:3], v10
	s_waitcnt lgkmcnt(0)
	v_pk_mul_f32 v[250:251], v[0:1], v[2:3] op_sel:[1,1] op_sel_hi:[1,0]
	v_pk_fma_f32 v[236:237], v[0:1], v[2:3], v[250:251] op_sel:[0,0,0] op_sel_hi:[0,1,1] neg_lo:[0,0,1]
	v_pk_mul_f32 v[250:251], v[236:237], v[236:237] op_sel:[1,1] op_sel_hi:[1,0]
	v_pk_fma_f32 v[238:239], v[236:237], v[236:237], v[250:251] op_sel:[0,0,0] op_sel_hi:[0,1,1] neg_lo:[0,0,1]
	v_pk_mul_f32 v[250:251], v[238:239], v[236:237] op_sel:[1,1] op_sel_hi:[1,0]
	v_pk_fma_f32 v[240:241], v[238:239], v[236:237], v[250:251] op_sel:[0,0,0] op_sel_hi:[0,1,1] neg_lo:[0,0,1]
	v_lshrrev_b32_e32 v226, 6, v154
	v_bfe_u32 v227, v154, 4, 2
	v_lshl_add_u32 v226, v227, 3, v226
	v_lshlrev_b32_e32 v226, 8, v226
	v_and_b32_e32 v227, 15, v154
	v_add_u32_e32 v226, v226, v227
	v_lshlrev_b32_e32 v226, 3, v226
	v_add_u32_e32 v227, 0x10000, v226
	ds_read_b64 v[0:1], v226 offset:0
	ds_read_b64 v[2:3], v226 offset:128
	ds_read_b64 v[4:5], v226 offset:256
	ds_read_b64 v[6:7], v226 offset:384
	ds_read_b64 v[8:9], v226 offset:512
	ds_read_b64 v[10:11], v226 offset:640
	ds_read_b64 v[12:13], v226 offset:768
	ds_read_b64 v[14:15], v226 offset:896
	ds_read_b64 v[16:17], v226 offset:1024
	ds_read_b64 v[18:19], v226 offset:1152
	ds_read_b64 v[20:21], v226 offset:1280
	ds_read_b64 v[22:23], v226 offset:1408
	ds_read_b64 v[24:25], v226 offset:1536
	ds_read_b64 v[26:27], v226 offset:1664
	ds_read_b64 v[28:29], v226 offset:1792
	ds_read_b64 v[30:31], v226 offset:1920
	s_waitcnt lgkmcnt(12)
	v_pk_mul_f32 v[250:251], v[4:5], v[238:239] op_sel:[1,1] op_sel_hi:[0,1]
	v_pk_fma_f32 v[4:5], v[4:5], v[238:239], v[250:251] op_sel:[0,0,0] op_sel_hi:[1,0,1] neg_hi:[0,0,1]
	v_pk_mul_f32 v[250:251], v[2:3], v[236:237] op_sel:[1,1] op_sel_hi:[0,1]
	v_pk_fma_f32 v[2:3], v[2:3], v[236:237], v[250:251] op_sel:[0,0,0] op_sel_hi:[1,0,1] neg_hi:[0,0,1]
	v_pk_mul_f32 v[250:251], v[6:7], v[240:241] op_sel:[1,1] op_sel_hi:[0,1]
	v_pk_fma_f32 v[6:7], v[6:7], v[240:241], v[250:251] op_sel:[0,0,0] op_sel_hi:[1,0,1] neg_hi:[0,0,1]
	v_pk_add_f32 v[242:243], v[0:1], v[4:5]
	v_pk_add_f32 v[244:245], v[0:1], v[4:5] neg_lo:[0,1] neg_hi:[0,1]
	v_pk_add_f32 v[246:247], v[2:3], v[6:7]
	v_pk_add_f32 v[248:249], v[2:3], v[6:7] neg_lo:[0,1] neg_hi:[0,1]
	v_pk_add_f32 v[0:1], v[242:243], v[246:247]
	v_pk_add_f32 v[2:3], v[244:245], v[248:249] op_sel:[0,1] op_sel_hi:[1,0] neg_lo:[0,1]
	v_pk_add_f32 v[4:5], v[242:243], v[246:247] neg_lo:[0,1] neg_hi:[0,1]
	v_pk_add_f32 v[6:7], v[244:245], v[248:249] op_sel:[0,1] op_sel_hi:[1,0] neg_hi:[0,1]
	s_waitcnt lgkmcnt(8)
	v_pk_mul_f32 v[250:251], v[12:13], v[238:239] op_sel:[1,1] op_sel_hi:[0,1]
	v_pk_fma_f32 v[12:13], v[12:13], v[238:239], v[250:251] op_sel:[0,0,0] op_sel_hi:[1,0,1] neg_hi:[0,0,1]
	v_pk_mul_f32 v[250:251], v[10:11], v[236:237] op_sel:[1,1] op_sel_hi:[0,1]
	v_pk_fma_f32 v[10:11], v[10:11], v[236:237], v[250:251] op_sel:[0,0,0] op_sel_hi:[1,0,1] neg_hi:[0,0,1]
	v_pk_mul_f32 v[250:251], v[14:15], v[240:241] op_sel:[1,1] op_sel_hi:[0,1]
	v_pk_fma_f32 v[14:15], v[14:15], v[240:241], v[250:251] op_sel:[0,0,0] op_sel_hi:[1,0,1] neg_hi:[0,0,1]
	v_pk_add_f32 v[242:243], v[8:9], v[12:13]
	v_pk_add_f32 v[244:245], v[8:9], v[12:13] neg_lo:[0,1] neg_hi:[0,1]
	v_pk_add_f32 v[246:247], v[10:11], v[14:15]
	v_pk_add_f32 v[248:249], v[10:11], v[14:15] neg_lo:[0,1] neg_hi:[0,1]
	v_pk_add_f32 v[8:9], v[242:243], v[246:247]
	v_pk_add_f32 v[10:11], v[244:245], v[248:249] op_sel:[0,1] op_sel_hi:[1,0] neg_lo:[0,1]
	v_pk_add_f32 v[12:13], v[242:243], v[246:247] neg_lo:[0,1] neg_hi:[0,1]
	v_pk_add_f32 v[14:15], v[244:245], v[248:249] op_sel:[0,1] op_sel_hi:[1,0] neg_hi:[0,1]
	s_waitcnt lgkmcnt(4)
; HD float2 cmul(float2 a, float2 b){ return make_float2(a.x*b.x - a.y*b.y, a.x*b.y + a.y*b.x); }
; HD float2 cmulc(float2 a, float2 b){ return make_float2(a.x*b.x + a.y*b.y, a.y*b.x - a.x*b.y); }
; template<bool INV, bool NOTW>
; HD void bf4c(float2* Z, int i0, int i1, int i2, int i3, float2 w1, float2 w2, float2 w3){
;   float2 a0=Z[i0], a1=Z[i1], a2=Z[i2], a3=Z[i3];
;   if (INV && !NOTW){ a1=cmulc(a1,w1); a2=cmulc(a2,w2); a3=cmulc(a3,w3); }
;   float2 s02=make_float2(a0.x+a2.x,a0.y+a2.y), d02=make_float2(a0.x-a2.x,a0.y-a2.y);
;   float2 s13=make_float2(a1.x+a3.x,a1.y+a3.y), d13=make_float2(a1.x-a3.x,a1.y-a3.y);
;   float2 y0=make_float2(s02.x+s13.x,s02.y+s13.y), y2=make_float2(s02.x-s13.x,s02.y-s13.y);
;   float2 ym=make_float2(d02.x+d13.y,d02.y-d13.x);
;   float2 yp=make_float2(d02.x-d13.y,d02.y+d13.x);
;   float2 y1, y3;
;   if (INV){ y1=yp; y3=ym; } else if (NOTW){ y1=ym; y3=yp; } else { y1=cmul(ym,w1); y2=cmul(y2,w2); y3=cmul(yp,w3); }
;   Z[i0]=y0; Z[i1]=y1; Z[i2]=y2; Z[i3]=y3;
; template<bool INV, int LQ, bool BARRIER=true>
; HD void fft_pass(float2* Z, const float2* twA, const float2* twB, int tid){
;     ...
;   } else {
;     int j=tid&(q-1); int base0=((tid>>LQ)<<(LQ+2))+j;
;     float2 w1=make_float2(1.f,0.f), w2=w1, w3=w1;
;     if (LQ>0){ int k=j*tws; w1=cmul(twA[k>>6],twB[k&63]); w2=cmul(w1,w1); w3=cmul(w2,w1); }
;     _Pragma("unroll") for (int i=0;i<8;++i){ int base=base0+i*2048; bf4c<INV,(LQ==0)>(Z,base,base+q,base+2*q,base+3*q,w1,w2,w3); }
;   }
;   if (BARRIER) __syncthreads(); else asm volatile("s_waitcnt lgkmcnt(0)" ::: "memory");
	v_pk_mul_f32 v[250:251], v[20:21], v[238:239] op_sel:[1,1] op_sel_hi:[0,1]
	v_pk_fma_f32 v[20:21], v[20:21], v[238:239], v[250:251] op_sel:[0,0,0] op_sel_hi:[1,0,1] neg_hi:[0,0,1]
	v_pk_mul_f32 v[250:251], v[18:19], v[236:237] op_sel:[1,1] op_sel_hi:[0,1]
	v_pk_fma_f32 v[18:19], v[18:19], v[236:237], v[250:251] op_sel:[0,0,0] op_sel_hi:[1,0,1] neg_hi:[0,0,1]
	v_pk_mul_f32 v[250:251], v[22:23], v[240:241] op_sel:[1,1] op_sel_hi:[0,1]
	v_pk_fma_f32 v[22:23], v[22:23], v[240:241], v[250:251] op_sel:[0,0,0] op_sel_hi:[1,0,1] neg_hi:[0,0,1]
	v_pk_add_f32 v[242:243], v[16:17], v[20:21]
	v_pk_add_f32 v[244:245], v[16:17], v[20:21] neg_lo:[0,1] neg_hi:[0,1]
	v_pk_add_f32 v[246:247], v[18:19], v[22:23]
	v_pk_add_f32 v[248:249], v[18:19], v[22:23] neg_lo:[0,1] neg_hi:[0,1]
	v_pk_add_f32 v[16:17], v[242:243], v[246:247]
	v_pk_add_f32 v[18:19], v[244:245], v[248:249] op_sel:[0,1] op_sel_hi:[1,0] neg_lo:[0,1]
	v_pk_add_f32 v[20:21], v[242:243], v[246:247] neg_lo:[0,1] neg_hi:[0,1]
	v_pk_add_f32 v[22:23], v[244:245], v[248:249] op_sel:[0,1] op_sel_hi:[1,0] neg_hi:[0,1]
	s_waitcnt lgkmcnt(0)
	v_pk_mul_f32 v[250:251], v[28:29], v[238:239] op_sel:[1,1] op_sel_hi:[0,1]
	v_pk_fma_f32 v[28:29], v[28:29], v[238:239], v[250:251] op_sel:[0,0,0] op_sel_hi:[1,0,1] neg_hi:[0,0,1]
	v_pk_mul_f32 v[250:251], v[26:27], v[236:237] op_sel:[1,1] op_sel_hi:[0,1]
	v_pk_fma_f32 v[26:27], v[26:27], v[236:237], v[250:251] op_sel:[0,0,0] op_sel_hi:[1,0,1] neg_hi:[0,0,1]
	v_pk_mul_f32 v[250:251], v[30:31], v[240:241] op_sel:[1,1] op_sel_hi:[0,1]
	v_pk_fma_f32 v[30:31], v[30:31], v[240:241], v[250:251] op_sel:[0,0,0] op_sel_hi:[1,0,1] neg_hi:[0,0,1]
	v_pk_add_f32 v[242:243], v[24:25], v[28:29]
	v_pk_add_f32 v[244:245], v[24:25], v[28:29] neg_lo:[0,1] neg_hi:[0,1]
	v_pk_add_f32 v[246:247], v[26:27], v[30:31]
	v_pk_add_f32 v[248:249], v[26:27], v[30:31] neg_lo:[0,1] neg_hi:[0,1]
	v_pk_add_f32 v[24:25], v[242:243], v[246:247]
	v_pk_add_f32 v[26:27], v[244:245], v[248:249] op_sel:[0,1] op_sel_hi:[1,0] neg_lo:[0,1]
	v_pk_add_f32 v[28:29], v[242:243], v[246:247] neg_lo:[0,1] neg_hi:[0,1]
	v_pk_add_f32 v[30:31], v[244:245], v[248:249] op_sel:[0,1] op_sel_hi:[1,0] neg_hi:[0,1]
	v_pk_mul_f32 v[250:251], v[16:17], v[82:83] op_sel:[1,1] op_sel_hi:[0,1]
	v_pk_fma_f32 v[16:17], v[16:17], v[82:83], v[250:251] op_sel:[0,0,0] op_sel_hi:[1,0,1] neg_hi:[0,0,1]
	v_pk_mul_f32 v[250:251], v[8:9], v[80:81] op_sel:[1,1] op_sel_hi:[0,1]
	v_pk_fma_f32 v[8:9], v[8:9], v[80:81], v[250:251] op_sel:[0,0,0] op_sel_hi:[1,0,1] neg_hi:[0,0,1]
	v_pk_mul_f32 v[250:251], v[24:25], v[84:85] op_sel:[1,1] op_sel_hi:[0,1]
	v_pk_fma_f32 v[24:25], v[24:25], v[84:85], v[250:251] op_sel:[0,0,0] op_sel_hi:[1,0,1] neg_hi:[0,0,1]
	v_pk_add_f32 v[242:243], v[0:1], v[16:17]
	v_pk_add_f32 v[244:245], v[0:1], v[16:17] neg_lo:[0,1] neg_hi:[0,1]
	v_pk_add_f32 v[246:247], v[8:9], v[24:25]
	v_pk_add_f32 v[248:249], v[8:9], v[24:25] neg_lo:[0,1] neg_hi:[0,1]
	v_pk_add_f32 v[0:1], v[242:243], v[246:247]
	ds_write_b64 v226, v[0:1] offset:0
	v_pk_add_f32 v[8:9], v[244:245], v[248:249] op_sel:[0,1] op_sel_hi:[1,0] neg_lo:[0,1]
	ds_write_b64 v226, v[8:9] offset:512
	v_pk_add_f32 v[16:17], v[242:243], v[246:247] neg_lo:[0,1] neg_hi:[0,1]
	ds_write_b64 v226, v[16:17] offset:1024
	v_pk_add_f32 v[24:25], v[244:245], v[248:249] op_sel:[0,1] op_sel_hi:[1,0] neg_hi:[0,1]
	ds_write_b64 v226, v[24:25] offset:1536
	v_pk_mul_f32 v[250:251], v[18:19], v[224:225] op_sel:[1,1] op_sel_hi:[1,0] neg_lo:[0,0] neg_hi:[0,0]
	v_pk_fma_f32 v[18:19], v[18:19], v[224:225], v[250:251] op_sel:[0,0,0] op_sel_hi:[0,1,1] neg_lo:[0,0,1] neg_hi:[0,0,0]
	v_pk_mul_f32 v[250:251], v[18:19], v[82:83] op_sel:[1,1] op_sel_hi:[0,1]
	v_pk_fma_f32 v[18:19], v[18:19], v[82:83], v[250:251] op_sel:[0,0,0] op_sel_hi:[1,0,1] neg_hi:[0,0,1]
	v_pk_mul_f32 v[250:251], v[10:11], v[222:223] op_sel:[1,1] op_sel_hi:[1,0] neg_lo:[0,0] neg_hi:[0,0]
	v_pk_fma_f32 v[10:11], v[10:11], v[222:223], v[250:251] op_sel:[0,0,0] op_sel_hi:[0,1,1] neg_lo:[0,0,1] neg_hi:[0,0,0]
	v_pk_mul_f32 v[250:251], v[10:11], v[80:81] op_sel:[1,1] op_sel_hi:[0,1]
	v_pk_fma_f32 v[10:11], v[10:11], v[80:81], v[250:251] op_sel:[0,0,0] op_sel_hi:[1,0,1] neg_hi:[0,0,1]
	v_pk_mul_f32 v[250:251], v[26:27], v[222:223] op_sel:[1,0] op_sel_hi:[1,1] neg_lo:[0,0] neg_hi:[0,0]
	v_pk_fma_f32 v[26:27], v[26:27], v[222:223], v[250:251] op_sel:[0,1,0] op_sel_hi:[0,0,1] neg_lo:[0,0,1] neg_hi:[0,0,0]
	v_pk_mul_f32 v[250:251], v[26:27], v[84:85] op_sel:[1,1] op_sel_hi:[0,1]
	v_pk_fma_f32 v[26:27], v[26:27], v[84:85], v[250:251] op_sel:[0,0,0] op_sel_hi:[1,0,1] neg_hi:[0,0,1]
	v_pk_add_f32 v[242:243], v[2:3], v[18:19]
	v_pk_add_f32 v[244:245], v[2:3], v[18:19] neg_lo:[0,1] neg_hi:[0,1]
	v_pk_add_f32 v[246:247], v[10:11], v[26:27]
	v_pk_add_f32 v[248:249], v[10:11], v[26:27] neg_lo:[0,1] neg_hi:[0,1]
	v_pk_add_f32 v[2:3], v[242:243], v[246:247]
	ds_write_b64 v226, v[2:3] offset:128
	v_pk_add_f32 v[10:11], v[244:245], v[248:249] op_sel:[0,1] op_sel_hi:[1,0] neg_lo:[0,1]
	ds_write_b64 v226, v[10:11] offset:640
	v_pk_add_f32 v[18:19], v[242:243], v[246:247] neg_lo:[0,1] neg_hi:[0,1]
	ds_write_b64 v226, v[18:19] offset:1152
	v_pk_add_f32 v[26:27], v[244:245], v[248:249] op_sel:[0,1] op_sel_hi:[1,0] neg_hi:[0,1]
	ds_write_b64 v226, v[26:27] offset:1664
	v_pk_add_f32 v[20:21], v[20:21], 0 op_sel:[1,0] op_sel_hi:[0,0] neg_lo:[1,0]
	v_pk_mul_f32 v[250:251], v[20:21], v[82:83] op_sel:[1,1] op_sel_hi:[0,1]
	v_pk_fma_f32 v[20:21], v[20:21], v[82:83], v[250:251] op_sel:[0,0,0] op_sel_hi:[1,0,1] neg_hi:[0,0,1]
	v_pk_mul_f32 v[250:251], v[12:13], v[224:225] op_sel:[1,1] op_sel_hi:[1,0] neg_lo:[0,0] neg_hi:[0,0]
; HD float2 cmul(float2 a, float2 b){ return make_float2(a.x*b.x - a.y*b.y, a.x*b.y + a.y*b.x); }
; HD float2 cmulc(float2 a, float2 b){ return make_float2(a.x*b.x + a.y*b.y, a.y*b.x - a.x*b.y); }
; template<bool INV, bool NOTW>
; HD void bf4c(float2* Z, int i0, int i1, int i2, int i3, float2 w1, float2 w2, float2 w3){
;   float2 a0=Z[i0], a1=Z[i1], a2=Z[i2], a3=Z[i3];
;   if (INV && !NOTW){ a1=cmulc(a1,w1); a2=cmulc(a2,w2); a3=cmulc(a3,w3); }
;   float2 s02=make_float2(a0.x+a2.x,a0.y+a2.y), d02=make_float2(a0.x-a2.x,a0.y-a2.y);
;   float2 s13=make_float2(a1.x+a3.x,a1.y+a3.y), d13=make_float2(a1.x-a3.x,a1.y-a3.y);
;   float2 y0=make_float2(s02.x+s13.x,s02.y+s13.y), y2=make_float2(s02.x-s13.x,s02.y-s13.y);
;   float2 ym=make_float2(d02.x+d13.y,d02.y-d13.x);
;   float2 yp=make_float2(d02.x-d13.y,d02.y+d13.x);
;   float2 y1, y3;
;   if (INV){ y1=yp; y3=ym; } else if (NOTW){ y1=ym; y3=yp; } else { y1=cmul(ym,w1); y2=cmul(y2,w2); y3=cmul(yp,w3); }
;   Z[i0]=y0; Z[i1]=y1; Z[i2]=y2; Z[i3]=y3;
; template<bool INV, int LQ, bool BARRIER=true>
; HD void fft_pass(float2* Z, const float2* twA, const float2* twB, int tid){
;     ...
;   } else {
;     int j=tid&(q-1); int base0=((tid>>LQ)<<(LQ+2))+j;
;     float2 w1=make_float2(1.f,0.f), w2=w1, w3=w1;
;     if (LQ>0){ int k=j*tws; w1=cmul(twA[k>>6],twB[k&63]); w2=cmul(w1,w1); w3=cmul(w2,w1); }
;     _Pragma("unroll") for (int i=0;i<8;++i){ int base=base0+i*2048; bf4c<INV,(LQ==0)>(Z,base,base+q,base+2*q,base+3*q,w1,w2,w3); }
;   }
;   if (BARRIER) __syncthreads(); else asm volatile("s_waitcnt lgkmcnt(0)" ::: "memory");
	v_pk_fma_f32 v[12:13], v[12:13], v[224:225], v[250:251] op_sel:[0,0,0] op_sel_hi:[0,1,1] neg_lo:[0,0,1] neg_hi:[0,0,0]
	v_pk_mul_f32 v[250:251], v[12:13], v[80:81] op_sel:[1,1] op_sel_hi:[0,1]
	v_pk_fma_f32 v[12:13], v[12:13], v[80:81], v[250:251] op_sel:[0,0,0] op_sel_hi:[1,0,1] neg_hi:[0,0,1]
	v_pk_mul_f32 v[250:251], v[28:29], v[224:225] op_sel:[1,1] op_sel_hi:[1,0] neg_lo:[0,0] neg_hi:[0,1]
	v_pk_fma_f32 v[28:29], v[28:29], v[224:225], v[250:251] op_sel:[0,0,0] op_sel_hi:[0,1,1] neg_lo:[0,1,1] neg_hi:[0,0,0]
	v_pk_mul_f32 v[250:251], v[28:29], v[84:85] op_sel:[1,1] op_sel_hi:[0,1]
	v_pk_fma_f32 v[28:29], v[28:29], v[84:85], v[250:251] op_sel:[0,0,0] op_sel_hi:[1,0,1] neg_hi:[0,0,1]
	v_pk_add_f32 v[242:243], v[4:5], v[20:21]
	v_pk_add_f32 v[244:245], v[4:5], v[20:21] neg_lo:[0,1] neg_hi:[0,1]
	v_pk_add_f32 v[246:247], v[12:13], v[28:29]
	v_pk_add_f32 v[248:249], v[12:13], v[28:29] neg_lo:[0,1] neg_hi:[0,1]
	v_pk_add_f32 v[4:5], v[242:243], v[246:247]
	ds_write_b64 v226, v[4:5] offset:256
	v_pk_add_f32 v[12:13], v[244:245], v[248:249] op_sel:[0,1] op_sel_hi:[1,0] neg_lo:[0,1]
	ds_write_b64 v226, v[12:13] offset:768
	v_pk_add_f32 v[20:21], v[242:243], v[246:247] neg_lo:[0,1] neg_hi:[0,1]
	ds_write_b64 v226, v[20:21] offset:1280
	v_pk_add_f32 v[28:29], v[244:245], v[248:249] op_sel:[0,1] op_sel_hi:[1,0] neg_hi:[0,1]
	ds_write_b64 v226, v[28:29] offset:1792
	v_pk_mul_f32 v[250:251], v[22:23], v[224:225] op_sel:[1,1] op_sel_hi:[1,0] neg_lo:[0,0] neg_hi:[0,1]
	v_pk_fma_f32 v[22:23], v[22:23], v[224:225], v[250:251] op_sel:[0,0,0] op_sel_hi:[0,1,1] neg_lo:[0,1,1] neg_hi:[0,0,0]
	v_pk_mul_f32 v[250:251], v[22:23], v[82:83] op_sel:[1,1] op_sel_hi:[0,1]
	v_pk_fma_f32 v[22:23], v[22:23], v[82:83], v[250:251] op_sel:[0,0,0] op_sel_hi:[1,0,1] neg_hi:[0,0,1]
	v_pk_mul_f32 v[250:251], v[14:15], v[222:223] op_sel:[1,0] op_sel_hi:[1,1] neg_lo:[0,0] neg_hi:[0,0]
	v_pk_fma_f32 v[14:15], v[14:15], v[222:223], v[250:251] op_sel:[0,1,0] op_sel_hi:[0,0,1] neg_lo:[0,0,1] neg_hi:[0,0,0]
	v_pk_mul_f32 v[250:251], v[14:15], v[80:81] op_sel:[1,1] op_sel_hi:[0,1]
	v_pk_fma_f32 v[14:15], v[14:15], v[80:81], v[250:251] op_sel:[0,0,0] op_sel_hi:[1,0,1] neg_hi:[0,0,1]
	v_pk_mul_f32 v[250:251], v[30:31], v[222:223] op_sel:[1,1] op_sel_hi:[1,0] neg_lo:[0,1] neg_hi:[0,1]
	v_pk_fma_f32 v[30:31], v[30:31], v[222:223], v[250:251] op_sel:[0,0,0] op_sel_hi:[0,1,1] neg_lo:[0,1,1] neg_hi:[0,1,0]
	v_pk_mul_f32 v[250:251], v[30:31], v[84:85] op_sel:[1,1] op_sel_hi:[0,1]
	v_pk_fma_f32 v[30:31], v[30:31], v[84:85], v[250:251] op_sel:[0,0,0] op_sel_hi:[1,0,1] neg_hi:[0,0,1]
	v_pk_add_f32 v[242:243], v[6:7], v[22:23]
	v_pk_add_f32 v[244:245], v[6:7], v[22:23] neg_lo:[0,1] neg_hi:[0,1]
	v_pk_add_f32 v[246:247], v[14:15], v[30:31]
	v_pk_add_f32 v[248:249], v[14:15], v[30:31] neg_lo:[0,1] neg_hi:[0,1]
	v_pk_add_f32 v[6:7], v[242:243], v[246:247]
	ds_write_b64 v226, v[6:7] offset:384
	v_pk_add_f32 v[14:15], v[244:245], v[248:249] op_sel:[0,1] op_sel_hi:[1,0] neg_lo:[0,1]
	ds_write_b64 v226, v[14:15] offset:896
	v_pk_add_f32 v[22:23], v[242:243], v[246:247] neg_lo:[0,1] neg_hi:[0,1]
	ds_write_b64 v226, v[22:23] offset:1408
	v_pk_add_f32 v[30:31], v[244:245], v[248:249] op_sel:[0,1] op_sel_hi:[1,0] neg_hi:[0,1]
	ds_write_b64 v226, v[30:31] offset:1920
	ds_read_b64 v[0:1], v227 offset:0
	ds_read_b64 v[2:3], v227 offset:128
	ds_read_b64 v[4:5], v227 offset:256
	ds_read_b64 v[6:7], v227 offset:384
	ds_read_b64 v[8:9], v227 offset:512
	ds_read_b64 v[10:11], v227 offset:640
	ds_read_b64 v[12:13], v227 offset:768
	ds_read_b64 v[14:15], v227 offset:896
	ds_read_b64 v[16:17], v227 offset:1024
	ds_read_b64 v[18:19], v227 offset:1152
	ds_read_b64 v[20:21], v227 offset:1280
	ds_read_b64 v[22:23], v227 offset:1408
	ds_read_b64 v[24:25], v227 offset:1536
	ds_read_b64 v[26:27], v227 offset:1664
	ds_read_b64 v[28:29], v227 offset:1792
	ds_read_b64 v[30:31], v227 offset:1920
	s_waitcnt lgkmcnt(12)
	v_pk_mul_f32 v[250:251], v[4:5], v[238:239] op_sel:[1,1] op_sel_hi:[0,1]
	v_pk_fma_f32 v[4:5], v[4:5], v[238:239], v[250:251] op_sel:[0,0,0] op_sel_hi:[1,0,1] neg_hi:[0,0,1]
	v_pk_mul_f32 v[250:251], v[2:3], v[236:237] op_sel:[1,1] op_sel_hi:[0,1]
	v_pk_fma_f32 v[2:3], v[2:3], v[236:237], v[250:251] op_sel:[0,0,0] op_sel_hi:[1,0,1] neg_hi:[0,0,1]
	v_pk_mul_f32 v[250:251], v[6:7], v[240:241] op_sel:[1,1] op_sel_hi:[0,1]
	v_pk_fma_f32 v[6:7], v[6:7], v[240:241], v[250:251] op_sel:[0,0,0] op_sel_hi:[1,0,1] neg_hi:[0,0,1]
	v_pk_add_f32 v[242:243], v[0:1], v[4:5]
	v_pk_add_f32 v[244:245], v[0:1], v[4:5] neg_lo:[0,1] neg_hi:[0,1]
	v_pk_add_f32 v[246:247], v[2:3], v[6:7]
	v_pk_add_f32 v[248:249], v[2:3], v[6:7] neg_lo:[0,1] neg_hi:[0,1]
	v_pk_add_f32 v[0:1], v[242:243], v[246:247]
	v_pk_add_f32 v[2:3], v[244:245], v[248:249] op_sel:[0,1] op_sel_hi:[1,0] neg_lo:[0,1]
	v_pk_add_f32 v[4:5], v[242:243], v[246:247] neg_lo:[0,1] neg_hi:[0,1]
	v_pk_add_f32 v[6:7], v[244:245], v[248:249] op_sel:[0,1] op_sel_hi:[1,0] neg_hi:[0,1]
	s_waitcnt lgkmcnt(8)
	v_pk_mul_f32 v[250:251], v[12:13], v[238:239] op_sel:[1,1] op_sel_hi:[0,1]
	v_pk_fma_f32 v[12:13], v[12:13], v[238:239], v[250:251] op_sel:[0,0,0] op_sel_hi:[1,0,1] neg_hi:[0,0,1]
	v_pk_mul_f32 v[250:251], v[10:11], v[236:237] op_sel:[1,1] op_sel_hi:[0,1]
	v_pk_fma_f32 v[10:11], v[10:11], v[236:237], v[250:251] op_sel:[0,0,0] op_sel_hi:[1,0,1] neg_hi:[0,0,1]
	v_pk_mul_f32 v[250:251], v[14:15], v[240:241] op_sel:[1,1] op_sel_hi:[0,1]
	v_pk_fma_f32 v[14:15], v[14:15], v[240:241], v[250:251] op_sel:[0,0,0] op_sel_hi:[1,0,1] neg_hi:[0,0,1]
	v_pk_add_f32 v[242:243], v[8:9], v[12:13]
	v_pk_add_f32 v[244:245], v[8:9], v[12:13] neg_lo:[0,1] neg_hi:[0,1]
	v_pk_add_f32 v[246:247], v[10:11], v[14:15]
	v_pk_add_f32 v[248:249], v[10:11], v[14:15] neg_lo:[0,1] neg_hi:[0,1]
	v_pk_add_f32 v[8:9], v[242:243], v[246:247]
	v_pk_add_f32 v[10:11], v[244:245], v[248:249] op_sel:[0,1] op_sel_hi:[1,0] neg_lo:[0,1]
	v_pk_add_f32 v[12:13], v[242:243], v[246:247] neg_lo:[0,1] neg_hi:[0,1]
	v_pk_add_f32 v[14:15], v[244:245], v[248:249] op_sel:[0,1] op_sel_hi:[1,0] neg_hi:[0,1]
	s_waitcnt lgkmcnt(4)
; HD float2 cmul(float2 a, float2 b){ return make_float2(a.x*b.x - a.y*b.y, a.x*b.y + a.y*b.x); }
; HD float2 cmulc(float2 a, float2 b){ return make_float2(a.x*b.x + a.y*b.y, a.y*b.x - a.x*b.y); }
; template<bool INV, bool NOTW>
; HD void bf4c(float2* Z, int i0, int i1, int i2, int i3, float2 w1, float2 w2, float2 w3){
;   float2 a0=Z[i0], a1=Z[i1], a2=Z[i2], a3=Z[i3];
;   if (INV && !NOTW){ a1=cmulc(a1,w1); a2=cmulc(a2,w2); a3=cmulc(a3,w3); }
;   float2 s02=make_float2(a0.x+a2.x,a0.y+a2.y), d02=make_float2(a0.x-a2.x,a0.y-a2.y);
;   float2 s13=make_float2(a1.x+a3.x,a1.y+a3.y), d13=make_float2(a1.x-a3.x,a1.y-a3.y);
;   float2 y0=make_float2(s02.x+s13.x,s02.y+s13.y), y2=make_float2(s02.x-s13.x,s02.y-s13.y);
;   float2 ym=make_float2(d02.x+d13.y,d02.y-d13.x);
;   float2 yp=make_float2(d02.x-d13.y,d02.y+d13.x);
;   float2 y1, y3;
;   if (INV){ y1=yp; y3=ym; } else if (NOTW){ y1=ym; y3=yp; } else { y1=cmul(ym,w1); y2=cmul(y2,w2); y3=cmul(yp,w3); }
;   Z[i0]=y0; Z[i1]=y1; Z[i2]=y2; Z[i3]=y3;
; template<bool INV, int LQ, bool BARRIER=true>
; HD void fft_pass(float2* Z, const float2* twA, const float2* twB, int tid){
;     ...
;   } else {
;     int j=tid&(q-1); int base0=((tid>>LQ)<<(LQ+2))+j;
;     float2 w1=make_float2(1.f,0.f), w2=w1, w3=w1;
;     if (LQ>0){ int k=j*tws; w1=cmul(twA[k>>6],twB[k&63]); w2=cmul(w1,w1); w3=cmul(w2,w1); }
;     _Pragma("unroll") for (int i=0;i<8;++i){ int base=base0+i*2048; bf4c<INV,(LQ==0)>(Z,base,base+q,base+2*q,base+3*q,w1,w2,w3); }
;   }
;   if (BARRIER) __syncthreads(); else asm volatile("s_waitcnt lgkmcnt(0)" ::: "memory");
	v_pk_mul_f32 v[250:251], v[20:21], v[238:239] op_sel:[1,1] op_sel_hi:[0,1]
	v_pk_fma_f32 v[20:21], v[20:21], v[238:239], v[250:251] op_sel:[0,0,0] op_sel_hi:[1,0,1] neg_hi:[0,0,1]
	v_pk_mul_f32 v[250:251], v[18:19], v[236:237] op_sel:[1,1] op_sel_hi:[0,1]
	v_pk_fma_f32 v[18:19], v[18:19], v[236:237], v[250:251] op_sel:[0,0,0] op_sel_hi:[1,0,1] neg_hi:[0,0,1]
	v_pk_mul_f32 v[250:251], v[22:23], v[240:241] op_sel:[1,1] op_sel_hi:[0,1]
	v_pk_fma_f32 v[22:23], v[22:23], v[240:241], v[250:251] op_sel:[0,0,0] op_sel_hi:[1,0,1] neg_hi:[0,0,1]
	v_pk_add_f32 v[242:243], v[16:17], v[20:21]
	v_pk_add_f32 v[244:245], v[16:17], v[20:21] neg_lo:[0,1] neg_hi:[0,1]
	v_pk_add_f32 v[246:247], v[18:19], v[22:23]
	v_pk_add_f32 v[248:249], v[18:19], v[22:23] neg_lo:[0,1] neg_hi:[0,1]
	v_pk_add_f32 v[16:17], v[242:243], v[246:247]
	v_pk_add_f32 v[18:19], v[244:245], v[248:249] op_sel:[0,1] op_sel_hi:[1,0] neg_lo:[0,1]
	v_pk_add_f32 v[20:21], v[242:243], v[246:247] neg_lo:[0,1] neg_hi:[0,1]
	v_pk_add_f32 v[22:23], v[244:245], v[248:249] op_sel:[0,1] op_sel_hi:[1,0] neg_hi:[0,1]
	s_waitcnt lgkmcnt(0)
	v_pk_mul_f32 v[250:251], v[28:29], v[238:239] op_sel:[1,1] op_sel_hi:[0,1]
	v_pk_fma_f32 v[28:29], v[28:29], v[238:239], v[250:251] op_sel:[0,0,0] op_sel_hi:[1,0,1] neg_hi:[0,0,1]
	v_pk_mul_f32 v[250:251], v[26:27], v[236:237] op_sel:[1,1] op_sel_hi:[0,1]
	v_pk_fma_f32 v[26:27], v[26:27], v[236:237], v[250:251] op_sel:[0,0,0] op_sel_hi:[1,0,1] neg_hi:[0,0,1]
	v_pk_mul_f32 v[250:251], v[30:31], v[240:241] op_sel:[1,1] op_sel_hi:[0,1]
	v_pk_fma_f32 v[30:31], v[30:31], v[240:241], v[250:251] op_sel:[0,0,0] op_sel_hi:[1,0,1] neg_hi:[0,0,1]
	v_pk_add_f32 v[242:243], v[24:25], v[28:29]
	v_pk_add_f32 v[244:245], v[24:25], v[28:29] neg_lo:[0,1] neg_hi:[0,1]
	v_pk_add_f32 v[246:247], v[26:27], v[30:31]
	v_pk_add_f32 v[248:249], v[26:27], v[30:31] neg_lo:[0,1] neg_hi:[0,1]
	v_pk_add_f32 v[24:25], v[242:243], v[246:247]
	v_pk_add_f32 v[26:27], v[244:245], v[248:249] op_sel:[0,1] op_sel_hi:[1,0] neg_lo:[0,1]
	v_pk_add_f32 v[28:29], v[242:243], v[246:247] neg_lo:[0,1] neg_hi:[0,1]
	v_pk_add_f32 v[30:31], v[244:245], v[248:249] op_sel:[0,1] op_sel_hi:[1,0] neg_hi:[0,1]
	v_pk_mul_f32 v[250:251], v[16:17], v[82:83] op_sel:[1,1] op_sel_hi:[0,1]
	v_pk_fma_f32 v[16:17], v[16:17], v[82:83], v[250:251] op_sel:[0,0,0] op_sel_hi:[1,0,1] neg_hi:[0,0,1]
	v_pk_mul_f32 v[250:251], v[8:9], v[80:81] op_sel:[1,1] op_sel_hi:[0,1]
	v_pk_fma_f32 v[8:9], v[8:9], v[80:81], v[250:251] op_sel:[0,0,0] op_sel_hi:[1,0,1] neg_hi:[0,0,1]
	v_pk_mul_f32 v[250:251], v[24:25], v[84:85] op_sel:[1,1] op_sel_hi:[0,1]
	v_pk_fma_f32 v[24:25], v[24:25], v[84:85], v[250:251] op_sel:[0,0,0] op_sel_hi:[1,0,1] neg_hi:[0,0,1]
	v_pk_add_f32 v[242:243], v[0:1], v[16:17]
	v_pk_add_f32 v[244:245], v[0:1], v[16:17] neg_lo:[0,1] neg_hi:[0,1]
	v_pk_add_f32 v[246:247], v[8:9], v[24:25]
	v_pk_add_f32 v[248:249], v[8:9], v[24:25] neg_lo:[0,1] neg_hi:[0,1]
	v_pk_add_f32 v[0:1], v[242:243], v[246:247]
	ds_write_b64 v227, v[0:1] offset:0
	v_pk_add_f32 v[8:9], v[244:245], v[248:249] op_sel:[0,1] op_sel_hi:[1,0] neg_lo:[0,1]
	ds_write_b64 v227, v[8:9] offset:512
	v_pk_add_f32 v[16:17], v[242:243], v[246:247] neg_lo:[0,1] neg_hi:[0,1]
	ds_write_b64 v227, v[16:17] offset:1024
	v_pk_add_f32 v[24:25], v[244:245], v[248:249] op_sel:[0,1] op_sel_hi:[1,0] neg_hi:[0,1]
	ds_write_b64 v227, v[24:25] offset:1536
	v_pk_mul_f32 v[250:251], v[18:19], v[224:225] op_sel:[1,1] op_sel_hi:[1,0] neg_lo:[0,0] neg_hi:[0,0]
	v_pk_fma_f32 v[18:19], v[18:19], v[224:225], v[250:251] op_sel:[0,0,0] op_sel_hi:[0,1,1] neg_lo:[0,0,1] neg_hi:[0,0,0]
	v_pk_mul_f32 v[250:251], v[18:19], v[82:83] op_sel:[1,1] op_sel_hi:[0,1]
	v_pk_fma_f32 v[18:19], v[18:19], v[82:83], v[250:251] op_sel:[0,0,0] op_sel_hi:[1,0,1] neg_hi:[0,0,1]
	v_pk_mul_f32 v[250:251], v[10:11], v[222:223] op_sel:[1,1] op_sel_hi:[1,0] neg_lo:[0,0] neg_hi:[0,0]
	v_pk_fma_f32 v[10:11], v[10:11], v[222:223], v[250:251] op_sel:[0,0,0] op_sel_hi:[0,1,1] neg_lo:[0,0,1] neg_hi:[0,0,0]
	v_pk_mul_f32 v[250:251], v[10:11], v[80:81] op_sel:[1,1] op_sel_hi:[0,1]
	v_pk_fma_f32 v[10:11], v[10:11], v[80:81], v[250:251] op_sel:[0,0,0] op_sel_hi:[1,0,1] neg_hi:[0,0,1]
	v_pk_mul_f32 v[250:251], v[26:27], v[222:223] op_sel:[1,0] op_sel_hi:[1,1] neg_lo:[0,0] neg_hi:[0,0]
	v_pk_fma_f32 v[26:27], v[26:27], v[222:223], v[250:251] op_sel:[0,1,0] op_sel_hi:[0,0,1] neg_lo:[0,0,1] neg_hi:[0,0,0]
	v_pk_mul_f32 v[250:251], v[26:27], v[84:85] op_sel:[1,1] op_sel_hi:[0,1]
	v_pk_fma_f32 v[26:27], v[26:27], v[84:85], v[250:251] op_sel:[0,0,0] op_sel_hi:[1,0,1] neg_hi:[0,0,1]
	v_pk_add_f32 v[242:243], v[2:3], v[18:19]
	v_pk_add_f32 v[244:245], v[2:3], v[18:19] neg_lo:[0,1] neg_hi:[0,1]
	v_pk_add_f32 v[246:247], v[10:11], v[26:27]
	v_pk_add_f32 v[248:249], v[10:11], v[26:27] neg_lo:[0,1] neg_hi:[0,1]
	v_pk_add_f32 v[2:3], v[242:243], v[246:247]
	ds_write_b64 v227, v[2:3] offset:128
	v_pk_add_f32 v[10:11], v[244:245], v[248:249] op_sel:[0,1] op_sel_hi:[1,0] neg_lo:[0,1]
	ds_write_b64 v227, v[10:11] offset:640
	v_pk_add_f32 v[18:19], v[242:243], v[246:247] neg_lo:[0,1] neg_hi:[0,1]
	ds_write_b64 v227, v[18:19] offset:1152
	v_pk_add_f32 v[26:27], v[244:245], v[248:249] op_sel:[0,1] op_sel_hi:[1,0] neg_hi:[0,1]
	ds_write_b64 v227, v[26:27] offset:1664
	v_pk_add_f32 v[20:21], v[20:21], 0 op_sel:[1,0] op_sel_hi:[0,0] neg_lo:[1,0]
	v_pk_mul_f32 v[250:251], v[20:21], v[82:83] op_sel:[1,1] op_sel_hi:[0,1]
	v_pk_fma_f32 v[20:21], v[20:21], v[82:83], v[250:251] op_sel:[0,0,0] op_sel_hi:[1,0,1] neg_hi:[0,0,1]
	v_pk_mul_f32 v[250:251], v[12:13], v[224:225] op_sel:[1,1] op_sel_hi:[1,0] neg_lo:[0,0] neg_hi:[0,0]
; HD float2 cmul(float2 a, float2 b){ return make_float2(a.x*b.x - a.y*b.y, a.x*b.y + a.y*b.x); }
; HD float2 cmulc(float2 a, float2 b){ return make_float2(a.x*b.x + a.y*b.y, a.y*b.x - a.x*b.y); }
; template<bool INV, bool NOTW>
; HD void bf4c(float2* Z, int i0, int i1, int i2, int i3, float2 w1, float2 w2, float2 w3){
;   float2 a0=Z[i0], a1=Z[i1], a2=Z[i2], a3=Z[i3];
;   if (INV && !NOTW){ a1=cmulc(a1,w1); a2=cmulc(a2,w2); a3=cmulc(a3,w3); }
;   float2 s02=make_float2(a0.x+a2.x,a0.y+a2.y), d02=make_float2(a0.x-a2.x,a0.y-a2.y);
;   float2 s13=make_float2(a1.x+a3.x,a1.y+a3.y), d13=make_float2(a1.x-a3.x,a1.y-a3.y);
;   float2 y0=make_float2(s02.x+s13.x,s02.y+s13.y), y2=make_float2(s02.x-s13.x,s02.y-s13.y);
;   float2 ym=make_float2(d02.x+d13.y,d02.y-d13.x);
;   float2 yp=make_float2(d02.x-d13.y,d02.y+d13.x);
;   float2 y1, y3;
;   if (INV){ y1=yp; y3=ym; } else if (NOTW){ y1=ym; y3=yp; } else { y1=cmul(ym,w1); y2=cmul(y2,w2); y3=cmul(yp,w3); }
;   Z[i0]=y0; Z[i1]=y1; Z[i2]=y2; Z[i3]=y3;
; template<bool INV, int LQ, bool BARRIER=true>
; HD void fft_pass(float2* Z, const float2* twA, const float2* twB, int tid){
;     ...
;     _Pragma("unroll") for (int e=0;e<2;++e){ int j=tid+512*e; int k=j*tws;
;       float2 w1=cmul(twA[k>>6],twB[k&63]), w2=cmul(w1,w1), w3=cmul(w2,w1);
;       _Pragma("unroll") for (int ip=0;ip<4;++ip){ int base=ip*4096+j; bf4c<INV,false>(Z,base,base+q,base+2*q,base+3*q,w1,w2,w3); } }
;   } else {
;     int j=tid&(q-1); int base0=((tid>>LQ)<<(LQ+2))+j;
;     float2 w1=make_float2(1.f,0.f), w2=w1, w3=w1;
;     if (LQ>0){ int k=j*tws; w1=cmul(twA[k>>6],twB[k&63]); w2=cmul(w1,w1); w3=cmul(w2,w1); }
;     _Pragma("unroll") for (int i=0;i<8;++i){ int base=base0+i*2048; bf4c<INV,(LQ==0)>(Z,base,base+q,base+2*q,base+3*q,w1,w2,w3); }
;   }
;   if (BARRIER) __syncthreads(); else asm volatile("s_waitcnt lgkmcnt(0)" ::: "memory");
	v_pk_fma_f32 v[12:13], v[12:13], v[224:225], v[250:251] op_sel:[0,0,0] op_sel_hi:[0,1,1] neg_lo:[0,0,1] neg_hi:[0,0,0]
	v_pk_mul_f32 v[250:251], v[12:13], v[80:81] op_sel:[1,1] op_sel_hi:[0,1]
	v_pk_fma_f32 v[12:13], v[12:13], v[80:81], v[250:251] op_sel:[0,0,0] op_sel_hi:[1,0,1] neg_hi:[0,0,1]
	v_pk_mul_f32 v[250:251], v[28:29], v[224:225] op_sel:[1,1] op_sel_hi:[1,0] neg_lo:[0,0] neg_hi:[0,1]
	v_pk_fma_f32 v[28:29], v[28:29], v[224:225], v[250:251] op_sel:[0,0,0] op_sel_hi:[0,1,1] neg_lo:[0,1,1] neg_hi:[0,0,0]
	v_pk_mul_f32 v[250:251], v[28:29], v[84:85] op_sel:[1,1] op_sel_hi:[0,1]
	v_pk_fma_f32 v[28:29], v[28:29], v[84:85], v[250:251] op_sel:[0,0,0] op_sel_hi:[1,0,1] neg_hi:[0,0,1]
	v_pk_add_f32 v[242:243], v[4:5], v[20:21]
	v_pk_add_f32 v[244:245], v[4:5], v[20:21] neg_lo:[0,1] neg_hi:[0,1]
	v_pk_add_f32 v[246:247], v[12:13], v[28:29]
	v_pk_add_f32 v[248:249], v[12:13], v[28:29] neg_lo:[0,1] neg_hi:[0,1]
	v_pk_add_f32 v[4:5], v[242:243], v[246:247]
	ds_write_b64 v227, v[4:5] offset:256
	v_pk_add_f32 v[12:13], v[244:245], v[248:249] op_sel:[0,1] op_sel_hi:[1,0] neg_lo:[0,1]
	ds_write_b64 v227, v[12:13] offset:768
	v_pk_add_f32 v[20:21], v[242:243], v[246:247] neg_lo:[0,1] neg_hi:[0,1]
	ds_write_b64 v227, v[20:21] offset:1280
	v_pk_add_f32 v[28:29], v[244:245], v[248:249] op_sel:[0,1] op_sel_hi:[1,0] neg_hi:[0,1]
	ds_write_b64 v227, v[28:29] offset:1792
	v_pk_mul_f32 v[250:251], v[22:23], v[224:225] op_sel:[1,1] op_sel_hi:[1,0] neg_lo:[0,0] neg_hi:[0,1]
	v_pk_fma_f32 v[22:23], v[22:23], v[224:225], v[250:251] op_sel:[0,0,0] op_sel_hi:[0,1,1] neg_lo:[0,1,1] neg_hi:[0,0,0]
	v_pk_mul_f32 v[250:251], v[22:23], v[82:83] op_sel:[1,1] op_sel_hi:[0,1]
	v_pk_fma_f32 v[22:23], v[22:23], v[82:83], v[250:251] op_sel:[0,0,0] op_sel_hi:[1,0,1] neg_hi:[0,0,1]
	v_pk_mul_f32 v[250:251], v[14:15], v[222:223] op_sel:[1,0] op_sel_hi:[1,1] neg_lo:[0,0] neg_hi:[0,0]
	v_pk_fma_f32 v[14:15], v[14:15], v[222:223], v[250:251] op_sel:[0,1,0] op_sel_hi:[0,0,1] neg_lo:[0,0,1] neg_hi:[0,0,0]
	v_pk_mul_f32 v[250:251], v[14:15], v[80:81] op_sel:[1,1] op_sel_hi:[0,1]
	v_pk_fma_f32 v[14:15], v[14:15], v[80:81], v[250:251] op_sel:[0,0,0] op_sel_hi:[1,0,1] neg_hi:[0,0,1]
	v_pk_mul_f32 v[250:251], v[30:31], v[222:223] op_sel:[1,1] op_sel_hi:[1,0] neg_lo:[0,1] neg_hi:[0,1]
	v_pk_fma_f32 v[30:31], v[30:31], v[222:223], v[250:251] op_sel:[0,0,0] op_sel_hi:[0,1,1] neg_lo:[0,1,1] neg_hi:[0,1,0]
	v_pk_mul_f32 v[250:251], v[30:31], v[84:85] op_sel:[1,1] op_sel_hi:[0,1]
	v_pk_fma_f32 v[30:31], v[30:31], v[84:85], v[250:251] op_sel:[0,0,0] op_sel_hi:[1,0,1] neg_hi:[0,0,1]
	v_pk_add_f32 v[242:243], v[6:7], v[22:23]
	v_pk_add_f32 v[244:245], v[6:7], v[22:23] neg_lo:[0,1] neg_hi:[0,1]
	v_pk_add_f32 v[246:247], v[14:15], v[30:31]
	v_pk_add_f32 v[248:249], v[14:15], v[30:31] neg_lo:[0,1] neg_hi:[0,1]
	v_pk_add_f32 v[6:7], v[242:243], v[246:247]
	ds_write_b64 v227, v[6:7] offset:384
	v_pk_add_f32 v[14:15], v[244:245], v[248:249] op_sel:[0,1] op_sel_hi:[1,0] neg_lo:[0,1]
	ds_write_b64 v227, v[14:15] offset:896
	v_pk_add_f32 v[22:23], v[242:243], v[246:247] neg_lo:[0,1] neg_hi:[0,1]
	ds_write_b64 v227, v[22:23] offset:1408
	v_pk_add_f32 v[30:31], v[244:245], v[248:249] op_sel:[0,1] op_sel_hi:[1,0] neg_hi:[0,1]
	ds_write_b64 v227, v[30:31] offset:1920
	s_waitcnt lgkmcnt(0)
	s_barrier
	v_and_b32_e32 v8, 255, v154
	v_lshrrev_b32_e32 v9, 4, v8
	v_lshlrev_b32_e32 v9, 3, v9
	v_add_u32_e32 v9, 0x20800, v9
	v_and_b32_e32 v10, 15, v8
	v_lshlrev_b32_e32 v10, 5, v10
	v_add_u32_e32 v10, 0x20a00, v10
	ds_read_b64 v[0:1], v9
	ds_read_b64 v[2:3], v10
	s_waitcnt lgkmcnt(0)
	v_pk_mul_f32 v[250:251], v[0:1], v[2:3] op_sel:[1,1] op_sel_hi:[1,0]
	v_pk_fma_f32 v[80:81], v[0:1], v[2:3], v[250:251] op_sel:[0,0,0] op_sel_hi:[0,1,1] neg_lo:[0,0,1]
	v_pk_mul_f32 v[250:251], v[80:81], v[80:81] op_sel:[1,1] op_sel_hi:[1,0]
	v_pk_fma_f32 v[82:83], v[80:81], v[80:81], v[250:251] op_sel:[0,0,0] op_sel_hi:[0,1,1] neg_lo:[0,0,1]
	v_pk_mul_f32 v[250:251], v[82:83], v[80:81] op_sel:[1,1] op_sel_hi:[1,0]
	v_pk_fma_f32 v[84:85], v[82:83], v[80:81], v[250:251] op_sel:[0,0,0] op_sel_hi:[0,1,1] neg_lo:[0,0,1]
	v_lshrrev_b32_e32 v9, 2, v8
	v_lshlrev_b32_e32 v9, 3, v9
	v_add_u32_e32 v9, 0x20800, v9
	v_and_b32_e32 v10, 3, v8
	v_lshlrev_b32_e32 v10, 7, v10
	v_add_u32_e32 v10, 0x20a00, v10
	ds_read_b64 v[0:1], v9
	ds_read_b64 v[2:3], v10
	s_waitcnt lgkmcnt(0)
	v_pk_mul_f32 v[250:251], v[0:1], v[2:3] op_sel:[1,1] op_sel_hi:[1,0]
	v_pk_fma_f32 v[236:237], v[0:1], v[2:3], v[250:251] op_sel:[0,0,0] op_sel_hi:[0,1,1] neg_lo:[0,0,1]
	v_pk_mul_f32 v[250:251], v[236:237], v[236:237] op_sel:[1,1] op_sel_hi:[1,0]
	v_pk_fma_f32 v[238:239], v[236:237], v[236:237], v[250:251] op_sel:[0,0,0] op_sel_hi:[0,1,1] neg_lo:[0,0,1]
	v_pk_mul_f32 v[250:251], v[238:239], v[236:237] op_sel:[1,1] op_sel_hi:[1,0]
	v_pk_fma_f32 v[240:241], v[238:239], v[236:237], v[250:251] op_sel:[0,0,0] op_sel_hi:[0,1,1] neg_lo:[0,0,1]
	v_lshrrev_b32_e32 v226, 8, v154
	v_lshlrev_b32_e32 v226, 12, v226
	v_and_b32_e32 v227, 255, v154
	v_add_u32_e32 v226, v226, v227
	v_lshlrev_b32_e32 v226, 3, v226
	v_add_u32_e32 v227, 0x10000, v226
	ds_read_b64 v[0:1], v226 offset:0
	ds_read_b64 v[2:3], v226 offset:2048
	ds_read_b64 v[4:5], v226 offset:4096
	ds_read_b64 v[6:7], v226 offset:6144
	ds_read_b64 v[8:9], v226 offset:8192
	ds_read_b64 v[10:11], v226 offset:10240
	ds_read_b64 v[12:13], v226 offset:12288
	ds_read_b64 v[14:15], v226 offset:14336
	ds_read_b64 v[16:17], v226 offset:16384
	ds_read_b64 v[18:19], v226 offset:18432
	ds_read_b64 v[20:21], v226 offset:20480
	ds_read_b64 v[22:23], v226 offset:22528
	ds_read_b64 v[24:25], v226 offset:24576
	ds_read_b64 v[26:27], v226 offset:26624
	ds_read_b64 v[28:29], v226 offset:28672
	ds_read_b64 v[30:31], v226 offset:30720
	s_waitcnt lgkmcnt(12)
; HD float2 cmul(float2 a, float2 b){ return make_float2(a.x*b.x - a.y*b.y, a.x*b.y + a.y*b.x); }
; HD float2 cmulc(float2 a, float2 b){ return make_float2(a.x*b.x + a.y*b.y, a.y*b.x - a.x*b.y); }
; template<bool INV, bool NOTW>
; HD void bf4c(float2* Z, int i0, int i1, int i2, int i3, float2 w1, float2 w2, float2 w3){
;   float2 a0=Z[i0], a1=Z[i1], a2=Z[i2], a3=Z[i3];
;   if (INV && !NOTW){ a1=cmulc(a1,w1); a2=cmulc(a2,w2); a3=cmulc(a3,w3); }
;   float2 s02=make_float2(a0.x+a2.x,a0.y+a2.y), d02=make_float2(a0.x-a2.x,a0.y-a2.y);
;   float2 s13=make_float2(a1.x+a3.x,a1.y+a3.y), d13=make_float2(a1.x-a3.x,a1.y-a3.y);
;   float2 y0=make_float2(s02.x+s13.x,s02.y+s13.y), y2=make_float2(s02.x-s13.x,s02.y-s13.y);
;   float2 ym=make_float2(d02.x+d13.y,d02.y-d13.x);
;   float2 yp=make_float2(d02.x-d13.y,d02.y+d13.x);
;   float2 y1, y3;
;   if (INV){ y1=yp; y3=ym; } else if (NOTW){ y1=ym; y3=yp; } else { y1=cmul(ym,w1); y2=cmul(y2,w2); y3=cmul(yp,w3); }
;   Z[i0]=y0; Z[i1]=y1; Z[i2]=y2; Z[i3]=y3;
; template<bool INV, int LQ, bool BARRIER=true>
; HD void fft_pass(float2* Z, const float2* twA, const float2* twB, int tid){
;     ...
;     _Pragma("unroll") for (int e=0;e<2;++e){ int j=tid+512*e; int k=j*tws;
;       float2 w1=cmul(twA[k>>6],twB[k&63]), w2=cmul(w1,w1), w3=cmul(w2,w1);
;       _Pragma("unroll") for (int ip=0;ip<4;++ip){ int base=ip*4096+j; bf4c<INV,false>(Z,base,base+q,base+2*q,base+3*q,w1,w2,w3); } }
;   } else {
;     int j=tid&(q-1); int base0=((tid>>LQ)<<(LQ+2))+j;
;     float2 w1=make_float2(1.f,0.f), w2=w1, w3=w1;
;     if (LQ>0){ int k=j*tws; w1=cmul(twA[k>>6],twB[k&63]); w2=cmul(w1,w1); w3=cmul(w2,w1); }
;     _Pragma("unroll") for (int i=0;i<8;++i){ int base=base0+i*2048; bf4c<INV,(LQ==0)>(Z,base,base+q,base+2*q,base+3*q,w1,w2,w3); }
;   }
;   if (BARRIER) __syncthreads(); else asm volatile("s_waitcnt lgkmcnt(0)" ::: "memory");
	v_pk_mul_f32 v[250:251], v[4:5], v[238:239] op_sel:[1,1] op_sel_hi:[0,1]
	v_pk_fma_f32 v[4:5], v[4:5], v[238:239], v[250:251] op_sel:[0,0,0] op_sel_hi:[1,0,1] neg_hi:[0,0,1]
	v_pk_mul_f32 v[250:251], v[2:3], v[236:237] op_sel:[1,1] op_sel_hi:[0,1]
	v_pk_fma_f32 v[2:3], v[2:3], v[236:237], v[250:251] op_sel:[0,0,0] op_sel_hi:[1,0,1] neg_hi:[0,0,1]
	v_pk_mul_f32 v[250:251], v[6:7], v[240:241] op_sel:[1,1] op_sel_hi:[0,1]
	v_pk_fma_f32 v[6:7], v[6:7], v[240:241], v[250:251] op_sel:[0,0,0] op_sel_hi:[1,0,1] neg_hi:[0,0,1]
	v_pk_add_f32 v[242:243], v[0:1], v[4:5]
	v_pk_add_f32 v[244:245], v[0:1], v[4:5] neg_lo:[0,1] neg_hi:[0,1]
	v_pk_add_f32 v[246:247], v[2:3], v[6:7]
	v_pk_add_f32 v[248:249], v[2:3], v[6:7] neg_lo:[0,1] neg_hi:[0,1]
	v_pk_add_f32 v[0:1], v[242:243], v[246:247]
	v_pk_add_f32 v[2:3], v[244:245], v[248:249] op_sel:[0,1] op_sel_hi:[1,0] neg_lo:[0,1]
	v_pk_add_f32 v[4:5], v[242:243], v[246:247] neg_lo:[0,1] neg_hi:[0,1]
	v_pk_add_f32 v[6:7], v[244:245], v[248:249] op_sel:[0,1] op_sel_hi:[1,0] neg_hi:[0,1]
	s_waitcnt lgkmcnt(8)
	v_pk_mul_f32 v[250:251], v[12:13], v[238:239] op_sel:[1,1] op_sel_hi:[0,1]
	v_pk_fma_f32 v[12:13], v[12:13], v[238:239], v[250:251] op_sel:[0,0,0] op_sel_hi:[1,0,1] neg_hi:[0,0,1]
	v_pk_mul_f32 v[250:251], v[10:11], v[236:237] op_sel:[1,1] op_sel_hi:[0,1]
	v_pk_fma_f32 v[10:11], v[10:11], v[236:237], v[250:251] op_sel:[0,0,0] op_sel_hi:[1,0,1] neg_hi:[0,0,1]
	v_pk_mul_f32 v[250:251], v[14:15], v[240:241] op_sel:[1,1] op_sel_hi:[0,1]
	v_pk_fma_f32 v[14:15], v[14:15], v[240:241], v[250:251] op_sel:[0,0,0] op_sel_hi:[1,0,1] neg_hi:[0,0,1]
	v_pk_add_f32 v[242:243], v[8:9], v[12:13]
	v_pk_add_f32 v[244:245], v[8:9], v[12:13] neg_lo:[0,1] neg_hi:[0,1]
	v_pk_add_f32 v[246:247], v[10:11], v[14:15]
	v_pk_add_f32 v[248:249], v[10:11], v[14:15] neg_lo:[0,1] neg_hi:[0,1]
	v_pk_add_f32 v[8:9], v[242:243], v[246:247]
	v_pk_add_f32 v[10:11], v[244:245], v[248:249] op_sel:[0,1] op_sel_hi:[1,0] neg_lo:[0,1]
	v_pk_add_f32 v[12:13], v[242:243], v[246:247] neg_lo:[0,1] neg_hi:[0,1]
	v_pk_add_f32 v[14:15], v[244:245], v[248:249] op_sel:[0,1] op_sel_hi:[1,0] neg_hi:[0,1]
	s_waitcnt lgkmcnt(4)
	v_pk_mul_f32 v[250:251], v[20:21], v[238:239] op_sel:[1,1] op_sel_hi:[0,1]
	v_pk_fma_f32 v[20:21], v[20:21], v[238:239], v[250:251] op_sel:[0,0,0] op_sel_hi:[1,0,1] neg_hi:[0,0,1]
	v_pk_mul_f32 v[250:251], v[18:19], v[236:237] op_sel:[1,1] op_sel_hi:[0,1]
	v_pk_fma_f32 v[18:19], v[18:19], v[236:237], v[250:251] op_sel:[0,0,0] op_sel_hi:[1,0,1] neg_hi:[0,0,1]
	v_pk_mul_f32 v[250:251], v[22:23], v[240:241] op_sel:[1,1] op_sel_hi:[0,1]
	v_pk_fma_f32 v[22:23], v[22:23], v[240:241], v[250:251] op_sel:[0,0,0] op_sel_hi:[1,0,1] neg_hi:[0,0,1]
	v_pk_add_f32 v[242:243], v[16:17], v[20:21]
	v_pk_add_f32 v[244:245], v[16:17], v[20:21] neg_lo:[0,1] neg_hi:[0,1]
	v_pk_add_f32 v[246:247], v[18:19], v[22:23]
	v_pk_add_f32 v[248:249], v[18:19], v[22:23] neg_lo:[0,1] neg_hi:[0,1]
	v_pk_add_f32 v[16:17], v[242:243], v[246:247]
	v_pk_add_f32 v[18:19], v[244:245], v[248:249] op_sel:[0,1] op_sel_hi:[1,0] neg_lo:[0,1]
	v_pk_add_f32 v[20:21], v[242:243], v[246:247] neg_lo:[0,1] neg_hi:[0,1]
	v_pk_add_f32 v[22:23], v[244:245], v[248:249] op_sel:[0,1] op_sel_hi:[1,0] neg_hi:[0,1]
	s_waitcnt lgkmcnt(0)
	v_pk_mul_f32 v[250:251], v[28:29], v[238:239] op_sel:[1,1] op_sel_hi:[0,1]
	v_pk_fma_f32 v[28:29], v[28:29], v[238:239], v[250:251] op_sel:[0,0,0] op_sel_hi:[1,0,1] neg_hi:[0,0,1]
	v_pk_mul_f32 v[250:251], v[26:27], v[236:237] op_sel:[1,1] op_sel_hi:[0,1]
	v_pk_fma_f32 v[26:27], v[26:27], v[236:237], v[250:251] op_sel:[0,0,0] op_sel_hi:[1,0,1] neg_hi:[0,0,1]
	v_pk_mul_f32 v[250:251], v[30:31], v[240:241] op_sel:[1,1] op_sel_hi:[0,1]
	v_pk_fma_f32 v[30:31], v[30:31], v[240:241], v[250:251] op_sel:[0,0,0] op_sel_hi:[1,0,1] neg_hi:[0,0,1]
	v_pk_add_f32 v[242:243], v[24:25], v[28:29]
	v_pk_add_f32 v[244:245], v[24:25], v[28:29] neg_lo:[0,1] neg_hi:[0,1]
	v_pk_add_f32 v[246:247], v[26:27], v[30:31]
	v_pk_add_f32 v[248:249], v[26:27], v[30:31] neg_lo:[0,1] neg_hi:[0,1]
	v_pk_add_f32 v[24:25], v[242:243], v[246:247]
	v_pk_add_f32 v[26:27], v[244:245], v[248:249] op_sel:[0,1] op_sel_hi:[1,0] neg_lo:[0,1]
	v_pk_add_f32 v[28:29], v[242:243], v[246:247] neg_lo:[0,1] neg_hi:[0,1]
	v_pk_add_f32 v[30:31], v[244:245], v[248:249] op_sel:[0,1] op_sel_hi:[1,0] neg_hi:[0,1]
	v_pk_mul_f32 v[250:251], v[16:17], v[82:83] op_sel:[1,1] op_sel_hi:[0,1]
	v_pk_fma_f32 v[16:17], v[16:17], v[82:83], v[250:251] op_sel:[0,0,0] op_sel_hi:[1,0,1] neg_hi:[0,0,1]
	v_pk_mul_f32 v[250:251], v[8:9], v[80:81] op_sel:[1,1] op_sel_hi:[0,1]
	v_pk_fma_f32 v[8:9], v[8:9], v[80:81], v[250:251] op_sel:[0,0,0] op_sel_hi:[1,0,1] neg_hi:[0,0,1]
	v_pk_mul_f32 v[250:251], v[24:25], v[84:85] op_sel:[1,1] op_sel_hi:[0,1]
	v_pk_fma_f32 v[24:25], v[24:25], v[84:85], v[250:251] op_sel:[0,0,0] op_sel_hi:[1,0,1] neg_hi:[0,0,1]
	v_pk_add_f32 v[242:243], v[0:1], v[16:17]
	v_pk_add_f32 v[244:245], v[0:1], v[16:17] neg_lo:[0,1] neg_hi:[0,1]
	v_pk_add_f32 v[246:247], v[8:9], v[24:25]
	v_pk_add_f32 v[248:249], v[8:9], v[24:25] neg_lo:[0,1] neg_hi:[0,1]
	v_pk_add_f32 v[0:1], v[242:243], v[246:247]
	ds_write_b64 v226, v[0:1] offset:0
	v_pk_add_f32 v[8:9], v[244:245], v[248:249] op_sel:[0,1] op_sel_hi:[1,0] neg_lo:[0,1]
	ds_write_b64 v226, v[8:9] offset:8192
	v_pk_add_f32 v[16:17], v[242:243], v[246:247] neg_lo:[0,1] neg_hi:[0,1]
	ds_write_b64 v226, v[16:17] offset:16384
	v_pk_add_f32 v[24:25], v[244:245], v[248:249] op_sel:[0,1] op_sel_hi:[1,0] neg_hi:[0,1]
	ds_write_b64 v226, v[24:25] offset:24576
	v_pk_mul_f32 v[250:251], v[18:19], v[224:225] op_sel:[1,1] op_sel_hi:[1,0] neg_lo:[0,0] neg_hi:[0,0]
; HD float2 cmul(float2 a, float2 b){ return make_float2(a.x*b.x - a.y*b.y, a.x*b.y + a.y*b.x); }
; HD float2 cmulc(float2 a, float2 b){ return make_float2(a.x*b.x + a.y*b.y, a.y*b.x - a.x*b.y); }
; template<bool INV, bool NOTW>
; HD void bf4c(float2* Z, int i0, int i1, int i2, int i3, float2 w1, float2 w2, float2 w3){
;   float2 a0=Z[i0], a1=Z[i1], a2=Z[i2], a3=Z[i3];
;   if (INV && !NOTW){ a1=cmulc(a1,w1); a2=cmulc(a2,w2); a3=cmulc(a3,w3); }
;   float2 s02=make_float2(a0.x+a2.x,a0.y+a2.y), d02=make_float2(a0.x-a2.x,a0.y-a2.y);
;   float2 s13=make_float2(a1.x+a3.x,a1.y+a3.y), d13=make_float2(a1.x-a3.x,a1.y-a3.y);
;   float2 y0=make_float2(s02.x+s13.x,s02.y+s13.y), y2=make_float2(s02.x-s13.x,s02.y-s13.y);
;   float2 ym=make_float2(d02.x+d13.y,d02.y-d13.x);
;   float2 yp=make_float2(d02.x-d13.y,d02.y+d13.x);
;   float2 y1, y3;
;   if (INV){ y1=yp; y3=ym; } else if (NOTW){ y1=ym; y3=yp; } else { y1=cmul(ym,w1); y2=cmul(y2,w2); y3=cmul(yp,w3); }
;   Z[i0]=y0; Z[i1]=y1; Z[i2]=y2; Z[i3]=y3;
; template<bool INV, int LQ, bool BARRIER=true>
; HD void fft_pass(float2* Z, const float2* twA, const float2* twB, int tid){
;     ...
;     _Pragma("unroll") for (int e=0;e<2;++e){ int j=tid+512*e; int k=j*tws;
;       float2 w1=cmul(twA[k>>6],twB[k&63]), w2=cmul(w1,w1), w3=cmul(w2,w1);
;       _Pragma("unroll") for (int ip=0;ip<4;++ip){ int base=ip*4096+j; bf4c<INV,false>(Z,base,base+q,base+2*q,base+3*q,w1,w2,w3); } }
;   } else {
;     int j=tid&(q-1); int base0=((tid>>LQ)<<(LQ+2))+j;
;     float2 w1=make_float2(1.f,0.f), w2=w1, w3=w1;
;     if (LQ>0){ int k=j*tws; w1=cmul(twA[k>>6],twB[k&63]); w2=cmul(w1,w1); w3=cmul(w2,w1); }
;     _Pragma("unroll") for (int i=0;i<8;++i){ int base=base0+i*2048; bf4c<INV,(LQ==0)>(Z,base,base+q,base+2*q,base+3*q,w1,w2,w3); }
;   }
;   if (BARRIER) __syncthreads(); else asm volatile("s_waitcnt lgkmcnt(0)" ::: "memory");
	v_pk_fma_f32 v[18:19], v[18:19], v[224:225], v[250:251] op_sel:[0,0,0] op_sel_hi:[0,1,1] neg_lo:[0,0,1] neg_hi:[0,0,0]
	v_pk_mul_f32 v[250:251], v[18:19], v[82:83] op_sel:[1,1] op_sel_hi:[0,1]
	v_pk_fma_f32 v[18:19], v[18:19], v[82:83], v[250:251] op_sel:[0,0,0] op_sel_hi:[1,0,1] neg_hi:[0,0,1]
	v_pk_mul_f32 v[250:251], v[10:11], v[222:223] op_sel:[1,1] op_sel_hi:[1,0] neg_lo:[0,0] neg_hi:[0,0]
	v_pk_fma_f32 v[10:11], v[10:11], v[222:223], v[250:251] op_sel:[0,0,0] op_sel_hi:[0,1,1] neg_lo:[0,0,1] neg_hi:[0,0,0]
	v_pk_mul_f32 v[250:251], v[10:11], v[80:81] op_sel:[1,1] op_sel_hi:[0,1]
	v_pk_fma_f32 v[10:11], v[10:11], v[80:81], v[250:251] op_sel:[0,0,0] op_sel_hi:[1,0,1] neg_hi:[0,0,1]
	v_pk_mul_f32 v[250:251], v[26:27], v[222:223] op_sel:[1,0] op_sel_hi:[1,1] neg_lo:[0,0] neg_hi:[0,0]
	v_pk_fma_f32 v[26:27], v[26:27], v[222:223], v[250:251] op_sel:[0,1,0] op_sel_hi:[0,0,1] neg_lo:[0,0,1] neg_hi:[0,0,0]
	v_pk_mul_f32 v[250:251], v[26:27], v[84:85] op_sel:[1,1] op_sel_hi:[0,1]
	v_pk_fma_f32 v[26:27], v[26:27], v[84:85], v[250:251] op_sel:[0,0,0] op_sel_hi:[1,0,1] neg_hi:[0,0,1]
	v_pk_add_f32 v[242:243], v[2:3], v[18:19]
	v_pk_add_f32 v[244:245], v[2:3], v[18:19] neg_lo:[0,1] neg_hi:[0,1]
	v_pk_add_f32 v[246:247], v[10:11], v[26:27]
	v_pk_add_f32 v[248:249], v[10:11], v[26:27] neg_lo:[0,1] neg_hi:[0,1]
	v_pk_add_f32 v[2:3], v[242:243], v[246:247]
	ds_write_b64 v226, v[2:3] offset:2048
	v_pk_add_f32 v[10:11], v[244:245], v[248:249] op_sel:[0,1] op_sel_hi:[1,0] neg_lo:[0,1]
	ds_write_b64 v226, v[10:11] offset:10240
	v_pk_add_f32 v[18:19], v[242:243], v[246:247] neg_lo:[0,1] neg_hi:[0,1]
	ds_write_b64 v226, v[18:19] offset:18432
	v_pk_add_f32 v[26:27], v[244:245], v[248:249] op_sel:[0,1] op_sel_hi:[1,0] neg_hi:[0,1]
	ds_write_b64 v226, v[26:27] offset:26624
	v_pk_add_f32 v[20:21], v[20:21], 0 op_sel:[1,0] op_sel_hi:[0,0] neg_lo:[1,0]
	v_pk_mul_f32 v[250:251], v[20:21], v[82:83] op_sel:[1,1] op_sel_hi:[0,1]
	v_pk_fma_f32 v[20:21], v[20:21], v[82:83], v[250:251] op_sel:[0,0,0] op_sel_hi:[1,0,1] neg_hi:[0,0,1]
	v_pk_mul_f32 v[250:251], v[12:13], v[224:225] op_sel:[1,1] op_sel_hi:[1,0] neg_lo:[0,0] neg_hi:[0,0]
	v_pk_fma_f32 v[12:13], v[12:13], v[224:225], v[250:251] op_sel:[0,0,0] op_sel_hi:[0,1,1] neg_lo:[0,0,1] neg_hi:[0,0,0]
	v_pk_mul_f32 v[250:251], v[12:13], v[80:81] op_sel:[1,1] op_sel_hi:[0,1]
	v_pk_fma_f32 v[12:13], v[12:13], v[80:81], v[250:251] op_sel:[0,0,0] op_sel_hi:[1,0,1] neg_hi:[0,0,1]
	v_pk_mul_f32 v[250:251], v[28:29], v[224:225] op_sel:[1,1] op_sel_hi:[1,0] neg_lo:[0,0] neg_hi:[0,1]
	v_pk_fma_f32 v[28:29], v[28:29], v[224:225], v[250:251] op_sel:[0,0,0] op_sel_hi:[0,1,1] neg_lo:[0,1,1] neg_hi:[0,0,0]
	v_pk_mul_f32 v[250:251], v[28:29], v[84:85] op_sel:[1,1] op_sel_hi:[0,1]
	v_pk_fma_f32 v[28:29], v[28:29], v[84:85], v[250:251] op_sel:[0,0,0] op_sel_hi:[1,0,1] neg_hi:[0,0,1]
	v_pk_add_f32 v[242:243], v[4:5], v[20:21]
	v_pk_add_f32 v[244:245], v[4:5], v[20:21] neg_lo:[0,1] neg_hi:[0,1]
	v_pk_add_f32 v[246:247], v[12:13], v[28:29]
	v_pk_add_f32 v[248:249], v[12:13], v[28:29] neg_lo:[0,1] neg_hi:[0,1]
	v_pk_add_f32 v[4:5], v[242:243], v[246:247]
	ds_write_b64 v226, v[4:5] offset:4096
	v_pk_add_f32 v[12:13], v[244:245], v[248:249] op_sel:[0,1] op_sel_hi:[1,0] neg_lo:[0,1]
	ds_write_b64 v226, v[12:13] offset:12288
	v_pk_add_f32 v[20:21], v[242:243], v[246:247] neg_lo:[0,1] neg_hi:[0,1]
	ds_write_b64 v226, v[20:21] offset:20480
	v_pk_add_f32 v[28:29], v[244:245], v[248:249] op_sel:[0,1] op_sel_hi:[1,0] neg_hi:[0,1]
	ds_write_b64 v226, v[28:29] offset:28672
	v_pk_mul_f32 v[250:251], v[22:23], v[224:225] op_sel:[1,1] op_sel_hi:[1,0] neg_lo:[0,0] neg_hi:[0,1]
	v_pk_fma_f32 v[22:23], v[22:23], v[224:225], v[250:251] op_sel:[0,0,0] op_sel_hi:[0,1,1] neg_lo:[0,1,1] neg_hi:[0,0,0]
	v_pk_mul_f32 v[250:251], v[22:23], v[82:83] op_sel:[1,1] op_sel_hi:[0,1]
	v_pk_fma_f32 v[22:23], v[22:23], v[82:83], v[250:251] op_sel:[0,0,0] op_sel_hi:[1,0,1] neg_hi:[0,0,1]
	v_pk_mul_f32 v[250:251], v[14:15], v[222:223] op_sel:[1,0] op_sel_hi:[1,1] neg_lo:[0,0] neg_hi:[0,0]
	v_pk_fma_f32 v[14:15], v[14:15], v[222:223], v[250:251] op_sel:[0,1,0] op_sel_hi:[0,0,1] neg_lo:[0,0,1] neg_hi:[0,0,0]
	v_pk_mul_f32 v[250:251], v[14:15], v[80:81] op_sel:[1,1] op_sel_hi:[0,1]
	v_pk_fma_f32 v[14:15], v[14:15], v[80:81], v[250:251] op_sel:[0,0,0] op_sel_hi:[1,0,1] neg_hi:[0,0,1]
	v_pk_mul_f32 v[250:251], v[30:31], v[222:223] op_sel:[1,1] op_sel_hi:[1,0] neg_lo:[0,1] neg_hi:[0,1]
	v_pk_fma_f32 v[30:31], v[30:31], v[222:223], v[250:251] op_sel:[0,0,0] op_sel_hi:[0,1,1] neg_lo:[0,1,1] neg_hi:[0,1,0]
	v_pk_mul_f32 v[250:251], v[30:31], v[84:85] op_sel:[1,1] op_sel_hi:[0,1]
	v_pk_fma_f32 v[30:31], v[30:31], v[84:85], v[250:251] op_sel:[0,0,0] op_sel_hi:[1,0,1] neg_hi:[0,0,1]
	v_pk_add_f32 v[242:243], v[6:7], v[22:23]
	v_pk_add_f32 v[244:245], v[6:7], v[22:23] neg_lo:[0,1] neg_hi:[0,1]
	v_pk_add_f32 v[246:247], v[14:15], v[30:31]
	v_pk_add_f32 v[248:249], v[14:15], v[30:31] neg_lo:[0,1] neg_hi:[0,1]
	v_pk_add_f32 v[6:7], v[242:243], v[246:247]
	ds_write_b64 v226, v[6:7] offset:6144
	v_pk_add_f32 v[14:15], v[244:245], v[248:249] op_sel:[0,1] op_sel_hi:[1,0] neg_lo:[0,1]
	ds_write_b64 v226, v[14:15] offset:14336
	v_pk_add_f32 v[22:23], v[242:243], v[246:247] neg_lo:[0,1] neg_hi:[0,1]
	ds_write_b64 v226, v[22:23] offset:22528
	v_pk_add_f32 v[30:31], v[244:245], v[248:249] op_sel:[0,1] op_sel_hi:[1,0] neg_hi:[0,1]
	ds_write_b64 v226, v[30:31] offset:30720
	ds_read_b64 v[0:1], v227 offset:0
	ds_read_b64 v[2:3], v227 offset:2048
	ds_read_b64 v[4:5], v227 offset:4096
	ds_read_b64 v[6:7], v227 offset:6144
	ds_read_b64 v[8:9], v227 offset:8192
	ds_read_b64 v[10:11], v227 offset:10240
	ds_read_b64 v[12:13], v227 offset:12288
	ds_read_b64 v[14:15], v227 offset:14336
	ds_read_b64 v[16:17], v227 offset:16384
	ds_read_b64 v[18:19], v227 offset:18432
	ds_read_b64 v[20:21], v227 offset:20480
	ds_read_b64 v[22:23], v227 offset:22528
	ds_read_b64 v[24:25], v227 offset:24576
	ds_read_b64 v[26:27], v227 offset:26624
	ds_read_b64 v[28:29], v227 offset:28672
	ds_read_b64 v[30:31], v227 offset:30720
	s_waitcnt lgkmcnt(12)
; HD float2 cmul(float2 a, float2 b){ return make_float2(a.x*b.x - a.y*b.y, a.x*b.y + a.y*b.x); }
; HD float2 cmulc(float2 a, float2 b){ return make_float2(a.x*b.x + a.y*b.y, a.y*b.x - a.x*b.y); }
; template<bool INV, bool NOTW>
; HD void bf4c(float2* Z, int i0, int i1, int i2, int i3, float2 w1, float2 w2, float2 w3){
;   float2 a0=Z[i0], a1=Z[i1], a2=Z[i2], a3=Z[i3];
;   if (INV && !NOTW){ a1=cmulc(a1,w1); a2=cmulc(a2,w2); a3=cmulc(a3,w3); }
;   float2 s02=make_float2(a0.x+a2.x,a0.y+a2.y), d02=make_float2(a0.x-a2.x,a0.y-a2.y);
;   float2 s13=make_float2(a1.x+a3.x,a1.y+a3.y), d13=make_float2(a1.x-a3.x,a1.y-a3.y);
;   float2 y0=make_float2(s02.x+s13.x,s02.y+s13.y), y2=make_float2(s02.x-s13.x,s02.y-s13.y);
;   float2 ym=make_float2(d02.x+d13.y,d02.y-d13.x);
;   float2 yp=make_float2(d02.x-d13.y,d02.y+d13.x);
;   float2 y1, y3;
;   if (INV){ y1=yp; y3=ym; } else if (NOTW){ y1=ym; y3=yp; } else { y1=cmul(ym,w1); y2=cmul(y2,w2); y3=cmul(yp,w3); }
;   Z[i0]=y0; Z[i1]=y1; Z[i2]=y2; Z[i3]=y3;
; template<bool INV, int LQ, bool BARRIER=true>
; HD void fft_pass(float2* Z, const float2* twA, const float2* twB, int tid){
;     ...
;     _Pragma("unroll") for (int e=0;e<2;++e){ int j=tid+512*e; int k=j*tws;
;       float2 w1=cmul(twA[k>>6],twB[k&63]), w2=cmul(w1,w1), w3=cmul(w2,w1);
;       _Pragma("unroll") for (int ip=0;ip<4;++ip){ int base=ip*4096+j; bf4c<INV,false>(Z,base,base+q,base+2*q,base+3*q,w1,w2,w3); } }
;   } else {
;     int j=tid&(q-1); int base0=((tid>>LQ)<<(LQ+2))+j;
;     float2 w1=make_float2(1.f,0.f), w2=w1, w3=w1;
;     if (LQ>0){ int k=j*tws; w1=cmul(twA[k>>6],twB[k&63]); w2=cmul(w1,w1); w3=cmul(w2,w1); }
;     _Pragma("unroll") for (int i=0;i<8;++i){ int base=base0+i*2048; bf4c<INV,(LQ==0)>(Z,base,base+q,base+2*q,base+3*q,w1,w2,w3); }
;   }
;   if (BARRIER) __syncthreads(); else asm volatile("s_waitcnt lgkmcnt(0)" ::: "memory");
	v_pk_mul_f32 v[250:251], v[4:5], v[238:239] op_sel:[1,1] op_sel_hi:[0,1]
	v_pk_fma_f32 v[4:5], v[4:5], v[238:239], v[250:251] op_sel:[0,0,0] op_sel_hi:[1,0,1] neg_hi:[0,0,1]
	v_pk_mul_f32 v[250:251], v[2:3], v[236:237] op_sel:[1,1] op_sel_hi:[0,1]
	v_pk_fma_f32 v[2:3], v[2:3], v[236:237], v[250:251] op_sel:[0,0,0] op_sel_hi:[1,0,1] neg_hi:[0,0,1]
	v_pk_mul_f32 v[250:251], v[6:7], v[240:241] op_sel:[1,1] op_sel_hi:[0,1]
	v_pk_fma_f32 v[6:7], v[6:7], v[240:241], v[250:251] op_sel:[0,0,0] op_sel_hi:[1,0,1] neg_hi:[0,0,1]
	v_pk_add_f32 v[242:243], v[0:1], v[4:5]
	v_pk_add_f32 v[244:245], v[0:1], v[4:5] neg_lo:[0,1] neg_hi:[0,1]
	v_pk_add_f32 v[246:247], v[2:3], v[6:7]
	v_pk_add_f32 v[248:249], v[2:3], v[6:7] neg_lo:[0,1] neg_hi:[0,1]
	v_pk_add_f32 v[0:1], v[242:243], v[246:247]
	v_pk_add_f32 v[2:3], v[244:245], v[248:249] op_sel:[0,1] op_sel_hi:[1,0] neg_lo:[0,1]
	v_pk_add_f32 v[4:5], v[242:243], v[246:247] neg_lo:[0,1] neg_hi:[0,1]
	v_pk_add_f32 v[6:7], v[244:245], v[248:249] op_sel:[0,1] op_sel_hi:[1,0] neg_hi:[0,1]
	s_waitcnt lgkmcnt(8)
	v_pk_mul_f32 v[250:251], v[12:13], v[238:239] op_sel:[1,1] op_sel_hi:[0,1]
	v_pk_fma_f32 v[12:13], v[12:13], v[238:239], v[250:251] op_sel:[0,0,0] op_sel_hi:[1,0,1] neg_hi:[0,0,1]
	v_pk_mul_f32 v[250:251], v[10:11], v[236:237] op_sel:[1,1] op_sel_hi:[0,1]
	v_pk_fma_f32 v[10:11], v[10:11], v[236:237], v[250:251] op_sel:[0,0,0] op_sel_hi:[1,0,1] neg_hi:[0,0,1]
	v_pk_mul_f32 v[250:251], v[14:15], v[240:241] op_sel:[1,1] op_sel_hi:[0,1]
	v_pk_fma_f32 v[14:15], v[14:15], v[240:241], v[250:251] op_sel:[0,0,0] op_sel_hi:[1,0,1] neg_hi:[0,0,1]
	v_pk_add_f32 v[242:243], v[8:9], v[12:13]
	v_pk_add_f32 v[244:245], v[8:9], v[12:13] neg_lo:[0,1] neg_hi:[0,1]
	v_pk_add_f32 v[246:247], v[10:11], v[14:15]
	v_pk_add_f32 v[248:249], v[10:11], v[14:15] neg_lo:[0,1] neg_hi:[0,1]
	v_pk_add_f32 v[8:9], v[242:243], v[246:247]
	v_pk_add_f32 v[10:11], v[244:245], v[248:249] op_sel:[0,1] op_sel_hi:[1,0] neg_lo:[0,1]
	v_pk_add_f32 v[12:13], v[242:243], v[246:247] neg_lo:[0,1] neg_hi:[0,1]
	v_pk_add_f32 v[14:15], v[244:245], v[248:249] op_sel:[0,1] op_sel_hi:[1,0] neg_hi:[0,1]
	s_waitcnt lgkmcnt(4)
	v_pk_mul_f32 v[250:251], v[20:21], v[238:239] op_sel:[1,1] op_sel_hi:[0,1]
	v_pk_fma_f32 v[20:21], v[20:21], v[238:239], v[250:251] op_sel:[0,0,0] op_sel_hi:[1,0,1] neg_hi:[0,0,1]
	v_pk_mul_f32 v[250:251], v[18:19], v[236:237] op_sel:[1,1] op_sel_hi:[0,1]
	v_pk_fma_f32 v[18:19], v[18:19], v[236:237], v[250:251] op_sel:[0,0,0] op_sel_hi:[1,0,1] neg_hi:[0,0,1]
	v_pk_mul_f32 v[250:251], v[22:23], v[240:241] op_sel:[1,1] op_sel_hi:[0,1]
	v_pk_fma_f32 v[22:23], v[22:23], v[240:241], v[250:251] op_sel:[0,0,0] op_sel_hi:[1,0,1] neg_hi:[0,0,1]
	v_pk_add_f32 v[242:243], v[16:17], v[20:21]
	v_pk_add_f32 v[244:245], v[16:17], v[20:21] neg_lo:[0,1] neg_hi:[0,1]
	v_pk_add_f32 v[246:247], v[18:19], v[22:23]
	v_pk_add_f32 v[248:249], v[18:19], v[22:23] neg_lo:[0,1] neg_hi:[0,1]
	v_pk_add_f32 v[16:17], v[242:243], v[246:247]
	v_pk_add_f32 v[18:19], v[244:245], v[248:249] op_sel:[0,1] op_sel_hi:[1,0] neg_lo:[0,1]
	v_pk_add_f32 v[20:21], v[242:243], v[246:247] neg_lo:[0,1] neg_hi:[0,1]
	v_pk_add_f32 v[22:23], v[244:245], v[248:249] op_sel:[0,1] op_sel_hi:[1,0] neg_hi:[0,1]
	s_waitcnt lgkmcnt(0)
	v_pk_mul_f32 v[250:251], v[28:29], v[238:239] op_sel:[1,1] op_sel_hi:[0,1]
	v_pk_fma_f32 v[28:29], v[28:29], v[238:239], v[250:251] op_sel:[0,0,0] op_sel_hi:[1,0,1] neg_hi:[0,0,1]
	v_pk_mul_f32 v[250:251], v[26:27], v[236:237] op_sel:[1,1] op_sel_hi:[0,1]
	v_pk_fma_f32 v[26:27], v[26:27], v[236:237], v[250:251] op_sel:[0,0,0] op_sel_hi:[1,0,1] neg_hi:[0,0,1]
	v_pk_mul_f32 v[250:251], v[30:31], v[240:241] op_sel:[1,1] op_sel_hi:[0,1]
	v_pk_fma_f32 v[30:31], v[30:31], v[240:241], v[250:251] op_sel:[0,0,0] op_sel_hi:[1,0,1] neg_hi:[0,0,1]
	v_pk_add_f32 v[242:243], v[24:25], v[28:29]
	v_pk_add_f32 v[244:245], v[24:25], v[28:29] neg_lo:[0,1] neg_hi:[0,1]
	v_pk_add_f32 v[246:247], v[26:27], v[30:31]
	v_pk_add_f32 v[248:249], v[26:27], v[30:31] neg_lo:[0,1] neg_hi:[0,1]
	v_pk_add_f32 v[24:25], v[242:243], v[246:247]
	v_pk_add_f32 v[26:27], v[244:245], v[248:249] op_sel:[0,1] op_sel_hi:[1,0] neg_lo:[0,1]
	v_pk_add_f32 v[28:29], v[242:243], v[246:247] neg_lo:[0,1] neg_hi:[0,1]
	v_pk_add_f32 v[30:31], v[244:245], v[248:249] op_sel:[0,1] op_sel_hi:[1,0] neg_hi:[0,1]
	v_pk_mul_f32 v[250:251], v[16:17], v[82:83] op_sel:[1,1] op_sel_hi:[0,1]
	v_pk_fma_f32 v[16:17], v[16:17], v[82:83], v[250:251] op_sel:[0,0,0] op_sel_hi:[1,0,1] neg_hi:[0,0,1]
	v_pk_mul_f32 v[250:251], v[8:9], v[80:81] op_sel:[1,1] op_sel_hi:[0,1]
	v_pk_fma_f32 v[8:9], v[8:9], v[80:81], v[250:251] op_sel:[0,0,0] op_sel_hi:[1,0,1] neg_hi:[0,0,1]
	v_pk_mul_f32 v[250:251], v[24:25], v[84:85] op_sel:[1,1] op_sel_hi:[0,1]
	v_pk_fma_f32 v[24:25], v[24:25], v[84:85], v[250:251] op_sel:[0,0,0] op_sel_hi:[1,0,1] neg_hi:[0,0,1]
	v_pk_add_f32 v[242:243], v[0:1], v[16:17]
	v_pk_add_f32 v[244:245], v[0:1], v[16:17] neg_lo:[0,1] neg_hi:[0,1]
	v_pk_add_f32 v[246:247], v[8:9], v[24:25]
	v_pk_add_f32 v[248:249], v[8:9], v[24:25] neg_lo:[0,1] neg_hi:[0,1]
	v_pk_add_f32 v[0:1], v[242:243], v[246:247]
	ds_write_b64 v227, v[0:1] offset:0
	v_pk_add_f32 v[8:9], v[244:245], v[248:249] op_sel:[0,1] op_sel_hi:[1,0] neg_lo:[0,1]
	ds_write_b64 v227, v[8:9] offset:8192
	v_pk_add_f32 v[16:17], v[242:243], v[246:247] neg_lo:[0,1] neg_hi:[0,1]
	ds_write_b64 v227, v[16:17] offset:16384
	v_pk_add_f32 v[24:25], v[244:245], v[248:249] op_sel:[0,1] op_sel_hi:[1,0] neg_hi:[0,1]
	ds_write_b64 v227, v[24:25] offset:24576
	v_pk_mul_f32 v[250:251], v[18:19], v[224:225] op_sel:[1,1] op_sel_hi:[1,0] neg_lo:[0,0] neg_hi:[0,0]
; HD float2 cmul(float2 a, float2 b){ return make_float2(a.x*b.x - a.y*b.y, a.x*b.y + a.y*b.x); }
; HD float2 cmulc(float2 a, float2 b){ return make_float2(a.x*b.x + a.y*b.y, a.y*b.x - a.x*b.y); }
; template<bool INV, bool NOTW>
; HD void bf4c(float2* Z, int i0, int i1, int i2, int i3, float2 w1, float2 w2, float2 w3){
;   float2 a0=Z[i0], a1=Z[i1], a2=Z[i2], a3=Z[i3];
;   if (INV && !NOTW){ a1=cmulc(a1,w1); a2=cmulc(a2,w2); a3=cmulc(a3,w3); }
;   float2 s02=make_float2(a0.x+a2.x,a0.y+a2.y), d02=make_float2(a0.x-a2.x,a0.y-a2.y);
;   float2 s13=make_float2(a1.x+a3.x,a1.y+a3.y), d13=make_float2(a1.x-a3.x,a1.y-a3.y);
;   float2 y0=make_float2(s02.x+s13.x,s02.y+s13.y), y2=make_float2(s02.x-s13.x,s02.y-s13.y);
;   float2 ym=make_float2(d02.x+d13.y,d02.y-d13.x);
;   float2 yp=make_float2(d02.x-d13.y,d02.y+d13.x);
;   float2 y1, y3;
;   if (INV){ y1=yp; y3=ym; } else if (NOTW){ y1=ym; y3=yp; } else { y1=cmul(ym,w1); y2=cmul(y2,w2); y3=cmul(yp,w3); }
;   Z[i0]=y0; Z[i1]=y1; Z[i2]=y2; Z[i3]=y3;
; template<bool INV, int LQ, bool BARRIER=true>
; HD void fft_pass(float2* Z, const float2* twA, const float2* twB, int tid){
;     ...
;     _Pragma("unroll") for (int e=0;e<2;++e){ int j=tid+512*e; int k=j*tws;
;       float2 w1=cmul(twA[k>>6],twB[k&63]), w2=cmul(w1,w1), w3=cmul(w2,w1);
;       _Pragma("unroll") for (int ip=0;ip<4;++ip){ int base=ip*4096+j; bf4c<INV,false>(Z,base,base+q,base+2*q,base+3*q,w1,w2,w3); } }
;   } else {
;     int j=tid&(q-1); int base0=((tid>>LQ)<<(LQ+2))+j;
;     float2 w1=make_float2(1.f,0.f), w2=w1, w3=w1;
;     if (LQ>0){ int k=j*tws; w1=cmul(twA[k>>6],twB[k&63]); w2=cmul(w1,w1); w3=cmul(w2,w1); }
;     _Pragma("unroll") for (int i=0;i<8;++i){ int base=base0+i*2048; bf4c<INV,(LQ==0)>(Z,base,base+q,base+2*q,base+3*q,w1,w2,w3); }
;   }
;   if (BARRIER) __syncthreads(); else asm volatile("s_waitcnt lgkmcnt(0)" ::: "memory");
	v_pk_fma_f32 v[18:19], v[18:19], v[224:225], v[250:251] op_sel:[0,0,0] op_sel_hi:[0,1,1] neg_lo:[0,0,1] neg_hi:[0,0,0]
	v_pk_mul_f32 v[250:251], v[18:19], v[82:83] op_sel:[1,1] op_sel_hi:[0,1]
	v_pk_fma_f32 v[18:19], v[18:19], v[82:83], v[250:251] op_sel:[0,0,0] op_sel_hi:[1,0,1] neg_hi:[0,0,1]
	v_pk_mul_f32 v[250:251], v[10:11], v[222:223] op_sel:[1,1] op_sel_hi:[1,0] neg_lo:[0,0] neg_hi:[0,0]
	v_pk_fma_f32 v[10:11], v[10:11], v[222:223], v[250:251] op_sel:[0,0,0] op_sel_hi:[0,1,1] neg_lo:[0,0,1] neg_hi:[0,0,0]
	v_pk_mul_f32 v[250:251], v[10:11], v[80:81] op_sel:[1,1] op_sel_hi:[0,1]
	v_pk_fma_f32 v[10:11], v[10:11], v[80:81], v[250:251] op_sel:[0,0,0] op_sel_hi:[1,0,1] neg_hi:[0,0,1]
	v_pk_mul_f32 v[250:251], v[26:27], v[222:223] op_sel:[1,0] op_sel_hi:[1,1] neg_lo:[0,0] neg_hi:[0,0]
	v_pk_fma_f32 v[26:27], v[26:27], v[222:223], v[250:251] op_sel:[0,1,0] op_sel_hi:[0,0,1] neg_lo:[0,0,1] neg_hi:[0,0,0]
	v_pk_mul_f32 v[250:251], v[26:27], v[84:85] op_sel:[1,1] op_sel_hi:[0,1]
	v_pk_fma_f32 v[26:27], v[26:27], v[84:85], v[250:251] op_sel:[0,0,0] op_sel_hi:[1,0,1] neg_hi:[0,0,1]
	v_pk_add_f32 v[242:243], v[2:3], v[18:19]
	v_pk_add_f32 v[244:245], v[2:3], v[18:19] neg_lo:[0,1] neg_hi:[0,1]
	v_pk_add_f32 v[246:247], v[10:11], v[26:27]
	v_pk_add_f32 v[248:249], v[10:11], v[26:27] neg_lo:[0,1] neg_hi:[0,1]
	v_pk_add_f32 v[2:3], v[242:243], v[246:247]
	ds_write_b64 v227, v[2:3] offset:2048
	v_pk_add_f32 v[10:11], v[244:245], v[248:249] op_sel:[0,1] op_sel_hi:[1,0] neg_lo:[0,1]
	ds_write_b64 v227, v[10:11] offset:10240
	v_pk_add_f32 v[18:19], v[242:243], v[246:247] neg_lo:[0,1] neg_hi:[0,1]
	ds_write_b64 v227, v[18:19] offset:18432
	v_pk_add_f32 v[26:27], v[244:245], v[248:249] op_sel:[0,1] op_sel_hi:[1,0] neg_hi:[0,1]
	ds_write_b64 v227, v[26:27] offset:26624
	v_pk_add_f32 v[20:21], v[20:21], 0 op_sel:[1,0] op_sel_hi:[0,0] neg_lo:[1,0]
	v_pk_mul_f32 v[250:251], v[20:21], v[82:83] op_sel:[1,1] op_sel_hi:[0,1]
	v_pk_fma_f32 v[20:21], v[20:21], v[82:83], v[250:251] op_sel:[0,0,0] op_sel_hi:[1,0,1] neg_hi:[0,0,1]
	v_pk_mul_f32 v[250:251], v[12:13], v[224:225] op_sel:[1,1] op_sel_hi:[1,0] neg_lo:[0,0] neg_hi:[0,0]
	v_pk_fma_f32 v[12:13], v[12:13], v[224:225], v[250:251] op_sel:[0,0,0] op_sel_hi:[0,1,1] neg_lo:[0,0,1] neg_hi:[0,0,0]
	v_pk_mul_f32 v[250:251], v[12:13], v[80:81] op_sel:[1,1] op_sel_hi:[0,1]
	v_pk_fma_f32 v[12:13], v[12:13], v[80:81], v[250:251] op_sel:[0,0,0] op_sel_hi:[1,0,1] neg_hi:[0,0,1]
	v_pk_mul_f32 v[250:251], v[28:29], v[224:225] op_sel:[1,1] op_sel_hi:[1,0] neg_lo:[0,0] neg_hi:[0,1]
	v_pk_fma_f32 v[28:29], v[28:29], v[224:225], v[250:251] op_sel:[0,0,0] op_sel_hi:[0,1,1] neg_lo:[0,1,1] neg_hi:[0,0,0]
	v_pk_mul_f32 v[250:251], v[28:29], v[84:85] op_sel:[1,1] op_sel_hi:[0,1]
	v_pk_fma_f32 v[28:29], v[28:29], v[84:85], v[250:251] op_sel:[0,0,0] op_sel_hi:[1,0,1] neg_hi:[0,0,1]
	v_pk_add_f32 v[242:243], v[4:5], v[20:21]
	v_pk_add_f32 v[244:245], v[4:5], v[20:21] neg_lo:[0,1] neg_hi:[0,1]
	v_pk_add_f32 v[246:247], v[12:13], v[28:29]
	v_pk_add_f32 v[248:249], v[12:13], v[28:29] neg_lo:[0,1] neg_hi:[0,1]
	v_pk_add_f32 v[4:5], v[242:243], v[246:247]
	ds_write_b64 v227, v[4:5] offset:4096
	v_pk_add_f32 v[12:13], v[244:245], v[248:249] op_sel:[0,1] op_sel_hi:[1,0] neg_lo:[0,1]
	ds_write_b64 v227, v[12:13] offset:12288
	v_pk_add_f32 v[20:21], v[242:243], v[246:247] neg_lo:[0,1] neg_hi:[0,1]
	ds_write_b64 v227, v[20:21] offset:20480
	v_pk_add_f32 v[28:29], v[244:245], v[248:249] op_sel:[0,1] op_sel_hi:[1,0] neg_hi:[0,1]
	ds_write_b64 v227, v[28:29] offset:28672
	v_pk_mul_f32 v[250:251], v[22:23], v[224:225] op_sel:[1,1] op_sel_hi:[1,0] neg_lo:[0,0] neg_hi:[0,1]
	v_pk_fma_f32 v[22:23], v[22:23], v[224:225], v[250:251] op_sel:[0,0,0] op_sel_hi:[0,1,1] neg_lo:[0,1,1] neg_hi:[0,0,0]
	v_pk_mul_f32 v[250:251], v[22:23], v[82:83] op_sel:[1,1] op_sel_hi:[0,1]
	v_pk_fma_f32 v[22:23], v[22:23], v[82:83], v[250:251] op_sel:[0,0,0] op_sel_hi:[1,0,1] neg_hi:[0,0,1]
	v_pk_mul_f32 v[250:251], v[14:15], v[222:223] op_sel:[1,0] op_sel_hi:[1,1] neg_lo:[0,0] neg_hi:[0,0]
	v_pk_fma_f32 v[14:15], v[14:15], v[222:223], v[250:251] op_sel:[0,1,0] op_sel_hi:[0,0,1] neg_lo:[0,0,1] neg_hi:[0,0,0]
	v_pk_mul_f32 v[250:251], v[14:15], v[80:81] op_sel:[1,1] op_sel_hi:[0,1]
	v_pk_fma_f32 v[14:15], v[14:15], v[80:81], v[250:251] op_sel:[0,0,0] op_sel_hi:[1,0,1] neg_hi:[0,0,1]
	v_pk_mul_f32 v[250:251], v[30:31], v[222:223] op_sel:[1,1] op_sel_hi:[1,0] neg_lo:[0,1] neg_hi:[0,1]
	v_pk_fma_f32 v[30:31], v[30:31], v[222:223], v[250:251] op_sel:[0,0,0] op_sel_hi:[0,1,1] neg_lo:[0,1,1] neg_hi:[0,1,0]
	v_pk_mul_f32 v[250:251], v[30:31], v[84:85] op_sel:[1,1] op_sel_hi:[0,1]
	v_pk_fma_f32 v[30:31], v[30:31], v[84:85], v[250:251] op_sel:[0,0,0] op_sel_hi:[1,0,1] neg_hi:[0,0,1]
	v_pk_add_f32 v[242:243], v[6:7], v[22:23]
	v_pk_add_f32 v[244:245], v[6:7], v[22:23] neg_lo:[0,1] neg_hi:[0,1]
	v_pk_add_f32 v[246:247], v[14:15], v[30:31]
	v_pk_add_f32 v[248:249], v[14:15], v[30:31] neg_lo:[0,1] neg_hi:[0,1]
	v_pk_add_f32 v[6:7], v[242:243], v[246:247]
	ds_write_b64 v227, v[6:7] offset:6144
	v_pk_add_f32 v[14:15], v[244:245], v[248:249] op_sel:[0,1] op_sel_hi:[1,0] neg_lo:[0,1]
	ds_write_b64 v227, v[14:15] offset:14336
	v_pk_add_f32 v[22:23], v[242:243], v[246:247] neg_lo:[0,1] neg_hi:[0,1]
	ds_write_b64 v227, v[22:23] offset:22528
	v_pk_add_f32 v[30:31], v[244:245], v[248:249] op_sel:[0,1] op_sel_hi:[1,0] neg_hi:[0,1]
	ds_write_b64 v227, v[30:31] offset:30720
	s_waitcnt lgkmcnt(0)
	s_barrier
	s_mov_b64 s[12:13], -1
	s_and_b64 vcc, exec, s[50:51]
	s_cbranch_vccz .LBB0_1340
; __device__ __forceinline__ float bf2f(u16 h){ return __uint_as_float(((unsigned)h)<<16); }
; HD float2 cmul(float2 a, float2 b){ return make_float2(a.x*b.x - a.y*b.y, a.x*b.y + a.y*b.x); }
; HD float2 cmulc(float2 a, float2 b){ return make_float2(a.x*b.x + a.y*b.y, a.y*b.x - a.x*b.y); }
; HD void inv12_half(const float2* Z, const float2* twA, const float2* twB, int t, float2& x0, float2& x1){
;   float2 w1=cmul(twA[t>>6],twB[t&63]), w2=cmul(w1,w1), w3=cmul(w2,w1);
;   float2 b0=Z[t], b1=cmulc(Z[t+4096],w1), b2=cmulc(Z[t+8192],w2), b3=cmulc(Z[t+12288],w3);
;   float2 s02=make_float2(b0.x+b2.x,b0.y+b2.y), d02=make_float2(b0.x-b2.x,b0.y-b2.y);
;   float2 s13=make_float2(b1.x+b3.x,b1.y+b3.y), d13=make_float2(b1.x-b3.x,b1.y-b3.y);
;   x0=make_float2(s02.x+s13.x,s02.y+s13.y);
;   x1=make_float2(d02.x-d13.y,d02.y+d13.x);
; __device__ __forceinline__ void phase_hyena(KP kp_, int hf){ asm volatile("" : "+s"(kp_)); const Params p=load_params(kp_);
;     ...
;           _Pragma("unroll 4") for (int i=0;i<8;++i){ int tb=tq+512*i; float2 xr[2]; inv12_half(Z,twA,twB,tb,xr[0],xr[1]);
;             _Pragma("unroll") for (int hh=0;hh<2;++hh){ int t=tb+hh*4096;
;               float x0=hconv3(r2,t,wb0,wb1,wb2,bb_), x1=hconv3(r2+8192,t,wb0,wb1,wb2,bb_);
;               float2 y=xr[hh]; y.x*=(1.f/16384.f); y.y*=(1.f/16384.f); float2 z1=Zs[t];
;               float o0=x0*(y.x+z1.x*bias1)*bf2f(rz[t]); float o1=x1*(y.y+z1.y*bias1)*bf2f(rz[8192+t]);
;               ybT[(size_t)c*16384+t]=f2bf(o0); ybT[(size_t)c*16384+8192+t]=f2bf(o1); } }
	v_lshlrev_b32_e32 v0, 1, v86
	v_add_u32_e32 v1, 0x1000, v0
	v_add_u32_e32 v2, 0x2000, v0
	v_add_u32_e32 v4, 0x3000, v0
	v_lshlrev_b32_e32 v5, 3, v86
	v_mov_b32_e32 v8, v5
	v_add_u32_e32 v9, 0x10000, v5
	v_lshrrev_b32_e32 v7, 6, v86
	v_lshl_add_u32 v7, v7, 3, s88
	v_and_b32_e32 v108, 63, v86
	v_lshl_add_u32 v108, v108, 3, s91
	ds_read_b64 v[10:11], v108
	s_add_u32 s12, s72, 0x4000
	s_addc_u32 s13, s73, 0
	s_add_u32 s50, s80, 0x8000
	s_addc_u32 s51, s81, 0
	v_mov_b32_e32 v107, 0
	global_load_ushort v228, v0, s[96:97] offset:0
	global_load_ushort v230, v0, s[74:75] offset:0
	global_load_ushort v232, v0, s[72:73] offset:0
	global_load_ushort v234, v0, s[12:13] offset:0
	global_load_ushort v229, v2, s[96:97] offset:0
	global_load_ushort v231, v2, s[74:75] offset:0
	global_load_ushort v233, v2, s[72:73] offset:0
	global_load_ushort v235, v2, s[12:13] offset:0
	v_mov_b32_e32 v6, v5
	global_load_dwordx2 v[236:237], v6, s[80:81]
	global_load_dwordx2 v[238:239], v6, s[50:51]
	ds_read_b64 v[12:13], v7 offset:0
	ds_read_b64 v[14:15], v8 offset:0
	ds_read_b64 v[16:17], v8 offset:32768
	ds_read_b64 v[18:19], v9 offset:0
	ds_read_b64 v[20:21], v9 offset:32768
	global_load_ushort v240, v0, s[96:97] offset:1024
	global_load_ushort v242, v0, s[74:75] offset:1024
	global_load_ushort v244, v0, s[72:73] offset:1024
	global_load_ushort v246, v0, s[12:13] offset:1024
	global_load_ushort v241, v2, s[96:97] offset:1024
	global_load_ushort v243, v2, s[74:75] offset:1024
	global_load_ushort v245, v2, s[72:73] offset:1024
	global_load_ushort v247, v2, s[12:13] offset:1024
	v_add_u32_e32 v6, 0x1000, v5
	global_load_dwordx2 v[248:249], v6, s[80:81]
	global_load_dwordx2 v[250:251], v6, s[50:51]
	ds_read_b64 v[58:59], v7 offset:64
	ds_read_b64 v[60:61], v8 offset:4096
	ds_read_b64 v[62:63], v8 offset:36864
	ds_read_b64 v[64:65], v9 offset:4096
	ds_read_b64 v[66:67], v9 offset:36864
	s_waitcnt lgkmcnt(5)
	v_pk_mul_f32 v[222:223], v[12:13], v[10:11] op_sel:[1,1] op_sel_hi:[1,0]
	v_pk_fma_f32 v[22:23], v[12:13], v[10:11], v[222:223] op_sel:[0,0,0] op_sel_hi:[0,1,1] neg_lo:[0,0,1]
	v_pk_mul_f32 v[222:223], v[22:23], v[22:23] op_sel:[1,1] op_sel_hi:[1,0]
	v_pk_fma_f32 v[24:25], v[22:23], v[22:23], v[222:223] op_sel:[0,0,0] op_sel_hi:[0,1,1] neg_lo:[0,0,1]
	v_pk_mul_f32 v[222:223], v[24:25], v[22:23] op_sel:[1,1] op_sel_hi:[1,0]
	v_pk_fma_f32 v[26:27], v[24:25], v[22:23], v[222:223] op_sel:[0,0,0] op_sel_hi:[0,1,1] neg_lo:[0,0,1]
	v_pk_mul_f32 v[222:223], v[16:17], v[22:23] op_sel:[1,1] op_sel_hi:[0,1]
	v_pk_fma_f32 v[28:29], v[16:17], v[22:23], v[222:223] op_sel:[0,0,0] op_sel_hi:[1,0,1] neg_hi:[0,0,1]
	v_pk_mul_f32 v[222:223], v[18:19], v[24:25] op_sel:[1,1] op_sel_hi:[0,1]
	v_pk_fma_f32 v[30:31], v[18:19], v[24:25], v[222:223] op_sel:[0,0,0] op_sel_hi:[1,0,1] neg_hi:[0,0,1]
	v_pk_mul_f32 v[222:223], v[20:21], v[26:27] op_sel:[1,1] op_sel_hi:[0,1]
	v_pk_fma_f32 v[68:69], v[20:21], v[26:27], v[222:223] op_sel:[0,0,0] op_sel_hi:[1,0,1] neg_hi:[0,0,1]
	v_pk_add_f32 v[70:71], v[14:15], v[30:31]
	v_pk_add_f32 v[72:73], v[14:15], v[30:31] neg_lo:[0,1] neg_hi:[0,1]
	v_pk_add_f32 v[74:75], v[28:29], v[68:69]
	v_pk_add_f32 v[80:81], v[28:29], v[68:69] neg_lo:[0,1] neg_hi:[0,1]
	v_pk_add_f32 v[82:83], v[70:71], v[74:75]
	v_pk_add_f32 v[84:85], v[72:73], v[80:81] op_sel:[0,1] op_sel_hi:[1,0] neg_lo:[0,1]
	s_waitcnt vmcnt(10)
	v_lshlrev_b32_e32 v224, 16, v228
	v_mov_b32_e32 v225, 0
	v_mov_b32_e32 v226, 0
	v_mov_b32_dpp v225, v224 wave_shr:1 row_mask:0xf bank_mask:0xf
	v_mov_b32_dpp v226, v224 wave_shl:1 row_mask:0xf bank_mask:0xf
	v_mul_f32_e32 v227, v88, v224
	v_fmac_f32_e32 v227, v87, v225
	v_fmac_f32_e32 v227, v89, v226
	v_add_f32_e32 v94, v90, v227
	v_lshlrev_b32_e32 v224, 16, v230
	v_mov_b32_e32 v225, 0
	v_mov_b32_e32 v226, 0
	v_mov_b32_dpp v225, v224 wave_shr:1 row_mask:0xf bank_mask:0xf
	v_mov_b32_dpp v226, v224 wave_shl:1 row_mask:0xf bank_mask:0xf
	v_mul_f32_e32 v227, v88, v224
	v_fmac_f32_e32 v227, v87, v225
	v_fmac_f32_e32 v227, v89, v226
	v_add_f32_e32 v97, v90, v227
	v_lshlrev_b32_e32 v224, 16, v229
	v_mov_b32_e32 v225, 0
	v_mov_b32_e32 v226, 0
	v_mov_b32_dpp v225, v224 wave_shr:1 row_mask:0xf bank_mask:0xf
	v_mov_b32_dpp v226, v224 wave_shl:1 row_mask:0xf bank_mask:0xf
	v_mul_f32_e32 v227, v88, v224
	v_fmac_f32_e32 v227, v87, v225
	v_fmac_f32_e32 v227, v89, v226
	v_add_f32_e32 v98, v90, v227
	v_lshlrev_b32_e32 v224, 16, v231
	v_mov_b32_e32 v225, 0
	v_mov_b32_e32 v226, 0
	v_mov_b32_dpp v225, v224 wave_shr:1 row_mask:0xf bank_mask:0xf
	v_mov_b32_dpp v226, v224 wave_shl:1 row_mask:0xf bank_mask:0xf
	v_mul_f32_e32 v227, v88, v224
	v_fmac_f32_e32 v227, v87, v225
	v_fmac_f32_e32 v227, v89, v226
	v_add_f32_e32 v100, v90, v227
	v_mul_f32_e32 v108, v91, v236
	v_fmac_f32_e32 v108, 0x38800000, v82
	v_mul_f32_e32 v108, v94, v108
	v_lshlrev_b32_e32 v109, 16, v232
	v_mul_f32_e32 v108, v108, v109
	v_cvt_pk_bf16_f32 v224, v108, v108
	v_mul_f32_e32 v108, v91, v237
	v_fmac_f32_e32 v108, 0x38800000, v83
	v_mul_f32_e32 v108, v108, v97
	v_lshlrev_b32_e32 v109, 16, v234
	v_mul_f32_e32 v108, v108, v109
	v_cvt_pk_bf16_f32 v225, v108, v108
	v_add_u32_e32 v106, 0x0, v0
	v_lshl_add_u64 v[104:105], v[54:55], 0, v[106:107]
	global_store_short v[104:105], v224, off
	v_lshl_add_u64 v[104:105], v[56:57], 0, v[106:107]
	global_store_short v[104:105], v225, off
	v_mul_f32_e32 v108, v91, v238
	v_fmac_f32_e32 v108, 0x38800000, v84
	v_mul_f32_e32 v108, v98, v108
	v_lshlrev_b32_e32 v109, 16, v233
	v_mul_f32_e32 v108, v108, v109
	v_cvt_pk_bf16_f32 v224, v108, v108
	v_mul_f32_e32 v108, v91, v239
	v_fmac_f32_e32 v108, 0x38800000, v85
	v_mul_f32_e32 v108, v108, v100
	v_lshlrev_b32_e32 v109, 16, v235
	v_mul_f32_e32 v108, v108, v109
	v_cvt_pk_bf16_f32 v225, v108, v108
	v_add_u32_e32 v106, 0x0, v2
	v_lshl_add_u64 v[104:105], v[54:55], 0, v[106:107]
	global_store_short v[104:105], v224, off
	v_lshl_add_u64 v[104:105], v[56:57], 0, v[106:107]
	global_store_short v[104:105], v225, off
	global_load_ushort v228, v0, s[96:97] offset:2048
	global_load_ushort v230, v0, s[74:75] offset:2048
	global_load_ushort v232, v0, s[72:73] offset:2048
	global_load_ushort v234, v0, s[12:13] offset:2048
	global_load_ushort v229, v2, s[96:97] offset:2048
	global_load_ushort v231, v2, s[74:75] offset:2048
	global_load_ushort v233, v2, s[72:73] offset:2048
	global_load_ushort v235, v2, s[12:13] offset:2048
	v_add_u32_e32 v6, 0x2000, v5
	global_load_dwordx2 v[236:237], v6, s[80:81]
	global_load_dwordx2 v[238:239], v6, s[50:51]
	ds_read_b64 v[12:13], v7 offset:128
	ds_read_b64 v[14:15], v8 offset:8192
	ds_read_b64 v[16:17], v8 offset:40960
	ds_read_b64 v[18:19], v9 offset:8192
	ds_read_b64 v[20:21], v9 offset:40960
	s_waitcnt lgkmcnt(5)
; __device__ __forceinline__ float bf2f(u16 h){ return __uint_as_float(((unsigned)h)<<16); }
; HD float2 cmul(float2 a, float2 b){ return make_float2(a.x*b.x - a.y*b.y, a.x*b.y + a.y*b.x); }
; HD float2 cmulc(float2 a, float2 b){ return make_float2(a.x*b.x + a.y*b.y, a.y*b.x - a.x*b.y); }
; HD void inv12_half(const float2* Z, const float2* twA, const float2* twB, int t, float2& x0, float2& x1){
;   float2 w1=cmul(twA[t>>6],twB[t&63]), w2=cmul(w1,w1), w3=cmul(w2,w1);
;   float2 b0=Z[t], b1=cmulc(Z[t+4096],w1), b2=cmulc(Z[t+8192],w2), b3=cmulc(Z[t+12288],w3);
;   float2 s02=make_float2(b0.x+b2.x,b0.y+b2.y), d02=make_float2(b0.x-b2.x,b0.y-b2.y);
;   float2 s13=make_float2(b1.x+b3.x,b1.y+b3.y), d13=make_float2(b1.x-b3.x,b1.y-b3.y);
;   x0=make_float2(s02.x+s13.x,s02.y+s13.y);
;   x1=make_float2(d02.x-d13.y,d02.y+d13.x);
; __device__ __forceinline__ void phase_hyena(KP kp_, int hf){ asm volatile("" : "+s"(kp_)); const Params p=load_params(kp_);
;     ...
;           _Pragma("unroll 4") for (int i=0;i<8;++i){ int tb=tq+512*i; float2 xr[2]; inv12_half(Z,twA,twB,tb,xr[0],xr[1]);
;             _Pragma("unroll") for (int hh=0;hh<2;++hh){ int t=tb+hh*4096;
;               float x0=hconv3(r2,t,wb0,wb1,wb2,bb_), x1=hconv3(r2+8192,t,wb0,wb1,wb2,bb_);
;               float2 y=xr[hh]; y.x*=(1.f/16384.f); y.y*=(1.f/16384.f); float2 z1=Zs[t];
;               float o0=x0*(y.x+z1.x*bias1)*bf2f(rz[t]); float o1=x1*(y.y+z1.y*bias1)*bf2f(rz[8192+t]);
;               ybT[(size_t)c*16384+t]=f2bf(o0); ybT[(size_t)c*16384+8192+t]=f2bf(o1); } }
	v_pk_mul_f32 v[222:223], v[58:59], v[10:11] op_sel:[1,1] op_sel_hi:[1,0]
	v_pk_fma_f32 v[22:23], v[58:59], v[10:11], v[222:223] op_sel:[0,0,0] op_sel_hi:[0,1,1] neg_lo:[0,0,1]
	v_pk_mul_f32 v[222:223], v[22:23], v[22:23] op_sel:[1,1] op_sel_hi:[1,0]
	v_pk_fma_f32 v[24:25], v[22:23], v[22:23], v[222:223] op_sel:[0,0,0] op_sel_hi:[0,1,1] neg_lo:[0,0,1]
	v_pk_mul_f32 v[222:223], v[24:25], v[22:23] op_sel:[1,1] op_sel_hi:[1,0]
	v_pk_fma_f32 v[26:27], v[24:25], v[22:23], v[222:223] op_sel:[0,0,0] op_sel_hi:[0,1,1] neg_lo:[0,0,1]
	v_pk_mul_f32 v[222:223], v[62:63], v[22:23] op_sel:[1,1] op_sel_hi:[0,1]
	v_pk_fma_f32 v[28:29], v[62:63], v[22:23], v[222:223] op_sel:[0,0,0] op_sel_hi:[1,0,1] neg_hi:[0,0,1]
	v_pk_mul_f32 v[222:223], v[64:65], v[24:25] op_sel:[1,1] op_sel_hi:[0,1]
	v_pk_fma_f32 v[30:31], v[64:65], v[24:25], v[222:223] op_sel:[0,0,0] op_sel_hi:[1,0,1] neg_hi:[0,0,1]
	v_pk_mul_f32 v[222:223], v[66:67], v[26:27] op_sel:[1,1] op_sel_hi:[0,1]
	v_pk_fma_f32 v[68:69], v[66:67], v[26:27], v[222:223] op_sel:[0,0,0] op_sel_hi:[1,0,1] neg_hi:[0,0,1]
	v_pk_add_f32 v[70:71], v[60:61], v[30:31]
	v_pk_add_f32 v[72:73], v[60:61], v[30:31] neg_lo:[0,1] neg_hi:[0,1]
	v_pk_add_f32 v[74:75], v[28:29], v[68:69]
	v_pk_add_f32 v[80:81], v[28:29], v[68:69] neg_lo:[0,1] neg_hi:[0,1]
	v_pk_add_f32 v[82:83], v[70:71], v[74:75]
	v_pk_add_f32 v[84:85], v[72:73], v[80:81] op_sel:[0,1] op_sel_hi:[1,0] neg_lo:[0,1]
	s_waitcnt vmcnt(14)
	v_lshlrev_b32_e32 v224, 16, v240
	v_mov_b32_e32 v225, 0
	v_mov_b32_e32 v226, 0
	v_mov_b32_dpp v225, v224 wave_shr:1 row_mask:0xf bank_mask:0xf
	v_mov_b32_dpp v226, v224 wave_shl:1 row_mask:0xf bank_mask:0xf
	v_mul_f32_e32 v227, v88, v224
	v_fmac_f32_e32 v227, v87, v225
	v_fmac_f32_e32 v227, v89, v226
	v_add_f32_e32 v94, v90, v227
	v_lshlrev_b32_e32 v224, 16, v242
	v_mov_b32_e32 v225, 0
	v_mov_b32_e32 v226, 0
	v_mov_b32_dpp v225, v224 wave_shr:1 row_mask:0xf bank_mask:0xf
	v_mov_b32_dpp v226, v224 wave_shl:1 row_mask:0xf bank_mask:0xf
	v_mul_f32_e32 v227, v88, v224
	v_fmac_f32_e32 v227, v87, v225
	v_fmac_f32_e32 v227, v89, v226
	v_add_f32_e32 v97, v90, v227
	v_lshlrev_b32_e32 v224, 16, v241
	v_mov_b32_e32 v225, 0
	v_mov_b32_e32 v226, 0
	v_mov_b32_dpp v225, v224 wave_shr:1 row_mask:0xf bank_mask:0xf
	v_mov_b32_dpp v226, v224 wave_shl:1 row_mask:0xf bank_mask:0xf
	v_mul_f32_e32 v227, v88, v224
	v_fmac_f32_e32 v227, v87, v225
	v_fmac_f32_e32 v227, v89, v226
	v_add_f32_e32 v98, v90, v227
	v_lshlrev_b32_e32 v224, 16, v243
	v_mov_b32_e32 v225, 0
	v_mov_b32_e32 v226, 0
	v_mov_b32_dpp v225, v224 wave_shr:1 row_mask:0xf bank_mask:0xf
	v_mov_b32_dpp v226, v224 wave_shl:1 row_mask:0xf bank_mask:0xf
	v_mul_f32_e32 v227, v88, v224
	v_fmac_f32_e32 v227, v87, v225
	v_fmac_f32_e32 v227, v89, v226
	v_add_f32_e32 v100, v90, v227
	v_mul_f32_e32 v108, v91, v248
	v_fmac_f32_e32 v108, 0x38800000, v82
	v_mul_f32_e32 v108, v94, v108
	v_lshlrev_b32_e32 v109, 16, v244
	v_mul_f32_e32 v108, v108, v109
	v_cvt_pk_bf16_f32 v224, v108, v108
	v_mul_f32_e32 v108, v91, v249
	v_fmac_f32_e32 v108, 0x38800000, v83
	v_mul_f32_e32 v108, v108, v97
	v_lshlrev_b32_e32 v109, 16, v246
	v_mul_f32_e32 v108, v108, v109
	v_cvt_pk_bf16_f32 v225, v108, v108
	v_add_u32_e32 v106, 0x400, v0
	v_lshl_add_u64 v[104:105], v[54:55], 0, v[106:107]
	global_store_short v[104:105], v224, off
	v_lshl_add_u64 v[104:105], v[56:57], 0, v[106:107]
	global_store_short v[104:105], v225, off
	v_mul_f32_e32 v108, v91, v250
	v_fmac_f32_e32 v108, 0x38800000, v84
	v_mul_f32_e32 v108, v98, v108
	v_lshlrev_b32_e32 v109, 16, v245
	v_mul_f32_e32 v108, v108, v109
	v_cvt_pk_bf16_f32 v224, v108, v108
	v_mul_f32_e32 v108, v91, v251
	v_fmac_f32_e32 v108, 0x38800000, v85
	v_mul_f32_e32 v108, v108, v100
	v_lshlrev_b32_e32 v109, 16, v247
	v_mul_f32_e32 v108, v108, v109
	v_cvt_pk_bf16_f32 v225, v108, v108
	v_add_u32_e32 v106, 0x400, v2
	v_lshl_add_u64 v[104:105], v[54:55], 0, v[106:107]
	global_store_short v[104:105], v224, off
	v_lshl_add_u64 v[104:105], v[56:57], 0, v[106:107]
	global_store_short v[104:105], v225, off
	global_load_ushort v240, v0, s[96:97] offset:3072
	global_load_ushort v242, v0, s[74:75] offset:3072
	global_load_ushort v244, v0, s[72:73] offset:3072
	global_load_ushort v246, v0, s[12:13] offset:3072
	global_load_ushort v241, v2, s[96:97] offset:3072
	global_load_ushort v243, v2, s[74:75] offset:3072
	global_load_ushort v245, v2, s[72:73] offset:3072
	global_load_ushort v247, v2, s[12:13] offset:3072
	v_add_u32_e32 v6, 0x3000, v5
	global_load_dwordx2 v[248:249], v6, s[80:81]
	global_load_dwordx2 v[250:251], v6, s[50:51]
	ds_read_b64 v[58:59], v7 offset:192
	ds_read_b64 v[60:61], v8 offset:12288
	ds_read_b64 v[62:63], v8 offset:45056
	ds_read_b64 v[64:65], v9 offset:12288
	ds_read_b64 v[66:67], v9 offset:45056
	s_waitcnt lgkmcnt(5)
	v_pk_mul_f32 v[222:223], v[12:13], v[10:11] op_sel:[1,1] op_sel_hi:[1,0]
	v_pk_fma_f32 v[22:23], v[12:13], v[10:11], v[222:223] op_sel:[0,0,0] op_sel_hi:[0,1,1] neg_lo:[0,0,1]
	v_pk_mul_f32 v[222:223], v[22:23], v[22:23] op_sel:[1,1] op_sel_hi:[1,0]
	v_pk_fma_f32 v[24:25], v[22:23], v[22:23], v[222:223] op_sel:[0,0,0] op_sel_hi:[0,1,1] neg_lo:[0,0,1]
	v_pk_mul_f32 v[222:223], v[24:25], v[22:23] op_sel:[1,1] op_sel_hi:[1,0]
	v_pk_fma_f32 v[26:27], v[24:25], v[22:23], v[222:223] op_sel:[0,0,0] op_sel_hi:[0,1,1] neg_lo:[0,0,1]
	v_pk_mul_f32 v[222:223], v[16:17], v[22:23] op_sel:[1,1] op_sel_hi:[0,1]
	v_pk_fma_f32 v[28:29], v[16:17], v[22:23], v[222:223] op_sel:[0,0,0] op_sel_hi:[1,0,1] neg_hi:[0,0,1]
	v_pk_mul_f32 v[222:223], v[18:19], v[24:25] op_sel:[1,1] op_sel_hi:[0,1]
	v_pk_fma_f32 v[30:31], v[18:19], v[24:25], v[222:223] op_sel:[0,0,0] op_sel_hi:[1,0,1] neg_hi:[0,0,1]
	v_pk_mul_f32 v[222:223], v[20:21], v[26:27] op_sel:[1,1] op_sel_hi:[0,1]
	v_pk_fma_f32 v[68:69], v[20:21], v[26:27], v[222:223] op_sel:[0,0,0] op_sel_hi:[1,0,1] neg_hi:[0,0,1]
	v_pk_add_f32 v[70:71], v[14:15], v[30:31]
	v_pk_add_f32 v[72:73], v[14:15], v[30:31] neg_lo:[0,1] neg_hi:[0,1]
	v_pk_add_f32 v[74:75], v[28:29], v[68:69]
	v_pk_add_f32 v[80:81], v[28:29], v[68:69] neg_lo:[0,1] neg_hi:[0,1]
	v_pk_add_f32 v[82:83], v[70:71], v[74:75]
	v_pk_add_f32 v[84:85], v[72:73], v[80:81] op_sel:[0,1] op_sel_hi:[1,0] neg_lo:[0,1]
	s_waitcnt vmcnt(14)
; __device__ __forceinline__ float bf2f(u16 h){ return __uint_as_float(((unsigned)h)<<16); }
; __device__ __forceinline__ float hconv3(const u16* __restrict__ row, int t, float w0, float w1, float w2, float bias){
;   float m = bf2f(row[t]);
;   int mi=__float_as_int(m);
;   float l=__int_as_float(__builtin_amdgcn_update_dpp(0, mi, 0x138, 0xf, 0xf, false));
;   float r=__int_as_float(__builtin_amdgcn_update_dpp(0, mi, 0x130, 0xf, 0xf, false));
;   return w0*l+w1*m+w2*r+bias;
; }
; __device__ __forceinline__ void phase_hyena(KP kp_, int hf){ asm volatile("" : "+s"(kp_)); const Params p=load_params(kp_);
;     ...
;           _Pragma("unroll 4") for (int i=0;i<8;++i){ int tb=tq+512*i; float2 xr[2]; inv12_half(Z,twA,twB,tb,xr[0],xr[1]);
;             _Pragma("unroll") for (int hh=0;hh<2;++hh){ int t=tb+hh*4096;
;               float x0=hconv3(r2,t,wb0,wb1,wb2,bb_), x1=hconv3(r2+8192,t,wb0,wb1,wb2,bb_);
;               float2 y=xr[hh]; y.x*=(1.f/16384.f); y.y*=(1.f/16384.f); float2 z1=Zs[t];
;               float o0=x0*(y.x+z1.x*bias1)*bf2f(rz[t]); float o1=x1*(y.y+z1.y*bias1)*bf2f(rz[8192+t]);
;               ybT[(size_t)c*16384+t]=f2bf(o0); ybT[(size_t)c*16384+8192+t]=f2bf(o1); } }
	v_lshlrev_b32_e32 v224, 16, v228
	v_mov_b32_e32 v225, 0
	v_mov_b32_e32 v226, 0
	v_mov_b32_dpp v225, v224 wave_shr:1 row_mask:0xf bank_mask:0xf
	v_mov_b32_dpp v226, v224 wave_shl:1 row_mask:0xf bank_mask:0xf
	v_mul_f32_e32 v227, v88, v224
	v_fmac_f32_e32 v227, v87, v225
	v_fmac_f32_e32 v227, v89, v226
	v_add_f32_e32 v94, v90, v227
	v_lshlrev_b32_e32 v224, 16, v230
	v_mov_b32_e32 v225, 0
	v_mov_b32_e32 v226, 0
	v_mov_b32_dpp v225, v224 wave_shr:1 row_mask:0xf bank_mask:0xf
	v_mov_b32_dpp v226, v224 wave_shl:1 row_mask:0xf bank_mask:0xf
	v_mul_f32_e32 v227, v88, v224
	v_fmac_f32_e32 v227, v87, v225
	v_fmac_f32_e32 v227, v89, v226
	v_add_f32_e32 v97, v90, v227
	v_lshlrev_b32_e32 v224, 16, v229
	v_mov_b32_e32 v225, 0
	v_mov_b32_e32 v226, 0
	v_mov_b32_dpp v225, v224 wave_shr:1 row_mask:0xf bank_mask:0xf
	v_mov_b32_dpp v226, v224 wave_shl:1 row_mask:0xf bank_mask:0xf
	v_mul_f32_e32 v227, v88, v224
	v_fmac_f32_e32 v227, v87, v225
	v_fmac_f32_e32 v227, v89, v226
	v_add_f32_e32 v98, v90, v227
	v_lshlrev_b32_e32 v224, 16, v231
	v_mov_b32_e32 v225, 0
	v_mov_b32_e32 v226, 0
	v_mov_b32_dpp v225, v224 wave_shr:1 row_mask:0xf bank_mask:0xf
	v_mov_b32_dpp v226, v224 wave_shl:1 row_mask:0xf bank_mask:0xf
	v_mul_f32_e32 v227, v88, v224
	v_fmac_f32_e32 v227, v87, v225
	v_fmac_f32_e32 v227, v89, v226
	v_add_f32_e32 v100, v90, v227
	v_mul_f32_e32 v108, v91, v236
	v_fmac_f32_e32 v108, 0x38800000, v82
	v_mul_f32_e32 v108, v94, v108
	v_lshlrev_b32_e32 v109, 16, v232
	v_mul_f32_e32 v108, v108, v109
	v_cvt_pk_bf16_f32 v224, v108, v108
	v_mul_f32_e32 v108, v91, v237
	v_fmac_f32_e32 v108, 0x38800000, v83
	v_mul_f32_e32 v108, v108, v97
	v_lshlrev_b32_e32 v109, 16, v234
	v_mul_f32_e32 v108, v108, v109
	v_cvt_pk_bf16_f32 v225, v108, v108
	v_add_u32_e32 v106, 0x800, v0
	v_lshl_add_u64 v[104:105], v[54:55], 0, v[106:107]
	global_store_short v[104:105], v224, off
	v_lshl_add_u64 v[104:105], v[56:57], 0, v[106:107]
	global_store_short v[104:105], v225, off
	v_mul_f32_e32 v108, v91, v238
	v_fmac_f32_e32 v108, 0x38800000, v84
	v_mul_f32_e32 v108, v98, v108
	v_lshlrev_b32_e32 v109, 16, v233
	v_mul_f32_e32 v108, v108, v109
	v_cvt_pk_bf16_f32 v224, v108, v108
	v_mul_f32_e32 v108, v91, v239
	v_fmac_f32_e32 v108, 0x38800000, v85
	v_mul_f32_e32 v108, v108, v100
	v_lshlrev_b32_e32 v109, 16, v235
	v_mul_f32_e32 v108, v108, v109
	v_cvt_pk_bf16_f32 v225, v108, v108
	v_add_u32_e32 v106, 0x800, v2
	v_lshl_add_u64 v[104:105], v[54:55], 0, v[106:107]
	global_store_short v[104:105], v224, off
	v_lshl_add_u64 v[104:105], v[56:57], 0, v[106:107]
	global_store_short v[104:105], v225, off
	global_load_ushort v228, v1, s[96:97] offset:0
	global_load_ushort v230, v1, s[74:75] offset:0
	global_load_ushort v232, v1, s[72:73] offset:0
	global_load_ushort v234, v1, s[12:13] offset:0
	global_load_ushort v229, v4, s[96:97] offset:0
	global_load_ushort v231, v4, s[74:75] offset:0
	global_load_ushort v233, v4, s[72:73] offset:0
	global_load_ushort v235, v4, s[12:13] offset:0
	v_add_u32_e32 v6, 0x4000, v5
	global_load_dwordx2 v[236:237], v6, s[80:81]
	global_load_dwordx2 v[238:239], v6, s[50:51]
	ds_read_b64 v[12:13], v7 offset:256
	ds_read_b64 v[14:15], v8 offset:16384
	ds_read_b64 v[16:17], v8 offset:49152
	ds_read_b64 v[18:19], v9 offset:16384
	ds_read_b64 v[20:21], v9 offset:49152
	s_waitcnt lgkmcnt(5)
	v_pk_mul_f32 v[222:223], v[58:59], v[10:11] op_sel:[1,1] op_sel_hi:[1,0]
	v_pk_fma_f32 v[22:23], v[58:59], v[10:11], v[222:223] op_sel:[0,0,0] op_sel_hi:[0,1,1] neg_lo:[0,0,1]
	v_pk_mul_f32 v[222:223], v[22:23], v[22:23] op_sel:[1,1] op_sel_hi:[1,0]
	v_pk_fma_f32 v[24:25], v[22:23], v[22:23], v[222:223] op_sel:[0,0,0] op_sel_hi:[0,1,1] neg_lo:[0,0,1]
	v_pk_mul_f32 v[222:223], v[24:25], v[22:23] op_sel:[1,1] op_sel_hi:[1,0]
	v_pk_fma_f32 v[26:27], v[24:25], v[22:23], v[222:223] op_sel:[0,0,0] op_sel_hi:[0,1,1] neg_lo:[0,0,1]
	v_pk_mul_f32 v[222:223], v[62:63], v[22:23] op_sel:[1,1] op_sel_hi:[0,1]
	v_pk_fma_f32 v[28:29], v[62:63], v[22:23], v[222:223] op_sel:[0,0,0] op_sel_hi:[1,0,1] neg_hi:[0,0,1]
	v_pk_mul_f32 v[222:223], v[64:65], v[24:25] op_sel:[1,1] op_sel_hi:[0,1]
	v_pk_fma_f32 v[30:31], v[64:65], v[24:25], v[222:223] op_sel:[0,0,0] op_sel_hi:[1,0,1] neg_hi:[0,0,1]
	v_pk_mul_f32 v[222:223], v[66:67], v[26:27] op_sel:[1,1] op_sel_hi:[0,1]
	v_pk_fma_f32 v[68:69], v[66:67], v[26:27], v[222:223] op_sel:[0,0,0] op_sel_hi:[1,0,1] neg_hi:[0,0,1]
	v_pk_add_f32 v[70:71], v[60:61], v[30:31]
	v_pk_add_f32 v[72:73], v[60:61], v[30:31] neg_lo:[0,1] neg_hi:[0,1]
	v_pk_add_f32 v[74:75], v[28:29], v[68:69]
	v_pk_add_f32 v[80:81], v[28:29], v[68:69] neg_lo:[0,1] neg_hi:[0,1]
	v_pk_add_f32 v[82:83], v[70:71], v[74:75]
	v_pk_add_f32 v[84:85], v[72:73], v[80:81] op_sel:[0,1] op_sel_hi:[1,0] neg_lo:[0,1]
	s_waitcnt vmcnt(14)
; __device__ __forceinline__ float bf2f(u16 h){ return __uint_as_float(((unsigned)h)<<16); }
; __device__ __forceinline__ float hconv3(const u16* __restrict__ row, int t, float w0, float w1, float w2, float bias){
;   float m = bf2f(row[t]);
;   int mi=__float_as_int(m);
;   float l=__int_as_float(__builtin_amdgcn_update_dpp(0, mi, 0x138, 0xf, 0xf, false));
;   float r=__int_as_float(__builtin_amdgcn_update_dpp(0, mi, 0x130, 0xf, 0xf, false));
;   return w0*l+w1*m+w2*r+bias;
; }
; __device__ __forceinline__ void phase_hyena(KP kp_, int hf){ asm volatile("" : "+s"(kp_)); const Params p=load_params(kp_);
;     ...
;           _Pragma("unroll 4") for (int i=0;i<8;++i){ int tb=tq+512*i; float2 xr[2]; inv12_half(Z,twA,twB,tb,xr[0],xr[1]);
;             _Pragma("unroll") for (int hh=0;hh<2;++hh){ int t=tb+hh*4096;
;               float x0=hconv3(r2,t,wb0,wb1,wb2,bb_), x1=hconv3(r2+8192,t,wb0,wb1,wb2,bb_);
;               float2 y=xr[hh]; y.x*=(1.f/16384.f); y.y*=(1.f/16384.f); float2 z1=Zs[t];
;               float o0=x0*(y.x+z1.x*bias1)*bf2f(rz[t]); float o1=x1*(y.y+z1.y*bias1)*bf2f(rz[8192+t]);
;               ybT[(size_t)c*16384+t]=f2bf(o0); ybT[(size_t)c*16384+8192+t]=f2bf(o1); } }
	v_lshlrev_b32_e32 v224, 16, v240
	v_mov_b32_e32 v225, 0
	v_mov_b32_e32 v226, 0
	v_mov_b32_dpp v225, v224 wave_shr:1 row_mask:0xf bank_mask:0xf
	v_mov_b32_dpp v226, v224 wave_shl:1 row_mask:0xf bank_mask:0xf
	v_mul_f32_e32 v227, v88, v224
	v_fmac_f32_e32 v227, v87, v225
	v_fmac_f32_e32 v227, v89, v226
	v_add_f32_e32 v94, v90, v227
	v_lshlrev_b32_e32 v224, 16, v242
	v_mov_b32_e32 v225, 0
	v_mov_b32_e32 v226, 0
	v_mov_b32_dpp v225, v224 wave_shr:1 row_mask:0xf bank_mask:0xf
	v_mov_b32_dpp v226, v224 wave_shl:1 row_mask:0xf bank_mask:0xf
	v_mul_f32_e32 v227, v88, v224
	v_fmac_f32_e32 v227, v87, v225
	v_fmac_f32_e32 v227, v89, v226
	v_add_f32_e32 v97, v90, v227
	v_lshlrev_b32_e32 v224, 16, v241
	v_mov_b32_e32 v225, 0
	v_mov_b32_e32 v226, 0
	v_mov_b32_dpp v225, v224 wave_shr:1 row_mask:0xf bank_mask:0xf
	v_mov_b32_dpp v226, v224 wave_shl:1 row_mask:0xf bank_mask:0xf
	v_mul_f32_e32 v227, v88, v224
	v_fmac_f32_e32 v227, v87, v225
	v_fmac_f32_e32 v227, v89, v226
	v_add_f32_e32 v98, v90, v227
	v_lshlrev_b32_e32 v224, 16, v243
	v_mov_b32_e32 v225, 0
	v_mov_b32_e32 v226, 0
	v_mov_b32_dpp v225, v224 wave_shr:1 row_mask:0xf bank_mask:0xf
	v_mov_b32_dpp v226, v224 wave_shl:1 row_mask:0xf bank_mask:0xf
	v_mul_f32_e32 v227, v88, v224
	v_fmac_f32_e32 v227, v87, v225
	v_fmac_f32_e32 v227, v89, v226
	v_add_f32_e32 v100, v90, v227
	v_mul_f32_e32 v108, v91, v248
	v_fmac_f32_e32 v108, 0x38800000, v82
	v_mul_f32_e32 v108, v94, v108
	v_lshlrev_b32_e32 v109, 16, v244
	v_mul_f32_e32 v108, v108, v109
	v_cvt_pk_bf16_f32 v224, v108, v108
	v_mul_f32_e32 v108, v91, v249
	v_fmac_f32_e32 v108, 0x38800000, v83
	v_mul_f32_e32 v108, v108, v97
	v_lshlrev_b32_e32 v109, 16, v246
	v_mul_f32_e32 v108, v108, v109
	v_cvt_pk_bf16_f32 v225, v108, v108
	v_add_u32_e32 v106, 0xc00, v0
	v_lshl_add_u64 v[104:105], v[54:55], 0, v[106:107]
	global_store_short v[104:105], v224, off
	v_lshl_add_u64 v[104:105], v[56:57], 0, v[106:107]
	global_store_short v[104:105], v225, off
	v_mul_f32_e32 v108, v91, v250
	v_fmac_f32_e32 v108, 0x38800000, v84
	v_mul_f32_e32 v108, v98, v108
	v_lshlrev_b32_e32 v109, 16, v245
	v_mul_f32_e32 v108, v108, v109
	v_cvt_pk_bf16_f32 v224, v108, v108
	v_mul_f32_e32 v108, v91, v251
	v_fmac_f32_e32 v108, 0x38800000, v85
	v_mul_f32_e32 v108, v108, v100
	v_lshlrev_b32_e32 v109, 16, v247
	v_mul_f32_e32 v108, v108, v109
	v_cvt_pk_bf16_f32 v225, v108, v108
	v_add_u32_e32 v106, 0xc00, v2
	v_lshl_add_u64 v[104:105], v[54:55], 0, v[106:107]
	global_store_short v[104:105], v224, off
	v_lshl_add_u64 v[104:105], v[56:57], 0, v[106:107]
	global_store_short v[104:105], v225, off
	global_load_ushort v240, v1, s[96:97] offset:1024
	global_load_ushort v242, v1, s[74:75] offset:1024
	global_load_ushort v244, v1, s[72:73] offset:1024
	global_load_ushort v246, v1, s[12:13] offset:1024
	global_load_ushort v241, v4, s[96:97] offset:1024
	global_load_ushort v243, v4, s[74:75] offset:1024
	global_load_ushort v245, v4, s[72:73] offset:1024
	global_load_ushort v247, v4, s[12:13] offset:1024
	v_add_u32_e32 v6, 0x5000, v5
	global_load_dwordx2 v[248:249], v6, s[80:81]
	global_load_dwordx2 v[250:251], v6, s[50:51]
	ds_read_b64 v[58:59], v7 offset:320
	ds_read_b64 v[60:61], v8 offset:20480
	ds_read_b64 v[62:63], v8 offset:53248
	ds_read_b64 v[64:65], v9 offset:20480
	ds_read_b64 v[66:67], v9 offset:53248
	s_waitcnt lgkmcnt(5)
	v_pk_mul_f32 v[222:223], v[12:13], v[10:11] op_sel:[1,1] op_sel_hi:[1,0]
	v_pk_fma_f32 v[22:23], v[12:13], v[10:11], v[222:223] op_sel:[0,0,0] op_sel_hi:[0,1,1] neg_lo:[0,0,1]
	v_pk_mul_f32 v[222:223], v[22:23], v[22:23] op_sel:[1,1] op_sel_hi:[1,0]
	v_pk_fma_f32 v[24:25], v[22:23], v[22:23], v[222:223] op_sel:[0,0,0] op_sel_hi:[0,1,1] neg_lo:[0,0,1]
	v_pk_mul_f32 v[222:223], v[24:25], v[22:23] op_sel:[1,1] op_sel_hi:[1,0]
	v_pk_fma_f32 v[26:27], v[24:25], v[22:23], v[222:223] op_sel:[0,0,0] op_sel_hi:[0,1,1] neg_lo:[0,0,1]
	v_pk_mul_f32 v[222:223], v[16:17], v[22:23] op_sel:[1,1] op_sel_hi:[0,1]
	v_pk_fma_f32 v[28:29], v[16:17], v[22:23], v[222:223] op_sel:[0,0,0] op_sel_hi:[1,0,1] neg_hi:[0,0,1]
	v_pk_mul_f32 v[222:223], v[18:19], v[24:25] op_sel:[1,1] op_sel_hi:[0,1]
	v_pk_fma_f32 v[30:31], v[18:19], v[24:25], v[222:223] op_sel:[0,0,0] op_sel_hi:[1,0,1] neg_hi:[0,0,1]
	v_pk_mul_f32 v[222:223], v[20:21], v[26:27] op_sel:[1,1] op_sel_hi:[0,1]
	v_pk_fma_f32 v[68:69], v[20:21], v[26:27], v[222:223] op_sel:[0,0,0] op_sel_hi:[1,0,1] neg_hi:[0,0,1]
	v_pk_add_f32 v[70:71], v[14:15], v[30:31]
	v_pk_add_f32 v[72:73], v[14:15], v[30:31] neg_lo:[0,1] neg_hi:[0,1]
	v_pk_add_f32 v[74:75], v[28:29], v[68:69]
	v_pk_add_f32 v[80:81], v[28:29], v[68:69] neg_lo:[0,1] neg_hi:[0,1]
	v_pk_add_f32 v[82:83], v[70:71], v[74:75]
	v_pk_add_f32 v[84:85], v[72:73], v[80:81] op_sel:[0,1] op_sel_hi:[1,0] neg_lo:[0,1]
	s_waitcnt vmcnt(14)
; __device__ __forceinline__ float bf2f(u16 h){ return __uint_as_float(((unsigned)h)<<16); }
; __device__ __forceinline__ float hconv3(const u16* __restrict__ row, int t, float w0, float w1, float w2, float bias){
;   float m = bf2f(row[t]);
;   int mi=__float_as_int(m);
;   float l=__int_as_float(__builtin_amdgcn_update_dpp(0, mi, 0x138, 0xf, 0xf, false));
;   float r=__int_as_float(__builtin_amdgcn_update_dpp(0, mi, 0x130, 0xf, 0xf, false));
;   return w0*l+w1*m+w2*r+bias;
; }
; __device__ __forceinline__ void phase_hyena(KP kp_, int hf){ asm volatile("" : "+s"(kp_)); const Params p=load_params(kp_);
;     ...
;           _Pragma("unroll 4") for (int i=0;i<8;++i){ int tb=tq+512*i; float2 xr[2]; inv12_half(Z,twA,twB,tb,xr[0],xr[1]);
;             _Pragma("unroll") for (int hh=0;hh<2;++hh){ int t=tb+hh*4096;
;               float x0=hconv3(r2,t,wb0,wb1,wb2,bb_), x1=hconv3(r2+8192,t,wb0,wb1,wb2,bb_);
;               float2 y=xr[hh]; y.x*=(1.f/16384.f); y.y*=(1.f/16384.f); float2 z1=Zs[t];
;               float o0=x0*(y.x+z1.x*bias1)*bf2f(rz[t]); float o1=x1*(y.y+z1.y*bias1)*bf2f(rz[8192+t]);
;               ybT[(size_t)c*16384+t]=f2bf(o0); ybT[(size_t)c*16384+8192+t]=f2bf(o1); } }
	v_lshlrev_b32_e32 v224, 16, v228
	v_mov_b32_e32 v225, 0
	v_mov_b32_e32 v226, 0
	v_mov_b32_dpp v225, v224 wave_shr:1 row_mask:0xf bank_mask:0xf
	v_mov_b32_dpp v226, v224 wave_shl:1 row_mask:0xf bank_mask:0xf
	v_mul_f32_e32 v227, v88, v224
	v_fmac_f32_e32 v227, v87, v225
	v_fmac_f32_e32 v227, v89, v226
	v_add_f32_e32 v94, v90, v227
	v_lshlrev_b32_e32 v224, 16, v230
	v_mov_b32_e32 v225, 0
	v_mov_b32_e32 v226, 0
	v_mov_b32_dpp v225, v224 wave_shr:1 row_mask:0xf bank_mask:0xf
	v_mov_b32_dpp v226, v224 wave_shl:1 row_mask:0xf bank_mask:0xf
	v_mul_f32_e32 v227, v88, v224
	v_fmac_f32_e32 v227, v87, v225
	v_fmac_f32_e32 v227, v89, v226
	v_add_f32_e32 v97, v90, v227
	v_lshlrev_b32_e32 v224, 16, v229
	v_mov_b32_e32 v225, 0
	v_mov_b32_e32 v226, 0
	v_mov_b32_dpp v225, v224 wave_shr:1 row_mask:0xf bank_mask:0xf
	v_mov_b32_dpp v226, v224 wave_shl:1 row_mask:0xf bank_mask:0xf
	v_mul_f32_e32 v227, v88, v224
	v_fmac_f32_e32 v227, v87, v225
	v_fmac_f32_e32 v227, v89, v226
	v_add_f32_e32 v98, v90, v227
	v_lshlrev_b32_e32 v224, 16, v231
	v_mov_b32_e32 v225, 0
	v_mov_b32_e32 v226, 0
	v_mov_b32_dpp v225, v224 wave_shr:1 row_mask:0xf bank_mask:0xf
	v_mov_b32_dpp v226, v224 wave_shl:1 row_mask:0xf bank_mask:0xf
	v_mul_f32_e32 v227, v88, v224
	v_fmac_f32_e32 v227, v87, v225
	v_fmac_f32_e32 v227, v89, v226
	v_add_f32_e32 v100, v90, v227
	v_mul_f32_e32 v108, v91, v236
	v_fmac_f32_e32 v108, 0x38800000, v82
	v_mul_f32_e32 v108, v94, v108
	v_lshlrev_b32_e32 v109, 16, v232
	v_mul_f32_e32 v108, v108, v109
	v_cvt_pk_bf16_f32 v224, v108, v108
	v_mul_f32_e32 v108, v91, v237
	v_fmac_f32_e32 v108, 0x38800000, v83
	v_mul_f32_e32 v108, v108, v97
	v_lshlrev_b32_e32 v109, 16, v234
	v_mul_f32_e32 v108, v108, v109
	v_cvt_pk_bf16_f32 v225, v108, v108
	v_add_u32_e32 v106, 0x0, v1
	v_lshl_add_u64 v[104:105], v[54:55], 0, v[106:107]
	global_store_short v[104:105], v224, off
	v_lshl_add_u64 v[104:105], v[56:57], 0, v[106:107]
	global_store_short v[104:105], v225, off
	v_mul_f32_e32 v108, v91, v238
	v_fmac_f32_e32 v108, 0x38800000, v84
	v_mul_f32_e32 v108, v98, v108
	v_lshlrev_b32_e32 v109, 16, v233
	v_mul_f32_e32 v108, v108, v109
	v_cvt_pk_bf16_f32 v224, v108, v108
	v_mul_f32_e32 v108, v91, v239
	v_fmac_f32_e32 v108, 0x38800000, v85
	v_mul_f32_e32 v108, v108, v100
	v_lshlrev_b32_e32 v109, 16, v235
	v_mul_f32_e32 v108, v108, v109
	v_cvt_pk_bf16_f32 v225, v108, v108
	v_add_u32_e32 v106, 0x0, v4
	v_lshl_add_u64 v[104:105], v[54:55], 0, v[106:107]
	global_store_short v[104:105], v224, off
	v_lshl_add_u64 v[104:105], v[56:57], 0, v[106:107]
	global_store_short v[104:105], v225, off
	global_load_ushort v228, v1, s[96:97] offset:2048
	global_load_ushort v230, v1, s[74:75] offset:2048
	global_load_ushort v232, v1, s[72:73] offset:2048
	global_load_ushort v234, v1, s[12:13] offset:2048
	global_load_ushort v229, v4, s[96:97] offset:2048
	global_load_ushort v231, v4, s[74:75] offset:2048
	global_load_ushort v233, v4, s[72:73] offset:2048
	global_load_ushort v235, v4, s[12:13] offset:2048
	v_add_u32_e32 v6, 0x6000, v5
	global_load_dwordx2 v[236:237], v6, s[80:81]
	global_load_dwordx2 v[238:239], v6, s[50:51]
	ds_read_b64 v[12:13], v7 offset:384
	ds_read_b64 v[14:15], v8 offset:24576
	ds_read_b64 v[16:17], v8 offset:57344
	ds_read_b64 v[18:19], v9 offset:24576
	ds_read_b64 v[20:21], v9 offset:57344
	s_waitcnt lgkmcnt(5)
	v_pk_mul_f32 v[222:223], v[58:59], v[10:11] op_sel:[1,1] op_sel_hi:[1,0]
	v_pk_fma_f32 v[22:23], v[58:59], v[10:11], v[222:223] op_sel:[0,0,0] op_sel_hi:[0,1,1] neg_lo:[0,0,1]
	v_pk_mul_f32 v[222:223], v[22:23], v[22:23] op_sel:[1,1] op_sel_hi:[1,0]
	v_pk_fma_f32 v[24:25], v[22:23], v[22:23], v[222:223] op_sel:[0,0,0] op_sel_hi:[0,1,1] neg_lo:[0,0,1]
	v_pk_mul_f32 v[222:223], v[24:25], v[22:23] op_sel:[1,1] op_sel_hi:[1,0]
	v_pk_fma_f32 v[26:27], v[24:25], v[22:23], v[222:223] op_sel:[0,0,0] op_sel_hi:[0,1,1] neg_lo:[0,0,1]
	v_pk_mul_f32 v[222:223], v[62:63], v[22:23] op_sel:[1,1] op_sel_hi:[0,1]
	v_pk_fma_f32 v[28:29], v[62:63], v[22:23], v[222:223] op_sel:[0,0,0] op_sel_hi:[1,0,1] neg_hi:[0,0,1]
	v_pk_mul_f32 v[222:223], v[64:65], v[24:25] op_sel:[1,1] op_sel_hi:[0,1]
	v_pk_fma_f32 v[30:31], v[64:65], v[24:25], v[222:223] op_sel:[0,0,0] op_sel_hi:[1,0,1] neg_hi:[0,0,1]
	v_pk_mul_f32 v[222:223], v[66:67], v[26:27] op_sel:[1,1] op_sel_hi:[0,1]
	v_pk_fma_f32 v[68:69], v[66:67], v[26:27], v[222:223] op_sel:[0,0,0] op_sel_hi:[1,0,1] neg_hi:[0,0,1]
	v_pk_add_f32 v[70:71], v[60:61], v[30:31]
	v_pk_add_f32 v[72:73], v[60:61], v[30:31] neg_lo:[0,1] neg_hi:[0,1]
	v_pk_add_f32 v[74:75], v[28:29], v[68:69]
	v_pk_add_f32 v[80:81], v[28:29], v[68:69] neg_lo:[0,1] neg_hi:[0,1]
	v_pk_add_f32 v[82:83], v[70:71], v[74:75]
	v_pk_add_f32 v[84:85], v[72:73], v[80:81] op_sel:[0,1] op_sel_hi:[1,0] neg_lo:[0,1]
	s_waitcnt vmcnt(14)
; __device__ __forceinline__ float bf2f(u16 h){ return __uint_as_float(((unsigned)h)<<16); }
; __device__ __forceinline__ float hconv3(const u16* __restrict__ row, int t, float w0, float w1, float w2, float bias){
;   float m = bf2f(row[t]);
;   int mi=__float_as_int(m);
;   float l=__int_as_float(__builtin_amdgcn_update_dpp(0, mi, 0x138, 0xf, 0xf, false));
;   float r=__int_as_float(__builtin_amdgcn_update_dpp(0, mi, 0x130, 0xf, 0xf, false));
;   return w0*l+w1*m+w2*r+bias;
; __device__ __forceinline__ void phase_hyena(KP kp_, int hf){ asm volatile("" : "+s"(kp_)); const Params p=load_params(kp_);
;     ...
;           _Pragma("unroll 4") for (int i=0;i<8;++i){ int tb=tq+512*i; float2 xr[2]; inv12_half(Z,twA,twB,tb,xr[0],xr[1]);
;             _Pragma("unroll") for (int hh=0;hh<2;++hh){ int t=tb+hh*4096;
;               float x0=hconv3(r2,t,wb0,wb1,wb2,bb_), x1=hconv3(r2+8192,t,wb0,wb1,wb2,bb_);
;               float2 y=xr[hh]; y.x*=(1.f/16384.f); y.y*=(1.f/16384.f); float2 z1=Zs[t];
;               float o0=x0*(y.x+z1.x*bias1)*bf2f(rz[t]); float o1=x1*(y.y+z1.y*bias1)*bf2f(rz[8192+t]);
;               ybT[(size_t)c*16384+t]=f2bf(o0); ybT[(size_t)c*16384+8192+t]=f2bf(o1); } }
	v_lshlrev_b32_e32 v224, 16, v240
	v_mov_b32_e32 v225, 0
	v_mov_b32_e32 v226, 0
	v_mov_b32_dpp v225, v224 wave_shr:1 row_mask:0xf bank_mask:0xf
	v_mov_b32_dpp v226, v224 wave_shl:1 row_mask:0xf bank_mask:0xf
	v_mul_f32_e32 v227, v88, v224
	v_fmac_f32_e32 v227, v87, v225
	v_fmac_f32_e32 v227, v89, v226
	v_add_f32_e32 v94, v90, v227
	v_lshlrev_b32_e32 v224, 16, v242
	v_mov_b32_e32 v225, 0
	v_mov_b32_e32 v226, 0
	v_mov_b32_dpp v225, v224 wave_shr:1 row_mask:0xf bank_mask:0xf
	v_mov_b32_dpp v226, v224 wave_shl:1 row_mask:0xf bank_mask:0xf
	v_mul_f32_e32 v227, v88, v224
	v_fmac_f32_e32 v227, v87, v225
	v_fmac_f32_e32 v227, v89, v226
	v_add_f32_e32 v97, v90, v227
	v_lshlrev_b32_e32 v224, 16, v241
	v_mov_b32_e32 v225, 0
	v_mov_b32_e32 v226, 0
	v_mov_b32_dpp v225, v224 wave_shr:1 row_mask:0xf bank_mask:0xf
	v_mov_b32_dpp v226, v224 wave_shl:1 row_mask:0xf bank_mask:0xf
	v_mul_f32_e32 v227, v88, v224
	v_fmac_f32_e32 v227, v87, v225
	v_fmac_f32_e32 v227, v89, v226
	v_add_f32_e32 v98, v90, v227
	v_lshlrev_b32_e32 v224, 16, v243
	v_mov_b32_e32 v225, 0
	v_mov_b32_e32 v226, 0
	v_mov_b32_dpp v225, v224 wave_shr:1 row_mask:0xf bank_mask:0xf
	v_mov_b32_dpp v226, v224 wave_shl:1 row_mask:0xf bank_mask:0xf
	v_mul_f32_e32 v227, v88, v224
	v_fmac_f32_e32 v227, v87, v225
	v_fmac_f32_e32 v227, v89, v226
	v_add_f32_e32 v100, v90, v227
	v_mul_f32_e32 v108, v91, v248
	v_fmac_f32_e32 v108, 0x38800000, v82
	v_mul_f32_e32 v108, v94, v108
	v_lshlrev_b32_e32 v109, 16, v244
	v_mul_f32_e32 v108, v108, v109
	v_cvt_pk_bf16_f32 v224, v108, v108
	v_mul_f32_e32 v108, v91, v249
	v_fmac_f32_e32 v108, 0x38800000, v83
	v_mul_f32_e32 v108, v108, v97
	v_lshlrev_b32_e32 v109, 16, v246
	v_mul_f32_e32 v108, v108, v109
	v_cvt_pk_bf16_f32 v225, v108, v108
	v_add_u32_e32 v106, 0x400, v1
	v_lshl_add_u64 v[104:105], v[54:55], 0, v[106:107]
	global_store_short v[104:105], v224, off
	v_lshl_add_u64 v[104:105], v[56:57], 0, v[106:107]
	global_store_short v[104:105], v225, off
	v_mul_f32_e32 v108, v91, v250
	v_fmac_f32_e32 v108, 0x38800000, v84
	v_mul_f32_e32 v108, v98, v108
	v_lshlrev_b32_e32 v109, 16, v245
	v_mul_f32_e32 v108, v108, v109
	v_cvt_pk_bf16_f32 v224, v108, v108
	v_mul_f32_e32 v108, v91, v251
	v_fmac_f32_e32 v108, 0x38800000, v85
	v_mul_f32_e32 v108, v108, v100
	v_lshlrev_b32_e32 v109, 16, v247
	v_mul_f32_e32 v108, v108, v109
	v_cvt_pk_bf16_f32 v225, v108, v108
	v_add_u32_e32 v106, 0x400, v4
	v_lshl_add_u64 v[104:105], v[54:55], 0, v[106:107]
	global_store_short v[104:105], v224, off
	v_lshl_add_u64 v[104:105], v[56:57], 0, v[106:107]
	global_store_short v[104:105], v225, off
	global_load_ushort v240, v1, s[96:97] offset:3072
	global_load_ushort v242, v1, s[74:75] offset:3072
	global_load_ushort v244, v1, s[72:73] offset:3072
	global_load_ushort v246, v1, s[12:13] offset:3072
	global_load_ushort v241, v4, s[96:97] offset:3072
	global_load_ushort v243, v4, s[74:75] offset:3072
	global_load_ushort v245, v4, s[72:73] offset:3072
	global_load_ushort v247, v4, s[12:13] offset:3072
	v_add_u32_e32 v6, 0x7000, v5
	global_load_dwordx2 v[248:249], v6, s[80:81]
	global_load_dwordx2 v[250:251], v6, s[50:51]
	ds_read_b64 v[58:59], v7 offset:448
	ds_read_b64 v[60:61], v8 offset:28672
	ds_read_b64 v[62:63], v8 offset:61440
	ds_read_b64 v[64:65], v9 offset:28672
	ds_read_b64 v[66:67], v9 offset:61440
	s_waitcnt lgkmcnt(5)
	v_pk_mul_f32 v[222:223], v[12:13], v[10:11] op_sel:[1,1] op_sel_hi:[1,0]
	v_pk_fma_f32 v[22:23], v[12:13], v[10:11], v[222:223] op_sel:[0,0,0] op_sel_hi:[0,1,1] neg_lo:[0,0,1]
	v_pk_mul_f32 v[222:223], v[22:23], v[22:23] op_sel:[1,1] op_sel_hi:[1,0]
	v_pk_fma_f32 v[24:25], v[22:23], v[22:23], v[222:223] op_sel:[0,0,0] op_sel_hi:[0,1,1] neg_lo:[0,0,1]
	v_pk_mul_f32 v[222:223], v[24:25], v[22:23] op_sel:[1,1] op_sel_hi:[1,0]
	v_pk_fma_f32 v[26:27], v[24:25], v[22:23], v[222:223] op_sel:[0,0,0] op_sel_hi:[0,1,1] neg_lo:[0,0,1]
	v_pk_mul_f32 v[222:223], v[16:17], v[22:23] op_sel:[1,1] op_sel_hi:[0,1]
	v_pk_fma_f32 v[28:29], v[16:17], v[22:23], v[222:223] op_sel:[0,0,0] op_sel_hi:[1,0,1] neg_hi:[0,0,1]
	v_pk_mul_f32 v[222:223], v[18:19], v[24:25] op_sel:[1,1] op_sel_hi:[0,1]
	v_pk_fma_f32 v[30:31], v[18:19], v[24:25], v[222:223] op_sel:[0,0,0] op_sel_hi:[1,0,1] neg_hi:[0,0,1]
	v_pk_mul_f32 v[222:223], v[20:21], v[26:27] op_sel:[1,1] op_sel_hi:[0,1]
	v_pk_fma_f32 v[68:69], v[20:21], v[26:27], v[222:223] op_sel:[0,0,0] op_sel_hi:[1,0,1] neg_hi:[0,0,1]
	v_pk_add_f32 v[70:71], v[14:15], v[30:31]
	v_pk_add_f32 v[72:73], v[14:15], v[30:31] neg_lo:[0,1] neg_hi:[0,1]
	v_pk_add_f32 v[74:75], v[28:29], v[68:69]
	v_pk_add_f32 v[80:81], v[28:29], v[68:69] neg_lo:[0,1] neg_hi:[0,1]
	v_pk_add_f32 v[82:83], v[70:71], v[74:75]
	v_pk_add_f32 v[84:85], v[72:73], v[80:81] op_sel:[0,1] op_sel_hi:[1,0] neg_lo:[0,1]
	s_waitcnt vmcnt(14)
; __device__ __forceinline__ float bf2f(u16 h){ return __uint_as_float(((unsigned)h)<<16); }
; __device__ __forceinline__ float hconv3(const u16* __restrict__ row, int t, float w0, float w1, float w2, float bias){
;   float m = bf2f(row[t]);
;   int mi=__float_as_int(m);
;   float l=__int_as_float(__builtin_amdgcn_update_dpp(0, mi, 0x138, 0xf, 0xf, false));
;   float r=__int_as_float(__builtin_amdgcn_update_dpp(0, mi, 0x130, 0xf, 0xf, false));
;   return w0*l+w1*m+w2*r+bias;
; __device__ __forceinline__ void phase_hyena(KP kp_, int hf){ asm volatile("" : "+s"(kp_)); const Params p=load_params(kp_);
;     ...
;           _Pragma("unroll 4") for (int i=0;i<8;++i){ int tb=tq+512*i; float2 xr[2]; inv12_half(Z,twA,twB,tb,xr[0],xr[1]);
;             _Pragma("unroll") for (int hh=0;hh<2;++hh){ int t=tb+hh*4096;
;               float x0=hconv3(r2,t,wb0,wb1,wb2,bb_), x1=hconv3(r2+8192,t,wb0,wb1,wb2,bb_);
;               float2 y=xr[hh]; y.x*=(1.f/16384.f); y.y*=(1.f/16384.f); float2 z1=Zs[t];
;               float o0=x0*(y.x+z1.x*bias1)*bf2f(rz[t]); float o1=x1*(y.y+z1.y*bias1)*bf2f(rz[8192+t]);
;               ybT[(size_t)c*16384+t]=f2bf(o0); ybT[(size_t)c*16384+8192+t]=f2bf(o1); } }
	v_lshlrev_b32_e32 v224, 16, v228
	v_mov_b32_e32 v225, 0
	v_mov_b32_e32 v226, 0
	v_mov_b32_dpp v225, v224 wave_shr:1 row_mask:0xf bank_mask:0xf
	v_mov_b32_dpp v226, v224 wave_shl:1 row_mask:0xf bank_mask:0xf
	v_mul_f32_e32 v227, v88, v224
	v_fmac_f32_e32 v227, v87, v225
	v_fmac_f32_e32 v227, v89, v226
	v_add_f32_e32 v94, v90, v227
	v_lshlrev_b32_e32 v224, 16, v230
	v_mov_b32_e32 v225, 0
	v_mov_b32_e32 v226, 0
	v_mov_b32_dpp v225, v224 wave_shr:1 row_mask:0xf bank_mask:0xf
	v_mov_b32_dpp v226, v224 wave_shl:1 row_mask:0xf bank_mask:0xf
	v_mul_f32_e32 v227, v88, v224
	v_fmac_f32_e32 v227, v87, v225
	v_fmac_f32_e32 v227, v89, v226
	v_add_f32_e32 v97, v90, v227
	v_lshlrev_b32_e32 v224, 16, v229
	v_mov_b32_e32 v225, 0
	v_mov_b32_e32 v226, 0
	v_mov_b32_dpp v225, v224 wave_shr:1 row_mask:0xf bank_mask:0xf
	v_mov_b32_dpp v226, v224 wave_shl:1 row_mask:0xf bank_mask:0xf
	v_mul_f32_e32 v227, v88, v224
	v_fmac_f32_e32 v227, v87, v225
	v_fmac_f32_e32 v227, v89, v226
	v_add_f32_e32 v98, v90, v227
	v_lshlrev_b32_e32 v224, 16, v231
	v_mov_b32_e32 v225, 0
	v_mov_b32_e32 v226, 0
	v_mov_b32_dpp v225, v224 wave_shr:1 row_mask:0xf bank_mask:0xf
	v_mov_b32_dpp v226, v224 wave_shl:1 row_mask:0xf bank_mask:0xf
	v_mul_f32_e32 v227, v88, v224
	v_fmac_f32_e32 v227, v87, v225
	v_fmac_f32_e32 v227, v89, v226
	v_add_f32_e32 v100, v90, v227
	v_mul_f32_e32 v108, v91, v236
	v_fmac_f32_e32 v108, 0x38800000, v82
	v_mul_f32_e32 v108, v94, v108
	v_lshlrev_b32_e32 v109, 16, v232
	v_mul_f32_e32 v108, v108, v109
	v_cvt_pk_bf16_f32 v224, v108, v108
	v_mul_f32_e32 v108, v91, v237
	v_fmac_f32_e32 v108, 0x38800000, v83
	v_mul_f32_e32 v108, v108, v97
	v_lshlrev_b32_e32 v109, 16, v234
	v_mul_f32_e32 v108, v108, v109
	v_cvt_pk_bf16_f32 v225, v108, v108
	v_add_u32_e32 v106, 0x800, v1
	v_lshl_add_u64 v[104:105], v[54:55], 0, v[106:107]
	global_store_short v[104:105], v224, off
	v_lshl_add_u64 v[104:105], v[56:57], 0, v[106:107]
	global_store_short v[104:105], v225, off
	v_mul_f32_e32 v108, v91, v238
	v_fmac_f32_e32 v108, 0x38800000, v84
	v_mul_f32_e32 v108, v98, v108
	v_lshlrev_b32_e32 v109, 16, v233
	v_mul_f32_e32 v108, v108, v109
	v_cvt_pk_bf16_f32 v224, v108, v108
	v_mul_f32_e32 v108, v91, v239
	v_fmac_f32_e32 v108, 0x38800000, v85
	v_mul_f32_e32 v108, v108, v100
	v_lshlrev_b32_e32 v109, 16, v235
	v_mul_f32_e32 v108, v108, v109
	v_cvt_pk_bf16_f32 v225, v108, v108
	v_add_u32_e32 v106, 0x800, v4
	v_lshl_add_u64 v[104:105], v[54:55], 0, v[106:107]
	global_store_short v[104:105], v224, off
	v_lshl_add_u64 v[104:105], v[56:57], 0, v[106:107]
	global_store_short v[104:105], v225, off
	s_waitcnt lgkmcnt(0)
	v_pk_mul_f32 v[222:223], v[58:59], v[10:11] op_sel:[1,1] op_sel_hi:[1,0]
	v_pk_fma_f32 v[22:23], v[58:59], v[10:11], v[222:223] op_sel:[0,0,0] op_sel_hi:[0,1,1] neg_lo:[0,0,1]
	v_pk_mul_f32 v[222:223], v[22:23], v[22:23] op_sel:[1,1] op_sel_hi:[1,0]
	v_pk_fma_f32 v[24:25], v[22:23], v[22:23], v[222:223] op_sel:[0,0,0] op_sel_hi:[0,1,1] neg_lo:[0,0,1]
	v_pk_mul_f32 v[222:223], v[24:25], v[22:23] op_sel:[1,1] op_sel_hi:[1,0]
	v_pk_fma_f32 v[26:27], v[24:25], v[22:23], v[222:223] op_sel:[0,0,0] op_sel_hi:[0,1,1] neg_lo:[0,0,1]
	v_pk_mul_f32 v[222:223], v[62:63], v[22:23] op_sel:[1,1] op_sel_hi:[0,1]
	v_pk_fma_f32 v[28:29], v[62:63], v[22:23], v[222:223] op_sel:[0,0,0] op_sel_hi:[1,0,1] neg_hi:[0,0,1]
	v_pk_mul_f32 v[222:223], v[64:65], v[24:25] op_sel:[1,1] op_sel_hi:[0,1]
	v_pk_fma_f32 v[30:31], v[64:65], v[24:25], v[222:223] op_sel:[0,0,0] op_sel_hi:[1,0,1] neg_hi:[0,0,1]
	v_pk_mul_f32 v[222:223], v[66:67], v[26:27] op_sel:[1,1] op_sel_hi:[0,1]
	v_pk_fma_f32 v[68:69], v[66:67], v[26:27], v[222:223] op_sel:[0,0,0] op_sel_hi:[1,0,1] neg_hi:[0,0,1]
	v_pk_add_f32 v[70:71], v[60:61], v[30:31]
	v_pk_add_f32 v[72:73], v[60:61], v[30:31] neg_lo:[0,1] neg_hi:[0,1]
	v_pk_add_f32 v[74:75], v[28:29], v[68:69]
	v_pk_add_f32 v[80:81], v[28:29], v[68:69] neg_lo:[0,1] neg_hi:[0,1]
	v_pk_add_f32 v[82:83], v[70:71], v[74:75]
	v_pk_add_f32 v[84:85], v[72:73], v[80:81] op_sel:[0,1] op_sel_hi:[1,0] neg_lo:[0,1]
	s_waitcnt vmcnt(4)
	v_lshlrev_b32_e32 v224, 16, v240
	v_mov_b32_e32 v225, 0
	v_mov_b32_e32 v226, 0
	v_mov_b32_dpp v225, v224 wave_shr:1 row_mask:0xf bank_mask:0xf
	v_mov_b32_dpp v226, v224 wave_shl:1 row_mask:0xf bank_mask:0xf
	v_mul_f32_e32 v227, v88, v224
	v_fmac_f32_e32 v227, v87, v225
	v_fmac_f32_e32 v227, v89, v226
	v_add_f32_e32 v94, v90, v227
	v_lshlrev_b32_e32 v224, 16, v242
	v_mov_b32_e32 v225, 0
	v_mov_b32_e32 v226, 0
	v_mov_b32_dpp v225, v224 wave_shr:1 row_mask:0xf bank_mask:0xf
	v_mov_b32_dpp v226, v224 wave_shl:1 row_mask:0xf bank_mask:0xf
	v_mul_f32_e32 v227, v88, v224
	v_fmac_f32_e32 v227, v87, v225
	v_fmac_f32_e32 v227, v89, v226
	v_add_f32_e32 v97, v90, v227
	v_lshlrev_b32_e32 v224, 16, v241
	v_mov_b32_e32 v225, 0
	v_mov_b32_e32 v226, 0
	v_mov_b32_dpp v225, v224 wave_shr:1 row_mask:0xf bank_mask:0xf
	v_mov_b32_dpp v226, v224 wave_shl:1 row_mask:0xf bank_mask:0xf
	v_mul_f32_e32 v227, v88, v224
	v_fmac_f32_e32 v227, v87, v225
	v_fmac_f32_e32 v227, v89, v226
	v_add_f32_e32 v98, v90, v227
	v_lshlrev_b32_e32 v224, 16, v243
	v_mov_b32_e32 v225, 0
	v_mov_b32_e32 v226, 0
	v_mov_b32_dpp v225, v224 wave_shr:1 row_mask:0xf bank_mask:0xf
	v_mov_b32_dpp v226, v224 wave_shl:1 row_mask:0xf bank_mask:0xf
	v_mul_f32_e32 v227, v88, v224
	v_fmac_f32_e32 v227, v87, v225
	v_fmac_f32_e32 v227, v89, v226
	v_add_f32_e32 v100, v90, v227
	v_mul_f32_e32 v108, v91, v248
	v_fmac_f32_e32 v108, 0x38800000, v82
	v_mul_f32_e32 v108, v94, v108
	v_lshlrev_b32_e32 v109, 16, v244
	v_mul_f32_e32 v108, v108, v109
	v_cvt_pk_bf16_f32 v224, v108, v108
	v_mul_f32_e32 v108, v91, v249
	v_fmac_f32_e32 v108, 0x38800000, v83
	v_mul_f32_e32 v108, v108, v97
	v_lshlrev_b32_e32 v109, 16, v246
	v_mul_f32_e32 v108, v108, v109
	v_cvt_pk_bf16_f32 v225, v108, v108
	v_add_u32_e32 v106, 0xc00, v1
	v_lshl_add_u64 v[104:105], v[54:55], 0, v[106:107]
	global_store_short v[104:105], v224, off
	v_lshl_add_u64 v[104:105], v[56:57], 0, v[106:107]
	global_store_short v[104:105], v225, off
	v_mul_f32_e32 v108, v91, v250
	v_fmac_f32_e32 v108, 0x38800000, v84
	v_mul_f32_e32 v108, v98, v108
	v_lshlrev_b32_e32 v109, 16, v245
	v_mul_f32_e32 v108, v108, v109
	v_cvt_pk_bf16_f32 v224, v108, v108
	v_mul_f32_e32 v108, v91, v251
	v_fmac_f32_e32 v108, 0x38800000, v85
	v_mul_f32_e32 v108, v108, v100
	v_lshlrev_b32_e32 v109, 16, v247
	v_mul_f32_e32 v108, v108, v109
	v_cvt_pk_bf16_f32 v225, v108, v108
	v_add_u32_e32 v106, 0xc00, v4
	v_lshl_add_u64 v[104:105], v[54:55], 0, v[106:107]
	global_store_short v[104:105], v224, off
	v_lshl_add_u64 v[104:105], v[56:57], 0, v[106:107]
	global_store_short v[104:105], v225, off
	s_mov_b32 s50, 0x2000
	s_mov_b32 s51, 0
	s_mov_b64 s[12:13], 0
